# back-edge rotation (guide 7.11): attention main-loop bookkeeping moved ahead of the closing barrier so step A's leading MFMA follows the barrier directly; on top of v18
# baseline (speedup 1.0000x reference)
; #define WAIT_BAR(N) asm volatile("s_waitcnt vmcnt(" #N ") lgkmcnt(0)\n\ts_barrier":::"memory")
;   #define RESC() do{ if(!NOMAX&&resc){ asm volatile("s_waitcnt lgkmcnt(0)":::"memory"); \
;       _Pragma("unroll") for(int d_=0;d_<2*VM;++d_) _Pragma("unroll") for(int r=0;r<16;++r)o[d_][r]*=wsf[crow(r,hi)]; } }while(0)
;   #define ROT() do{sl_prev=sl_cur;sl_cur=sl_next;sl_next=(sl_next==(NSLOT-1)*SLOTB)?0:sl_next+SLOTB;}while(0)
; template<int THRL,int VM,bool NOMAX> __device__ __forceinline__ void attn_unit(const bf16*Qb,const bf16*__restrict__ Kh,const bf16*__restrict__ Vh,bf16*Ob,const int NT,const int sp,float*wscr,char*shm){
;     ...
;   int t=1;
;   for(;t+5<NT;t+=2){
;     STEP(pB0,pB1,pA0,pA1,t,true,true,true);     if constexpr(VM==2){WAIT_BAR(3);}else{WAIT_BAR(2);} RESC(); ROT();
;     STEP(pA0,pA1,pB0,pB1,t+1,true,true,true);   if constexpr(VM==2){WAIT_BAR(3);}else{WAIT_BAR(2);} RESC(); ROT();
;   }
.LBB0_863:
	v_mfma_f32_32x32x16_bf16 v[112:127], v[100:103], v[218:221], 0
	v_lshl_add_u32 v206, s89, 1, v168
	ds_read_b64_tr_b16 v[194:195], v206 offset:24576
	ds_read_b64_tr_b16 v[196:197], v206 offset:25088
	v_add_f32_e32 v108, v80, v81
	v_add_f32_e32 v108, v82, v108
	v_add_f32_e32 v108, v83, v108
	v_add_f32_e32 v108, v84, v108
	v_add_f32_e32 v108, v85, v108
	v_cvt_pk_bf16_f32 v156, v80, v81
	v_cvt_pk_bf16_f32 v157, v82, v83
	ds_read_b64_tr_b16 v[80:81], v206 offset:28672
	ds_read_b64_tr_b16 v[82:83], v206 offset:29184
	v_add_f32_e32 v104, v86, v108
	v_add_f32_e32 v104, v87, v104
	v_add_f32_e32 v104, v88, v104
	v_add_f32_e32 v144, v89, v104
	v_mfma_f32_32x32x16_bf16 v[96:111], v[96:99], v[218:221], 0
	v_cvt_pk_bf16_f32 v158, v84, v85
	v_cvt_pk_bf16_f32 v159, v86, v87
	ds_read_b64_tr_b16 v[84:85], v206 offset:25600
	ds_read_b64_tr_b16 v[86:87], v206 offset:26112
	v_add_f32_e32 v144, v90, v144
	v_add_f32_e32 v144, v91, v144
	v_add_f32_e32 v144, v92, v144
	v_add_f32_e32 v144, v93, v144
	v_cvt_pk_bf16_f32 v152, v88, v89
	v_cvt_pk_bf16_f32 v153, v90, v91
	v_mfma_f32_32x32x16_bf16 v[112:127], v[164:167], v[222:225], v[112:127]
	ds_read_b64_tr_b16 v[88:89], v206 offset:29696
	ds_read_b64_tr_b16 v[90:91], v206 offset:30208
	v_add_f32_e32 v144, v94, v144
	v_add_f32_e32 v144, v95, v144
	v_add_f32_e32 v144, v64, v144
	v_add_f32_e32 v144, v65, v144
	v_mfma_f32_32x32x16_bf16 v[96:111], v[160:163], v[222:225], v[96:111]
	v_cvt_pk_bf16_f32 v154, v92, v93
	v_cvt_pk_bf16_f32 v155, v94, v95
	ds_read_b64_tr_b16 v[92:93], v206 offset:26624
	ds_read_b64_tr_b16 v[94:95], v206 offset:27136
	v_add_f32_e32 v144, v66, v144
	v_add_f32_e32 v144, v67, v144
	v_add_f32_e32 v144, v68, v144
	v_add_f32_e32 v144, v69, v144
	v_cvt_pk_bf16_f32 v148, v64, v65
	v_cvt_pk_bf16_f32 v149, v66, v67
	v_mfma_f32_32x32x16_bf16 v[112:127], v[140:143], v[226:229], v[112:127]
	ds_read_b64_tr_b16 v[198:199], v206 offset:30720
	ds_read_b64_tr_b16 v[200:201], v206 offset:31232
	v_add_f32_e32 v140, v70, v144
	v_add_f32_e32 v140, v71, v140
	v_add_f32_e32 v140, v72, v140
	v_add_f32_e32 v140, v73, v140
	v_mfma_f32_32x32x16_bf16 v[96:111], v[136:139], v[226:229], v[96:111]
	v_cvt_pk_bf16_f32 v150, v68, v69
	v_cvt_pk_bf16_f32 v151, v70, v71
	ds_read_b64_tr_b16 v[202:203], v206 offset:27648
	ds_read_b64_tr_b16 v[204:205], v206 offset:28160
	v_add_f32_e32 v68, v74, v140
	v_add_f32_e32 v68, v75, v68
	v_add_f32_e32 v68, v76, v68
	v_add_f32_e32 v68, v77, v68
	v_cvt_pk_bf16_f32 v144, v72, v73
	v_cvt_pk_bf16_f32 v145, v74, v75
	v_mfma_f32_32x32x16_bf16 v[112:127], v[132:135], v[230:233], v[112:127]
	ds_read_b64_tr_b16 v[72:73], v206 offset:31744
	ds_read_b64_tr_b16 v[74:75], v206 offset:32256
	v_add_f32_e32 v68, v78, v68
	v_add_f32_e32 v68, v79, v68
	v_add_f32_e32 v68, 0, v68
	v_cvt_pk_bf16_f32 v146, v76, v77
	v_mfma_f32_32x32x16_bf16 v[96:111], v[128:131], v[230:233], v[96:111]
	v_cvt_pk_bf16_f32 v147, v78, v79
	s_add_i32 s88, s87, s35
	v_lshl_add_u64 v[64:65], v[180:181], 0, s[54:55]
	s_mov_b32 s89, m0
	s_mov_b32 m0, s88
	s_nop 0
	global_load_lds_dwordx4 v[64:65], off
	s_mov_b32 m0, s89
	s_lshl_b32 s88, s86, 1
	v_lshl_add_u64 v[64:65], v[178:179], 0, s[54:55]
	s_add_i32 s88, s88, s16
	s_mov_b32 s89, m0
	s_mov_b32 m0, s88
	s_nop 0
	global_load_lds_dwordx4 v[64:65], off
	s_mov_b32 m0, s89
	v_lshl_add_u64 v[64:65], v[176:177], 0, s[54:55]
	s_addk_i32 s88, 0x2000
	s_mov_b32 s89, m0
	s_mov_b32 m0, s88
	s_nop 0
	global_load_lds_dwordx4 v[64:65], off
	s_mov_b32 m0, s89
	v_add_f32_e32 v193, v193, v68
	s_waitcnt lgkmcnt(12)
	v_mfma_f32_32x32x16_bf16 v[48:63], v[156:159], v[194:197], v[48:63]
	ds_read_b64_tr_b16 v[76:77], v206 offset:32768
	ds_read_b64_tr_b16 v[78:79], v206 offset:33280
	v_exp_f32_e32 v112, v112
	v_exp_f32_e32 v113, v113
	v_mfma_f32_32x32x16_bf16 v[32:47], v[156:159], v[80:83], v[32:47]
	ds_read_b64_tr_b16 v[194:195], v206 offset:36864
	ds_read_b64_tr_b16 v[196:197], v206 offset:37376
	v_exp_f32_e32 v114, v114
	v_exp_f32_e32 v115, v115
	v_add_u32_e32 v242, s86, v234
	v_add_u32_e32 v243, s86, v235
	v_add_u32_e32 v244, s86, v236
	v_add_u32_e32 v245, s86, v237
	ds_read_b128 v[68:71], v242
	ds_read_b128 v[64:67], v242 offset:4096
	s_waitcnt lgkmcnt(14)
	v_mfma_f32_32x32x16_bf16 v[48:63], v[152:155], v[84:87], v[48:63]
	ds_read_b64_tr_b16 v[80:81], v206 offset:33792
	ds_read_b64_tr_b16 v[82:83], v206 offset:34304
	v_exp_f32_e32 v116, v116
	v_exp_f32_e32 v117, v117
	ds_read_b128 v[164:167], v243
	ds_read_b128 v[140:143], v243 offset:4096
	v_mfma_f32_32x32x16_bf16 v[32:47], v[152:155], v[88:91], v[32:47]
	ds_read_b64_tr_b16 v[84:85], v206 offset:37888
	ds_read_b64_tr_b16 v[86:87], v206 offset:38400
	v_exp_f32_e32 v118, v118
	v_exp_f32_e32 v119, v119
	ds_read_b128 v[160:163], v244
	ds_read_b128 v[132:135], v244 offset:4096
	s_waitcnt lgkmcnt(14)
	v_mfma_f32_32x32x16_bf16 v[48:63], v[148:151], v[92:95], v[48:63]
	ds_read_b64_tr_b16 v[88:89], v206 offset:34816
	ds_read_b64_tr_b16 v[90:91], v206 offset:35328
	v_exp_f32_e32 v120, v120
	v_exp_f32_e32 v121, v121
	ds_read_b128 v[136:139], v245
	ds_read_b128 v[128:131], v245 offset:4096
	v_mfma_f32_32x32x16_bf16 v[32:47], v[148:151], v[198:201], v[32:47]
	ds_read_b64_tr_b16 v[92:93], v206 offset:38912
	ds_read_b64_tr_b16 v[94:95], v206 offset:39424
	v_exp_f32_e32 v122, v122
	v_exp_f32_e32 v123, v123
	s_waitcnt lgkmcnt(14)
	v_mfma_f32_32x32x16_bf16 v[48:63], v[144:147], v[202:205], v[48:63]
	ds_read_b64_tr_b16 v[198:199], v206 offset:35840
	ds_read_b64_tr_b16 v[200:201], v206 offset:36352
	v_exp_f32_e32 v124, v124
	v_exp_f32_e32 v125, v125
	v_mfma_f32_32x32x16_bf16 v[32:47], v[144:147], v[72:75], v[32:47]
	ds_read_b64_tr_b16 v[202:203], v206 offset:39936
	ds_read_b64_tr_b16 v[204:205], v206 offset:40448
	v_exp_f32_e32 v126, v126
	v_exp_f32_e32 v127, v127
	s_waitcnt lgkmcnt(14)
	v_mfma_f32_32x32x16_bf16 v[16:31], v[156:159], v[76:79], v[16:31]
	v_exp_f32_e32 v96, v96
	v_exp_f32_e32 v97, v97
	v_mfma_f32_32x32x16_bf16 v[0:15], v[156:159], v[194:197], v[0:15]
	v_exp_f32_e32 v98, v98
	v_exp_f32_e32 v99, v99
	v_mfma_f32_32x32x16_bf16 v[16:31], v[152:155], v[80:83], v[16:31]
	v_exp_f32_e32 v100, v100
	v_exp_f32_e32 v101, v101
	s_waitcnt lgkmcnt(12)
	v_mfma_f32_32x32x16_bf16 v[0:15], v[152:155], v[84:87], v[0:15]
	v_exp_f32_e32 v102, v102
	v_exp_f32_e32 v103, v103
	s_waitcnt lgkmcnt(8)
	v_mfma_f32_32x32x16_bf16 v[16:31], v[148:151], v[88:91], v[16:31]
	v_exp_f32_e32 v104, v104
	v_exp_f32_e32 v105, v105
	s_waitcnt lgkmcnt(4)
	v_mfma_f32_32x32x16_bf16 v[0:15], v[148:151], v[92:95], v[0:15]
	v_exp_f32_e32 v106, v106
	v_exp_f32_e32 v107, v107
	s_waitcnt lgkmcnt(2)
	v_mfma_f32_32x32x16_bf16 v[16:31], v[144:147], v[198:201], v[16:31]
	v_exp_f32_e32 v108, v108
	v_exp_f32_e32 v109, v109
	s_waitcnt lgkmcnt(0)
	v_mfma_f32_32x32x16_bf16 v[0:15], v[144:147], v[202:205], v[0:15]
	v_exp_f32_e32 v110, v110
	v_exp_f32_e32 v111, v111
	s_waitcnt vmcnt(3) lgkmcnt(0)
	s_barrier
; #define WAIT_BAR(N) asm volatile("s_waitcnt vmcnt(" #N ") lgkmcnt(0)\n\ts_barrier":::"memory")
;   #define RESC() do{ if(!NOMAX&&resc){ asm volatile("s_waitcnt lgkmcnt(0)":::"memory"); \
;       _Pragma("unroll") for(int d_=0;d_<2*VM;++d_) _Pragma("unroll") for(int r=0;r<16;++r)o[d_][r]*=wsf[crow(r,hi)]; } }while(0)
;   #define ROT() do{sl_prev=sl_cur;sl_cur=sl_next;sl_next=(sl_next==(NSLOT-1)*SLOTB)?0:sl_next+SLOTB;}while(0)
; template<int THRL,int VM,bool NOMAX> __device__ __forceinline__ void attn_unit(const bf16*Qb,const bf16*__restrict__ Kh,const bf16*__restrict__ Vh,bf16*Ob,const int NT,const int sp,float*wscr,char*shm){
;     ...
;   int t=1;
;   for(;t+5<NT;t+=2){
;     STEP(pB0,pB1,pA0,pA1,t,true,true,true);     if constexpr(VM==2){WAIT_BAR(3);}else{WAIT_BAR(2);} RESC(); ROT();
;     STEP(pA0,pA1,pB0,pB1,t+1,true,true,true);   if constexpr(VM==2){WAIT_BAR(3);}else{WAIT_BAR(2);} RESC(); ROT();
;   }
	v_mfma_f32_32x32x16_bf16 v[80:95], v[68:71], v[218:221], 0
	s_add_i32 s88, s86, 0x2000
	s_cmpk_lg_i32 s86, 0x4000
	s_cselect_b32 s88, s88, 0
	v_lshl_add_u32 v206, s87, 1, v168
	ds_read_b64_tr_b16 v[194:195], v206 offset:24576
	ds_read_b64_tr_b16 v[196:197], v206 offset:25088
	v_add_f32_e32 v76, v112, v113
	v_add_f32_e32 v76, v114, v76
	v_add_f32_e32 v76, v115, v76
	v_add_f32_e32 v76, v116, v76
	v_add_f32_e32 v76, v117, v76
	v_cvt_pk_bf16_f32 v156, v112, v113
	v_cvt_pk_bf16_f32 v157, v114, v115
	ds_read_b64_tr_b16 v[112:113], v206 offset:28672
	ds_read_b64_tr_b16 v[114:115], v206 offset:29184
	v_add_f32_e32 v72, v118, v76
	v_add_f32_e32 v72, v119, v72
	v_add_f32_e32 v72, v120, v72
	v_add_f32_e32 v144, v121, v72
	v_mfma_f32_32x32x16_bf16 v[64:79], v[64:67], v[218:221], 0
	v_cvt_pk_bf16_f32 v158, v116, v117
	v_cvt_pk_bf16_f32 v159, v118, v119
	ds_read_b64_tr_b16 v[116:117], v206 offset:25600
	ds_read_b64_tr_b16 v[118:119], v206 offset:26112
	v_add_f32_e32 v144, v122, v144
	v_add_f32_e32 v144, v123, v144
	v_add_f32_e32 v144, v124, v144
	v_add_f32_e32 v144, v125, v144
	v_mfma_f32_32x32x16_bf16 v[80:95], v[164:167], v[222:225], v[80:95]
	v_cvt_pk_bf16_f32 v152, v120, v121
	v_cvt_pk_bf16_f32 v153, v122, v123
	ds_read_b64_tr_b16 v[120:121], v206 offset:29696
	ds_read_b64_tr_b16 v[122:123], v206 offset:30208
	v_add_f32_e32 v144, v126, v144
	v_add_f32_e32 v144, v127, v144
	v_add_f32_e32 v144, v96, v144
	v_add_f32_e32 v144, v97, v144
	v_mfma_f32_32x32x16_bf16 v[64:79], v[140:143], v[222:225], v[64:79]
	v_cvt_pk_bf16_f32 v154, v124, v125
	v_cvt_pk_bf16_f32 v155, v126, v127
	ds_read_b64_tr_b16 v[124:125], v206 offset:26624
	ds_read_b64_tr_b16 v[126:127], v206 offset:27136
	v_add_f32_e32 v144, v98, v144
	v_add_f32_e32 v144, v99, v144
	v_add_f32_e32 v144, v100, v144
	v_add_f32_e32 v144, v101, v144
	v_mfma_f32_32x32x16_bf16 v[80:95], v[160:163], v[226:229], v[80:95]
	v_cvt_pk_bf16_f32 v148, v96, v97
	v_cvt_pk_bf16_f32 v149, v98, v99
	ds_read_b64_tr_b16 v[198:199], v206 offset:30720
	ds_read_b64_tr_b16 v[200:201], v206 offset:31232
	v_add_f32_e32 v140, v102, v144
	v_add_f32_e32 v140, v103, v140
	v_add_f32_e32 v140, v104, v140
	v_add_f32_e32 v140, v105, v140
	v_mfma_f32_32x32x16_bf16 v[64:79], v[132:135], v[226:229], v[64:79]
	v_cvt_pk_bf16_f32 v150, v100, v101
	v_cvt_pk_bf16_f32 v151, v102, v103
	ds_read_b64_tr_b16 v[202:203], v206 offset:27648
	ds_read_b64_tr_b16 v[204:205], v206 offset:28160
	v_add_f32_e32 v100, v106, v140
	v_add_f32_e32 v100, v107, v100
	v_add_f32_e32 v100, v108, v100
	v_add_f32_e32 v100, v109, v100
	v_mfma_f32_32x32x16_bf16 v[80:95], v[136:139], v[230:233], v[80:95]
	v_cvt_pk_bf16_f32 v144, v104, v105
	v_cvt_pk_bf16_f32 v145, v106, v107
	ds_read_b64_tr_b16 v[104:105], v206 offset:31744
	ds_read_b64_tr_b16 v[106:107], v206 offset:32256
	v_add_f32_e32 v100, v110, v100
	v_add_f32_e32 v100, v111, v100
	v_add_f32_e32 v100, 0, v100
	v_cvt_pk_bf16_f32 v146, v108, v109
	v_mfma_f32_32x32x16_bf16 v[64:79], v[128:131], v[230:233], v[64:79]
	v_cvt_pk_bf16_f32 v147, v110, v111
	s_add_i32 s87, s86, s35
	s_mov_b32 s89, m0
	s_mov_b32 m0, s87
	s_nop 0
	global_load_lds_dwordx4 v[180:181], off
	s_mov_b32 m0, s89
	s_lshl_b32 s87, s88, 1
	s_add_i32 s87, s87, s16
	s_mov_b32 s89, m0
	s_mov_b32 m0, s87
	s_nop 0
	global_load_lds_dwordx4 v[178:179], off
	s_mov_b32 m0, s89
	s_addk_i32 s87, 0x2000
	s_mov_b32 s89, m0
	s_mov_b32 m0, s87
	s_nop 0
	global_load_lds_dwordx4 v[176:177], off
	s_mov_b32 m0, s89
	v_add_f32_e32 v193, v193, v100
	s_waitcnt lgkmcnt(12)
	v_mfma_f32_32x32x16_bf16 v[48:63], v[156:159], v[194:197], v[48:63]
	ds_read_b64_tr_b16 v[108:109], v206 offset:32768
	ds_read_b64_tr_b16 v[110:111], v206 offset:33280
	v_exp_f32_e32 v80, v80
	v_exp_f32_e32 v81, v81
	v_mfma_f32_32x32x16_bf16 v[32:47], v[156:159], v[112:115], v[32:47]
	ds_read_b64_tr_b16 v[194:195], v206 offset:36864
	ds_read_b64_tr_b16 v[196:197], v206 offset:37376
	v_exp_f32_e32 v82, v82
	v_exp_f32_e32 v83, v83
	v_add_u32_e32 v242, s88, v234
	v_add_u32_e32 v243, s88, v235
	v_add_u32_e32 v244, s88, v236
	v_add_u32_e32 v245, s88, v237
	ds_read_b128 v[100:103], v242
	ds_read_b128 v[96:99], v242 offset:4096
	s_waitcnt lgkmcnt(14)
	v_mfma_f32_32x32x16_bf16 v[48:63], v[152:155], v[116:119], v[48:63]
	ds_read_b64_tr_b16 v[112:113], v206 offset:33792
	ds_read_b64_tr_b16 v[114:115], v206 offset:34304
	v_exp_f32_e32 v84, v84
	v_exp_f32_e32 v85, v85
	ds_read_b128 v[164:167], v243
	ds_read_b128 v[160:163], v243 offset:4096
	v_mfma_f32_32x32x16_bf16 v[32:47], v[152:155], v[120:123], v[32:47]
	ds_read_b64_tr_b16 v[116:117], v206 offset:37888
	ds_read_b64_tr_b16 v[118:119], v206 offset:38400
	v_exp_f32_e32 v86, v86
	v_exp_f32_e32 v87, v87
	ds_read_b128 v[140:143], v244
	ds_read_b128 v[136:139], v244 offset:4096
	s_waitcnt lgkmcnt(14)
	v_mfma_f32_32x32x16_bf16 v[48:63], v[148:151], v[124:127], v[48:63]
	ds_read_b64_tr_b16 v[120:121], v206 offset:34816
	ds_read_b64_tr_b16 v[122:123], v206 offset:35328
	v_exp_f32_e32 v88, v88
	v_exp_f32_e32 v89, v89
	ds_read_b128 v[132:135], v245
	ds_read_b128 v[128:131], v245 offset:4096
	v_mfma_f32_32x32x16_bf16 v[32:47], v[148:151], v[198:201], v[32:47]
	ds_read_b64_tr_b16 v[124:125], v206 offset:38912
	ds_read_b64_tr_b16 v[126:127], v206 offset:39424
	v_exp_f32_e32 v90, v90
	v_exp_f32_e32 v91, v91
	s_waitcnt lgkmcnt(14)
	v_mfma_f32_32x32x16_bf16 v[48:63], v[144:147], v[202:205], v[48:63]
	ds_read_b64_tr_b16 v[198:199], v206 offset:35840
	ds_read_b64_tr_b16 v[200:201], v206 offset:36352
	v_exp_f32_e32 v92, v92
	v_exp_f32_e32 v93, v93
	v_mfma_f32_32x32x16_bf16 v[32:47], v[144:147], v[104:107], v[32:47]
	ds_read_b64_tr_b16 v[202:203], v206 offset:39936
	ds_read_b64_tr_b16 v[204:205], v206 offset:40448
	v_exp_f32_e32 v94, v94
	v_exp_f32_e32 v95, v95
	s_waitcnt lgkmcnt(14)
; #define WAIT_BAR(N) asm volatile("s_waitcnt vmcnt(" #N ") lgkmcnt(0)\n\ts_barrier":::"memory")
;   #define RESC() do{ if(!NOMAX&&resc){ asm volatile("s_waitcnt lgkmcnt(0)":::"memory"); \
;       _Pragma("unroll") for(int d_=0;d_<2*VM;++d_) _Pragma("unroll") for(int r=0;r<16;++r)o[d_][r]*=wsf[crow(r,hi)]; } }while(0)
;   #define ROT() do{sl_prev=sl_cur;sl_cur=sl_next;sl_next=(sl_next==(NSLOT-1)*SLOTB)?0:sl_next+SLOTB;}while(0)
;   #define ENDW(tt) do{ if((tt)+3<NT){ if constexpr(VM==2){WAIT_BAR(3);}else{WAIT_BAR(2);} } else if((tt)+2<NT){ if constexpr(VM==2){WAIT_BAR(2);}else{WAIT_BAR(1);} } else {WAIT_BAR(0);} }while(0)
; template<int THRL,int VM,bool NOMAX> __device__ __forceinline__ void attn_unit(const bf16*Qb,const bf16*__restrict__ Kh,const bf16*__restrict__ Vh,bf16*Ob,const int NT,const int sp,float*wscr,char*shm){
;     ...
;   for(;t+5<NT;t+=2){
;     STEP(pB0,pB1,pA0,pA1,t,true,true,true);     if constexpr(VM==2){WAIT_BAR(3);}else{WAIT_BAR(2);} RESC(); ROT();
;     STEP(pA0,pA1,pB0,pB1,t+1,true,true,true);   if constexpr(VM==2){WAIT_BAR(3);}else{WAIT_BAR(2);} RESC(); ROT();
;   }
;     ...
;   for(;t+1<NT;t+=2){
;     STEP(pB0,pB1,pA0,pA1,t,(t+3<NT),(t+1<NT),(t+1<NT));       ENDW(t);   RESC(); ROT();
;     STEP(pA0,pA1,pB0,pB1,t+1,(t+4<NT),(t+2<NT),(t+2<NT));     ENDW(t+1); RESC(); ROT();
;   }
	v_mfma_f32_32x32x16_bf16 v[16:31], v[156:159], v[108:111], v[16:31]
	v_exp_f32_e32 v64, v64
	v_exp_f32_e32 v65, v65
	v_mfma_f32_32x32x16_bf16 v[0:15], v[156:159], v[194:197], v[0:15]
	v_exp_f32_e32 v66, v66
	v_exp_f32_e32 v67, v67
	v_mfma_f32_32x32x16_bf16 v[16:31], v[152:155], v[112:115], v[16:31]
	v_exp_f32_e32 v68, v68
	v_exp_f32_e32 v69, v69
	s_waitcnt lgkmcnt(12)
	v_mfma_f32_32x32x16_bf16 v[0:15], v[152:155], v[116:119], v[0:15]
	v_exp_f32_e32 v70, v70
	v_exp_f32_e32 v71, v71
	s_waitcnt lgkmcnt(8)
	v_mfma_f32_32x32x16_bf16 v[16:31], v[148:151], v[120:123], v[16:31]
	v_exp_f32_e32 v72, v72
	v_exp_f32_e32 v73, v73
	s_waitcnt lgkmcnt(4)
	v_mfma_f32_32x32x16_bf16 v[0:15], v[148:151], v[124:127], v[0:15]
	v_exp_f32_e32 v74, v74
	v_exp_f32_e32 v75, v75
	s_waitcnt lgkmcnt(2)
	v_mfma_f32_32x32x16_bf16 v[16:31], v[144:147], v[198:201], v[16:31]
	v_exp_f32_e32 v76, v76
	v_exp_f32_e32 v77, v77
	s_waitcnt lgkmcnt(0)
	v_mfma_f32_32x32x16_bf16 v[0:15], v[144:147], v[202:205], v[0:15]
	v_exp_f32_e32 v78, v78
	v_exp_f32_e32 v79, v79
	s_add_i32 s90, s88, 0x2000
	s_cmpk_lg_i32 s88, 0x4000
	s_mov_b32 s89, s86
	s_cselect_b32 s86, s90, 0
	s_add_i32 s85, s85, 2
	v_lshl_add_u64 v[176:177], v[176:177], 0, s[56:57]
	v_lshl_add_u64 v[178:179], v[178:179], 0, s[56:57]
	v_lshl_add_u64 v[180:181], v[180:181], 0, s[56:57]
	s_mov_b32 s87, s88
	s_cmpk_lt_u32 s85, 0x79
	s_waitcnt vmcnt(3) lgkmcnt(0)
	s_barrier
	s_cbranch_scc1 .LBB0_863
	s_and_b32 s34, s34, 0x3fffffc0
	s_lshl_b32 s34, s34, 2
	s_add_i32 s34, s34, 0
	s_add_i32 s34, s34, 0x12000
	s_cmp_lg_u32 0, -1
	s_cselect_b32 s85, 0, 0
	s_add_i32 s86, s85, 0x6000
	v_add_u32_e32 v104, s86, v191
	v_add3_u32 v176, v104, v190, v192
	v_add_u32_e32 v177, 0x6000, v168
	ds_read_b64_tr_b16 v[178:179], v168 offset:57344
	ds_read_b64_tr_b16 v[180:181], v168 offset:57856
	v_add_f32_e32 v108, v80, v81
	ds_read_b128 v[104:107], v188
	v_add_f32_e32 v108, v82, v108
	v_add_f32_e32 v108, v83, v108
	v_add_f32_e32 v108, v84, v108
	v_add_f32_e32 v108, v85, v108
	v_cvt_pk_bf16_f32 v156, v80, v81
	v_cvt_pk_bf16_f32 v157, v82, v83
	s_waitcnt lgkmcnt(0)
	v_mfma_f32_32x32x16_bf16 v[112:127], v[100:103], v[104:107], 0
	ds_read_b64_tr_b16 v[80:81], v168 offset:61440
	ds_read_b64_tr_b16 v[82:83], v168 offset:61952
	ds_read_b128 v[100:103], v188
	v_add_f32_e32 v104, v86, v108
	v_add_f32_e32 v104, v87, v104
	v_add_f32_e32 v104, v88, v104
	v_add_f32_e32 v144, v89, v104
	v_cvt_pk_bf16_f32 v158, v84, v85
	v_cvt_pk_bf16_f32 v159, v86, v87
	s_waitcnt lgkmcnt(0)
	v_mfma_f32_32x32x16_bf16 v[96:111], v[96:99], v[100:103], 0
	ds_read_b64_tr_b16 v[84:85], v168 offset:58368
	ds_read_b64_tr_b16 v[86:87], v168 offset:58880
	ds_read_b128 v[194:197], v188 offset:1024
	v_add_f32_e32 v144, v90, v144
	v_add_f32_e32 v144, v91, v144
	v_add_f32_e32 v144, v92, v144
	v_add_f32_e32 v144, v93, v144
	v_cvt_pk_bf16_f32 v152, v88, v89
	v_cvt_pk_bf16_f32 v153, v90, v91
	s_waitcnt lgkmcnt(0)
	v_mfma_f32_32x32x16_bf16 v[112:127], v[164:167], v[194:197], v[112:127]
	ds_read_b64_tr_b16 v[88:89], v168 offset:62464
	ds_read_b64_tr_b16 v[90:91], v168 offset:62976
	ds_read_b128 v[164:167], v188 offset:1024
	v_add_f32_e32 v144, v94, v144
	v_add_f32_e32 v144, v95, v144
	v_add_f32_e32 v144, v64, v144
	v_add_f32_e32 v144, v65, v144
	v_cvt_pk_bf16_f32 v154, v92, v93
	v_cvt_pk_bf16_f32 v155, v94, v95
	s_waitcnt lgkmcnt(0)
	v_mfma_f32_32x32x16_bf16 v[96:111], v[160:163], v[164:167], v[96:111]
	ds_read_b64_tr_b16 v[194:195], v168 offset:59392
	ds_read_b64_tr_b16 v[196:197], v168 offset:59904
	ds_read_b128 v[92:95], v188 offset:2048
	v_add_f32_e32 v144, v66, v144
	v_add_f32_e32 v144, v67, v144
	v_add_f32_e32 v144, v68, v144
	v_add_f32_e32 v144, v69, v144
	v_cvt_pk_bf16_f32 v148, v64, v65
	v_cvt_pk_bf16_f32 v149, v66, v67
	s_waitcnt lgkmcnt(0)
	v_mfma_f32_32x32x16_bf16 v[112:127], v[140:143], v[92:95], v[112:127]
	ds_read_b64_tr_b16 v[140:141], v168 offset:63488
	ds_read_b64_tr_b16 v[142:143], v168 offset:64000
	ds_read_b128 v[64:67], v188 offset:2048
	v_add_f32_e32 v92, v70, v144
	v_add_f32_e32 v92, v71, v92
	v_add_f32_e32 v92, v72, v92
	v_add_f32_e32 v92, v73, v92
	v_cvt_pk_bf16_f32 v150, v68, v69
	v_cvt_pk_bf16_f32 v151, v70, v71
	s_waitcnt lgkmcnt(0)
	v_mfma_f32_32x32x16_bf16 v[96:111], v[136:139], v[64:67], v[96:111]
	ds_read_b64_tr_b16 v[136:137], v168 offset:60416
	ds_read_b64_tr_b16 v[138:139], v168 offset:60928
	ds_read_b128 v[64:67], v188 offset:3072
	v_add_f32_e32 v68, v74, v92
	v_add_f32_e32 v68, v75, v68
	v_add_f32_e32 v68, v76, v68
	v_add_f32_e32 v68, v77, v68
	v_cvt_pk_bf16_f32 v144, v72, v73
	v_cvt_pk_bf16_f32 v145, v74, v75
	s_waitcnt lgkmcnt(0)
	v_mfma_f32_32x32x16_bf16 v[112:127], v[132:135], v[64:67], v[112:127]
	ds_read_b64_tr_b16 v[72:73], v168 offset:64512
	ds_read_b64_tr_b16 v[74:75], v168 offset:65024
	ds_read_b128 v[64:67], v188 offset:3072
	v_add_f32_e32 v68, v78, v68
	v_add_f32_e32 v68, v79, v68
	v_add_f32_e32 v68, 0, v68
	v_cvt_pk_bf16_f32 v146, v76, v77
	v_cvt_pk_bf16_f32 v147, v78, v79
	s_waitcnt lgkmcnt(0)
; #define WAIT_BAR(N) asm volatile("s_waitcnt vmcnt(" #N ") lgkmcnt(0)\n\ts_barrier":::"memory")
;   #define RESC() do{ if(!NOMAX&&resc){ asm volatile("s_waitcnt lgkmcnt(0)":::"memory"); \
;       _Pragma("unroll") for(int d_=0;d_<2*VM;++d_) _Pragma("unroll") for(int r=0;r<16;++r)o[d_][r]*=wsf[crow(r,hi)]; } }while(0)
;   #define ROT() do{sl_prev=sl_cur;sl_cur=sl_next;sl_next=(sl_next==(NSLOT-1)*SLOTB)?0:sl_next+SLOTB;}while(0)
;   #define ENDW(tt) do{ if((tt)+3<NT){ if constexpr(VM==2){WAIT_BAR(3);}else{WAIT_BAR(2);} } else if((tt)+2<NT){ if constexpr(VM==2){WAIT_BAR(2);}else{WAIT_BAR(1);} } else {WAIT_BAR(0);} }while(0)
; template<int THRL,int VM,bool NOMAX> __device__ __forceinline__ void attn_unit(const bf16*Qb,const bf16*__restrict__ Kh,const bf16*__restrict__ Vh,bf16*Ob,const int NT,const int sp,float*wscr,char*shm){
;     ...
;   int t=1;
;   for(;t+5<NT;t+=2){
;     STEP(pB0,pB1,pA0,pA1,t,true,true,true);     if constexpr(VM==2){WAIT_BAR(3);}else{WAIT_BAR(2);} RESC(); ROT();
;     STEP(pA0,pA1,pB0,pB1,t+1,true,true,true);   if constexpr(VM==2){WAIT_BAR(3);}else{WAIT_BAR(2);} RESC(); ROT();
;   }
;     ...
;   for(;t+1<NT;t+=2){
;     STEP(pB0,pB1,pA0,pA1,t,(t+3<NT),(t+1<NT),(t+1<NT));       ENDW(t);   RESC(); ROT();
;     STEP(pA0,pA1,pB0,pB1,t+1,(t+4<NT),(t+2<NT),(t+2<NT));     ENDW(t+1); RESC(); ROT();
;   }
	v_mfma_f32_32x32x16_bf16 v[96:111], v[128:131], v[64:67], v[96:111]
	v_lshl_add_u64 v[64:65], v[174:175], 0, s[58:59]
	s_mov_b32 s86, m0
	s_mov_b32 m0, s35
	s_nop 0
	global_load_lds_dwordx4 v[64:65], off
	s_mov_b32 m0, s86
	s_add_i32 s85, s85, s17
	v_lshl_add_u64 v[64:65], v[170:171], 0, s[60:61]
	s_add_i32 s17, s85, 0xa000
	s_mov_b32 s35, m0
	s_mov_b32 m0, s17
	s_nop 0
	global_load_lds_dwordx4 v[64:65], off
	s_mov_b32 m0, s35
	v_lshl_add_u64 v[64:65], v[172:173], 0, s[60:61]
	s_add_i32 s35, s17, 0x2000
	s_mov_b32 s86, m0
	s_mov_b32 m0, s35
	s_nop 0
	global_load_lds_dwordx4 v[64:65], off
	s_mov_b32 m0, s86
	v_add_f32_e32 v198, v193, v68
	v_mfma_f32_32x32x16_bf16 v[48:63], v[156:159], v[178:181], v[48:63]
	ds_read_b64_tr_b16 v[76:77], v177 offset:40960
	ds_read_b64_tr_b16 v[78:79], v177 offset:41472
	v_exp_f32_e32 v112, v112
	v_exp_f32_e32 v113, v113
	v_mfma_f32_32x32x16_bf16 v[32:47], v[156:159], v[80:83], v[32:47]
	ds_read_b64_tr_b16 v[128:129], v177 offset:45056
	ds_read_b64_tr_b16 v[130:131], v177 offset:45568
	v_exp_f32_e32 v114, v114
	v_exp_f32_e32 v115, v115
	ds_read_b128 v[68:71], v234 offset:8192
	ds_read_b128 v[64:67], v234 offset:12288
	v_mfma_f32_32x32x16_bf16 v[48:63], v[152:155], v[84:87], v[48:63]
	ds_read_b64_tr_b16 v[132:133], v177 offset:41984
	ds_read_b64_tr_b16 v[134:135], v177 offset:42496
	v_exp_f32_e32 v116, v116
	v_exp_f32_e32 v117, v117
	ds_read_b128 v[164:167], v235 offset:8192
	ds_read_b128 v[92:95], v235 offset:12288
	v_mfma_f32_32x32x16_bf16 v[32:47], v[152:155], v[88:91], v[32:47]
	ds_read_b64_tr_b16 v[178:179], v177 offset:46080
	ds_read_b64_tr_b16 v[180:181], v177 offset:46592
	v_exp_f32_e32 v118, v118
	v_exp_f32_e32 v119, v119
	ds_read_b128 v[160:163], v236 offset:8192
	ds_read_b128 v[84:87], v236 offset:12288
	v_mfma_f32_32x32x16_bf16 v[48:63], v[148:151], v[194:197], v[48:63]
	ds_read_b64_tr_b16 v[190:191], v177 offset:43008
	ds_read_b64_tr_b16 v[192:193], v177 offset:43520
	v_exp_f32_e32 v120, v120
	v_exp_f32_e32 v121, v121
	ds_read_b128 v[88:91], v237 offset:8192
	ds_read_b128 v[80:83], v237 offset:12288
	v_mfma_f32_32x32x16_bf16 v[32:47], v[148:151], v[140:143], v[32:47]
	ds_read_b64_tr_b16 v[194:195], v177 offset:47104
	ds_read_b64_tr_b16 v[196:197], v177 offset:47616
	v_exp_f32_e32 v122, v122
	v_exp_f32_e32 v123, v123
	v_mfma_f32_32x32x16_bf16 v[48:63], v[144:147], v[136:139], v[48:63]
	ds_read_b64_tr_b16 v[140:141], v177 offset:44032
	ds_read_b64_tr_b16 v[142:143], v177 offset:44544
	v_exp_f32_e32 v124, v124
	v_exp_f32_e32 v125, v125
	v_mfma_f32_32x32x16_bf16 v[32:47], v[144:147], v[72:75], v[32:47]
	ds_read_b64_tr_b16 v[136:137], v177 offset:48128
	ds_read_b64_tr_b16 v[138:139], v177 offset:48640
	v_exp_f32_e32 v126, v126
	v_exp_f32_e32 v127, v127
	s_waitcnt lgkmcnt(14)
	v_mfma_f32_32x32x16_bf16 v[16:31], v[156:159], v[76:79], v[16:31]
	v_exp_f32_e32 v96, v96
	v_exp_f32_e32 v97, v97
	v_mfma_f32_32x32x16_bf16 v[0:15], v[156:159], v[128:131], v[0:15]
	v_exp_f32_e32 v98, v98
	v_exp_f32_e32 v99, v99
	v_mfma_f32_32x32x16_bf16 v[16:31], v[152:155], v[132:135], v[16:31]
	v_exp_f32_e32 v100, v100
	v_exp_f32_e32 v101, v101
	s_waitcnt lgkmcnt(12)
	v_mfma_f32_32x32x16_bf16 v[0:15], v[152:155], v[178:181], v[0:15]
	v_exp_f32_e32 v102, v102
	v_exp_f32_e32 v103, v103
	s_waitcnt lgkmcnt(8)
	v_mfma_f32_32x32x16_bf16 v[16:31], v[148:151], v[190:193], v[16:31]
	v_exp_f32_e32 v104, v104
	v_exp_f32_e32 v105, v105
	s_waitcnt lgkmcnt(4)
	v_mfma_f32_32x32x16_bf16 v[0:15], v[148:151], v[194:197], v[0:15]
	v_exp_f32_e32 v106, v106
	v_exp_f32_e32 v107, v107
	s_waitcnt lgkmcnt(2)
	v_mfma_f32_32x32x16_bf16 v[16:31], v[144:147], v[140:143], v[16:31]
	v_exp_f32_e32 v108, v108
	v_exp_f32_e32 v109, v109
	s_waitcnt lgkmcnt(0)
	v_mfma_f32_32x32x16_bf16 v[0:15], v[144:147], v[136:139], v[0:15]
	v_exp_f32_e32 v110, v110
	v_exp_f32_e32 v111, v111
	s_waitcnt vmcnt(3) lgkmcnt(0)
	s_barrier
	ds_read_b64_tr_b16 v[178:179], v168 offset:24576
	ds_read_b64_tr_b16 v[180:181], v168 offset:25088
	v_add_f32_e32 v76, v112, v113
	ds_read_b128 v[72:75], v188
	v_add_f32_e32 v76, v114, v76
	v_add_f32_e32 v76, v115, v76
	v_add_f32_e32 v76, v116, v76
	v_add_f32_e32 v76, v117, v76
	v_cvt_pk_bf16_f32 v156, v112, v113
	v_cvt_pk_bf16_f32 v157, v114, v115
	s_waitcnt lgkmcnt(0)
	v_mfma_f32_32x32x16_bf16 v[128:143], v[68:71], v[72:75], 0
	ds_read_b64_tr_b16 v[112:113], v168 offset:28672
	ds_read_b64_tr_b16 v[114:115], v168 offset:29184
	ds_read_b128 v[68:71], v188
	v_add_f32_e32 v72, v118, v76
	v_add_f32_e32 v72, v119, v72
	v_add_f32_e32 v72, v120, v72
	v_add_f32_e32 v144, v121, v72
	s_waitcnt lgkmcnt(0)
	v_mfma_f32_32x32x16_bf16 v[64:79], v[64:67], v[68:71], 0
	v_cvt_pk_bf16_f32 v158, v116, v117
	v_cvt_pk_bf16_f32 v159, v118, v119
	ds_read_b64_tr_b16 v[116:117], v168 offset:25600
	ds_read_b64_tr_b16 v[118:119], v168 offset:26112
	ds_read_b128 v[190:193], v188 offset:1024
	v_add_f32_e32 v144, v122, v144
	v_add_f32_e32 v144, v123, v144
	v_add_f32_e32 v144, v124, v144
	v_add_f32_e32 v144, v125, v144
	v_cvt_pk_bf16_f32 v152, v120, v121
	v_cvt_pk_bf16_f32 v153, v122, v123
	s_waitcnt lgkmcnt(0)
	v_mfma_f32_32x32x16_bf16 v[128:143], v[164:167], v[190:193], v[128:143]
	ds_read_b64_tr_b16 v[120:121], v168 offset:29696
	ds_read_b64_tr_b16 v[122:123], v168 offset:30208
	ds_read_b128 v[164:167], v188 offset:1024
	v_add_f32_e32 v144, v126, v144
	v_add_f32_e32 v144, v127, v144
	v_add_f32_e32 v144, v96, v144
	v_add_f32_e32 v144, v97, v144
	s_waitcnt lgkmcnt(0)
; #define WAIT_BAR(N) asm volatile("s_waitcnt vmcnt(" #N ") lgkmcnt(0)\n\ts_barrier":::"memory")
;   #define RESC() do{ if(!NOMAX&&resc){ asm volatile("s_waitcnt lgkmcnt(0)":::"memory"); \
;       _Pragma("unroll") for(int d_=0;d_<2*VM;++d_) _Pragma("unroll") for(int r=0;r<16;++r)o[d_][r]*=wsf[crow(r,hi)]; } }while(0)
;   #define ROT() do{sl_prev=sl_cur;sl_cur=sl_next;sl_next=(sl_next==(NSLOT-1)*SLOTB)?0:sl_next+SLOTB;}while(0)
;   #define ENDW(tt) do{ if((tt)+3<NT){ if constexpr(VM==2){WAIT_BAR(3);}else{WAIT_BAR(2);} } else if((tt)+2<NT){ if constexpr(VM==2){WAIT_BAR(2);}else{WAIT_BAR(1);} } else {WAIT_BAR(0);} }while(0)
; template<int THRL,int VM,bool NOMAX> __device__ __forceinline__ void attn_unit(const bf16*Qb,const bf16*__restrict__ Kh,const bf16*__restrict__ Vh,bf16*Ob,const int NT,const int sp,float*wscr,char*shm){
;     ...
;   int t=1;
;   for(;t+5<NT;t+=2){
;     STEP(pB0,pB1,pA0,pA1,t,true,true,true);     if constexpr(VM==2){WAIT_BAR(3);}else{WAIT_BAR(2);} RESC(); ROT();
;     STEP(pA0,pA1,pB0,pB1,t+1,true,true,true);   if constexpr(VM==2){WAIT_BAR(3);}else{WAIT_BAR(2);} RESC(); ROT();
;   }
;     ...
;   for(;t+1<NT;t+=2){
;     STEP(pB0,pB1,pA0,pA1,t,(t+3<NT),(t+1<NT),(t+1<NT));       ENDW(t);   RESC(); ROT();
;     STEP(pA0,pA1,pB0,pB1,t+1,(t+4<NT),(t+2<NT),(t+2<NT));     ENDW(t+1); RESC(); ROT();
;   }
	v_mfma_f32_32x32x16_bf16 v[64:79], v[92:95], v[164:167], v[64:79]
	v_cvt_pk_bf16_f32 v154, v124, v125
	v_cvt_pk_bf16_f32 v155, v126, v127
	ds_read_b64_tr_b16 v[92:93], v168 offset:26624
	ds_read_b64_tr_b16 v[94:95], v168 offset:27136
	ds_read_b128 v[124:127], v188 offset:2048
	v_add_f32_e32 v144, v98, v144
	v_add_f32_e32 v144, v99, v144
	v_add_f32_e32 v144, v100, v144
	v_add_f32_e32 v144, v101, v144
	v_cvt_pk_bf16_f32 v148, v96, v97
	v_cvt_pk_bf16_f32 v149, v98, v99
	s_waitcnt lgkmcnt(0)
	v_mfma_f32_32x32x16_bf16 v[128:143], v[160:163], v[124:127], v[128:143]
	ds_read_b64_tr_b16 v[96:97], v168 offset:30720
	ds_read_b64_tr_b16 v[98:99], v168 offset:31232
	ds_read_b128 v[124:127], v188 offset:2048
	v_add_f32_e32 v144, v102, v144
	v_add_f32_e32 v144, v103, v144
	v_add_f32_e32 v144, v104, v144
	v_add_f32_e32 v144, v105, v144
	s_waitcnt lgkmcnt(0)
	v_mfma_f32_32x32x16_bf16 v[64:79], v[84:87], v[124:127], v[64:79]
	v_cvt_pk_bf16_f32 v150, v100, v101
	v_cvt_pk_bf16_f32 v151, v102, v103
	ds_read_b64_tr_b16 v[100:101], v168 offset:27648
	ds_read_b64_tr_b16 v[102:103], v168 offset:28160
	ds_read_b128 v[84:87], v188 offset:3072
	v_add_f32_e32 v124, v106, v144
	v_add_f32_e32 v124, v107, v124
	v_add_f32_e32 v124, v108, v124
	v_add_f32_e32 v124, v109, v124
	v_cvt_pk_bf16_f32 v144, v104, v105
	v_cvt_pk_bf16_f32 v145, v106, v107
	s_waitcnt lgkmcnt(0)
	v_mfma_f32_32x32x16_bf16 v[128:143], v[88:91], v[84:87], v[128:143]
	ds_read_b64_tr_b16 v[88:89], v168 offset:31744
	ds_read_b64_tr_b16 v[90:91], v168 offset:32256
	ds_read_b128 v[84:87], v188 offset:3072
	v_add_f32_e32 v104, v110, v124
	v_add_f32_e32 v104, v111, v104
	v_add_f32_e32 v104, 0, v104
	v_cvt_pk_bf16_f32 v146, v108, v109
	s_waitcnt lgkmcnt(0)
	v_mfma_f32_32x32x16_bf16 v[64:79], v[80:83], v[84:87], v[64:79]
	v_cvt_pk_bf16_f32 v147, v110, v111
	v_lshl_add_u64 v[80:81], v[174:175], 0, s[62:63]
	s_add_i32 s86, s85, 0x2000
	s_mov_b32 s87, m0
	s_mov_b32 m0, s86
	s_nop 0
	global_load_lds_dwordx4 v[80:81], off
	s_mov_b32 m0, s87
	v_lshl_add_u64 v[80:81], v[170:171], 0, s[64:65]
	s_add_i32 s86, s85, 0xe000
	s_mov_b32 s87, m0
	s_mov_b32 m0, s86
	s_nop 0
	global_load_lds_dwordx4 v[80:81], off
	s_mov_b32 m0, s87
	v_lshl_add_u64 v[80:81], v[172:173], 0, s[64:65]
	s_add_i32 s85, s85, 0x10000
	s_mov_b32 s86, m0
	s_mov_b32 m0, s85
	s_nop 0
	global_load_lds_dwordx4 v[80:81], off
	s_mov_b32 m0, s86
	v_add_f32_e32 v198, v198, v104
	v_mfma_f32_32x32x16_bf16 v[48:63], v[156:159], v[178:181], v[48:63]
	ds_read_b64_tr_b16 v[104:105], v168 offset:32768
	ds_read_b64_tr_b16 v[106:107], v168 offset:33280
	v_exp_f32_e32 v128, v128
	v_exp_f32_e32 v129, v129
	v_mfma_f32_32x32x16_bf16 v[32:47], v[156:159], v[112:115], v[32:47]
	ds_read_b64_tr_b16 v[108:109], v168 offset:36864
	ds_read_b64_tr_b16 v[110:111], v168 offset:37376
	v_exp_f32_e32 v130, v130
	v_exp_f32_e32 v131, v131
	ds_read_b128 v[84:87], v234 offset:16384
	ds_read_b128 v[80:83], v234 offset:20480
	v_mfma_f32_32x32x16_bf16 v[48:63], v[152:155], v[116:119], v[48:63]
	ds_read_b64_tr_b16 v[178:179], v168 offset:33792
	ds_read_b64_tr_b16 v[180:181], v168 offset:34304
	v_exp_f32_e32 v132, v132
	v_exp_f32_e32 v133, v133
	ds_read_b128 v[164:167], v235 offset:16384
	ds_read_b128 v[124:127], v235 offset:20480
	v_mfma_f32_32x32x16_bf16 v[32:47], v[152:155], v[120:123], v[32:47]
	ds_read_b64_tr_b16 v[190:191], v168 offset:37888
	ds_read_b64_tr_b16 v[192:193], v168 offset:38400
	v_exp_f32_e32 v134, v134
	v_exp_f32_e32 v135, v135
	ds_read_b128 v[160:163], v236 offset:16384
	ds_read_b128 v[116:119], v236 offset:20480
	v_mfma_f32_32x32x16_bf16 v[48:63], v[148:151], v[92:95], v[48:63]
	ds_read_b64_tr_b16 v[194:195], v168 offset:34816
	ds_read_b64_tr_b16 v[196:197], v168 offset:35328
	v_exp_f32_e32 v136, v136
	v_exp_f32_e32 v137, v137
	ds_read_b128 v[120:123], v237 offset:16384
	ds_read_b128 v[112:115], v237 offset:20480
	v_mfma_f32_32x32x16_bf16 v[32:47], v[148:151], v[96:99], v[32:47]
	ds_read_b64_tr_b16 v[92:93], v168 offset:38912
	ds_read_b64_tr_b16 v[94:95], v168 offset:39424
	v_exp_f32_e32 v138, v138
	v_exp_f32_e32 v139, v139
	v_mfma_f32_32x32x16_bf16 v[48:63], v[144:147], v[100:103], v[48:63]
	ds_read_b64_tr_b16 v[96:97], v168 offset:35840
	ds_read_b64_tr_b16 v[98:99], v168 offset:36352
	v_exp_f32_e32 v140, v140
	v_exp_f32_e32 v141, v141
	v_mfma_f32_32x32x16_bf16 v[32:47], v[144:147], v[88:91], v[32:47]
	ds_read_b64_tr_b16 v[100:101], v168 offset:39936
	ds_read_b64_tr_b16 v[102:103], v168 offset:40448
	v_exp_f32_e32 v142, v142
	v_exp_f32_e32 v143, v143
	s_waitcnt lgkmcnt(14)
	v_mfma_f32_32x32x16_bf16 v[16:31], v[156:159], v[104:107], v[16:31]
	v_exp_f32_e32 v64, v64
	v_exp_f32_e32 v65, v65
	v_mfma_f32_32x32x16_bf16 v[0:15], v[156:159], v[108:111], v[0:15]
	v_exp_f32_e32 v66, v66
	v_exp_f32_e32 v67, v67
	v_mfma_f32_32x32x16_bf16 v[16:31], v[152:155], v[178:181], v[16:31]
	v_exp_f32_e32 v68, v68
	v_exp_f32_e32 v69, v69
	s_waitcnt lgkmcnt(12)
	v_mfma_f32_32x32x16_bf16 v[0:15], v[152:155], v[190:193], v[0:15]
	v_exp_f32_e32 v70, v70
	v_exp_f32_e32 v71, v71
	s_waitcnt lgkmcnt(8)
	v_mfma_f32_32x32x16_bf16 v[16:31], v[148:151], v[194:197], v[16:31]
	v_exp_f32_e32 v72, v72
	v_exp_f32_e32 v73, v73
	s_waitcnt lgkmcnt(4)
	v_mfma_f32_32x32x16_bf16 v[0:15], v[148:151], v[92:95], v[0:15]
	v_exp_f32_e32 v74, v74
	v_exp_f32_e32 v75, v75
	s_waitcnt lgkmcnt(2)
	v_mfma_f32_32x32x16_bf16 v[16:31], v[144:147], v[96:99], v[16:31]
	v_exp_f32_e32 v76, v76
	v_exp_f32_e32 v77, v77
	s_waitcnt lgkmcnt(0)
	v_mfma_f32_32x32x16_bf16 v[0:15], v[144:147], v[100:103], v[0:15]
	v_exp_f32_e32 v78, v78
	v_exp_f32_e32 v79, v79
	s_waitcnt vmcnt(3) lgkmcnt(0)
	s_barrier
; #define WAIT_BAR(N) asm volatile("s_waitcnt vmcnt(" #N ") lgkmcnt(0)\n\ts_barrier":::"memory")
;   #define RESC() do{ if(!NOMAX&&resc){ asm volatile("s_waitcnt lgkmcnt(0)":::"memory"); \
;       _Pragma("unroll") for(int d_=0;d_<2*VM;++d_) _Pragma("unroll") for(int r=0;r<16;++r)o[d_][r]*=wsf[crow(r,hi)]; } }while(0)
;   #define ROT() do{sl_prev=sl_cur;sl_cur=sl_next;sl_next=(sl_next==(NSLOT-1)*SLOTB)?0:sl_next+SLOTB;}while(0)
;   #define ENDW(tt) do{ if((tt)+3<NT){ if constexpr(VM==2){WAIT_BAR(3);}else{WAIT_BAR(2);} } else if((tt)+2<NT){ if constexpr(VM==2){WAIT_BAR(2);}else{WAIT_BAR(1);} } else {WAIT_BAR(0);} }while(0)
; template<int THRL,int VM,bool NOMAX> __device__ __forceinline__ void attn_unit(const bf16*Qb,const bf16*__restrict__ Kh,const bf16*__restrict__ Vh,bf16*Ob,const int NT,const int sp,float*wscr,char*shm){
;     ...
;   int t=1;
;   for(;t+5<NT;t+=2){
;     STEP(pB0,pB1,pA0,pA1,t,true,true,true);     if constexpr(VM==2){WAIT_BAR(3);}else{WAIT_BAR(2);} RESC(); ROT();
;     STEP(pA0,pA1,pB0,pB1,t+1,true,true,true);   if constexpr(VM==2){WAIT_BAR(3);}else{WAIT_BAR(2);} RESC(); ROT();
;   }
;     ...
;   for(;t+1<NT;t+=2){
;     STEP(pB0,pB1,pA0,pA1,t,(t+3<NT),(t+1<NT),(t+1<NT));       ENDW(t);   RESC(); ROT();
;     STEP(pA0,pA1,pB0,pB1,t+1,(t+4<NT),(t+2<NT),(t+2<NT));     ENDW(t+1); RESC(); ROT();
;   }
	ds_read_b64_tr_b16 v[178:179], v168 offset:40960
	ds_read_b64_tr_b16 v[180:181], v168 offset:41472
	v_add_f32_e32 v92, v128, v129
	ds_read_b128 v[88:91], v188
	v_add_f32_e32 v92, v130, v92
	v_add_f32_e32 v92, v131, v92
	v_add_f32_e32 v92, v132, v92
	v_add_f32_e32 v92, v133, v92
	v_cvt_pk_bf16_f32 v156, v128, v129
	v_cvt_pk_bf16_f32 v157, v130, v131
	s_waitcnt lgkmcnt(0)
	v_mfma_f32_32x32x16_bf16 v[96:111], v[84:87], v[88:91], 0
	ds_read_b64_tr_b16 v[128:129], v168 offset:45056
	ds_read_b64_tr_b16 v[130:131], v168 offset:45568
	ds_read_b128 v[84:87], v188
	v_add_f32_e32 v88, v134, v92
	v_add_f32_e32 v88, v135, v88
	v_add_f32_e32 v88, v136, v88
	v_add_f32_e32 v144, v137, v88
	v_cvt_pk_bf16_f32 v158, v132, v133
	v_cvt_pk_bf16_f32 v159, v134, v135
	s_waitcnt lgkmcnt(0)
	v_mfma_f32_32x32x16_bf16 v[80:95], v[80:83], v[84:87], 0
	ds_read_b64_tr_b16 v[132:133], v168 offset:41984
	ds_read_b64_tr_b16 v[134:135], v168 offset:42496
	ds_read_b128 v[190:193], v188 offset:1024
	v_add_f32_e32 v144, v138, v144
	v_add_f32_e32 v144, v139, v144
	v_add_f32_e32 v144, v140, v144
	v_add_f32_e32 v144, v141, v144
	v_cvt_pk_bf16_f32 v152, v136, v137
	v_cvt_pk_bf16_f32 v153, v138, v139
	s_waitcnt lgkmcnt(0)
	v_mfma_f32_32x32x16_bf16 v[96:111], v[164:167], v[190:193], v[96:111]
	ds_read_b64_tr_b16 v[136:137], v168 offset:46080
	ds_read_b64_tr_b16 v[138:139], v168 offset:46592
	ds_read_b128 v[164:167], v188 offset:1024
	v_add_f32_e32 v144, v142, v144
	v_add_f32_e32 v144, v143, v144
	v_add_f32_e32 v144, v64, v144
	v_add_f32_e32 v144, v65, v144
	v_cvt_pk_bf16_f32 v154, v140, v141
	v_cvt_pk_bf16_f32 v155, v142, v143
	s_waitcnt lgkmcnt(0)
	v_mfma_f32_32x32x16_bf16 v[80:95], v[124:127], v[164:167], v[80:95]
	ds_read_b64_tr_b16 v[124:125], v168 offset:43008
	ds_read_b64_tr_b16 v[126:127], v168 offset:43520
	ds_read_b128 v[140:143], v188 offset:2048
	v_add_f32_e32 v144, v66, v144
	v_add_f32_e32 v144, v67, v144
	v_add_f32_e32 v144, v68, v144
	v_add_f32_e32 v144, v69, v144
	v_cvt_pk_bf16_f32 v148, v64, v65
	v_cvt_pk_bf16_f32 v149, v66, v67
	s_waitcnt lgkmcnt(0)
	v_mfma_f32_32x32x16_bf16 v[96:111], v[160:163], v[140:143], v[96:111]
	ds_read_b64_tr_b16 v[190:191], v168 offset:47104
	ds_read_b64_tr_b16 v[192:193], v168 offset:47616
	ds_read_b128 v[64:67], v188 offset:2048
	v_add_f32_e32 v140, v70, v144
	v_add_f32_e32 v140, v71, v140
	v_add_f32_e32 v140, v72, v140
	v_add_f32_e32 v140, v73, v140
	v_cvt_pk_bf16_f32 v150, v68, v69
	v_cvt_pk_bf16_f32 v151, v70, v71
	s_waitcnt lgkmcnt(0)
	v_mfma_f32_32x32x16_bf16 v[80:95], v[116:119], v[64:67], v[80:95]
	ds_read_b64_tr_b16 v[116:117], v168 offset:44032
	ds_read_b64_tr_b16 v[118:119], v168 offset:44544
	ds_read_b128 v[64:67], v188 offset:3072
	v_add_f32_e32 v68, v74, v140
	v_add_f32_e32 v68, v75, v68
	v_add_f32_e32 v68, v76, v68
	v_add_f32_e32 v68, v77, v68
	v_cvt_pk_bf16_f32 v144, v72, v73
	v_cvt_pk_bf16_f32 v145, v74, v75
	s_waitcnt lgkmcnt(0)
	v_mfma_f32_32x32x16_bf16 v[96:111], v[120:123], v[64:67], v[96:111]
	ds_read_b64_tr_b16 v[72:73], v168 offset:48128
	ds_read_b64_tr_b16 v[74:75], v168 offset:48640
	ds_read_b128 v[64:67], v188 offset:3072
	v_add_f32_e32 v68, v78, v68
	v_add_f32_e32 v68, v79, v68
	v_add_f32_e32 v68, 0, v68
	v_cvt_pk_bf16_f32 v146, v76, v77
	v_cvt_pk_bf16_f32 v147, v78, v79
	s_waitcnt lgkmcnt(0)
	v_mfma_f32_32x32x16_bf16 v[80:95], v[112:115], v[64:67], v[80:95]
	v_lshl_add_u64 v[64:65], v[170:171], 0, s[58:59]
	s_mov_b32 s85, m0
	s_mov_b32 m0, s16
	s_nop 0
	global_load_lds_dwordx4 v[64:65], off
	s_mov_b32 m0, s85
	v_lshl_add_u64 v[64:65], v[172:173], 0, s[58:59]
	s_addk_i32 s16, 0x2000
	s_mov_b32 s85, m0
	s_mov_b32 m0, s16
	s_nop 0
	global_load_lds_dwordx4 v[64:65], off
	s_mov_b32 m0, s85
	v_add_f32_e32 v174, v198, v68
	v_mfma_f32_32x32x16_bf16 v[48:63], v[156:159], v[178:181], v[48:63]
	ds_read_b64_tr_b16 v[76:77], v168 offset:49152
	ds_read_b64_tr_b16 v[78:79], v168 offset:49664
	v_exp_f32_e32 v96, v96
	v_exp_f32_e32 v97, v97
	v_mfma_f32_32x32x16_bf16 v[32:47], v[156:159], v[128:131], v[32:47]
	ds_read_b64_tr_b16 v[112:113], v168 offset:53248
	ds_read_b64_tr_b16 v[114:115], v168 offset:53760
	v_exp_f32_e32 v98, v98
	v_exp_f32_e32 v99, v99
	ds_read_b128 v[68:71], v234
	ds_read_b128 v[64:67], v234 offset:4096
	v_mfma_f32_32x32x16_bf16 v[48:63], v[152:155], v[132:135], v[48:63]
	ds_read_b64_tr_b16 v[120:121], v168 offset:50176
	ds_read_b64_tr_b16 v[122:123], v168 offset:50688
	v_exp_f32_e32 v100, v100
	v_exp_f32_e32 v101, v101
	ds_read_b128 v[164:167], v235
	ds_read_b128 v[140:143], v235 offset:4096
	v_mfma_f32_32x32x16_bf16 v[32:47], v[152:155], v[136:139], v[32:47]
	ds_read_b64_tr_b16 v[178:179], v168 offset:54272
	ds_read_b64_tr_b16 v[180:181], v168 offset:54784
	v_exp_f32_e32 v102, v102
	v_exp_f32_e32 v103, v103
	ds_read_b128 v[160:163], v236
	ds_read_b128 v[132:135], v236 offset:4096
	v_mfma_f32_32x32x16_bf16 v[48:63], v[148:151], v[124:127], v[48:63]
	ds_read_b64_tr_b16 v[194:195], v168 offset:51200
	ds_read_b64_tr_b16 v[196:197], v168 offset:51712
	v_exp_f32_e32 v104, v104
	v_exp_f32_e32 v105, v105
	ds_read_b128 v[136:139], v237
	ds_read_b128 v[128:131], v237 offset:4096
	v_mfma_f32_32x32x16_bf16 v[32:47], v[148:151], v[190:193], v[32:47]
	ds_read_b64_tr_b16 v[124:125], v168 offset:55296
	ds_read_b64_tr_b16 v[126:127], v168 offset:55808
	v_exp_f32_e32 v106, v106
	v_exp_f32_e32 v107, v107
	v_mfma_f32_32x32x16_bf16 v[48:63], v[144:147], v[116:119], v[48:63]
	ds_read_b64_tr_b16 v[190:191], v168 offset:52224
	ds_read_b64_tr_b16 v[192:193], v168 offset:52736
	v_exp_f32_e32 v108, v108
	v_exp_f32_e32 v109, v109
	v_mfma_f32_32x32x16_bf16 v[32:47], v[144:147], v[72:75], v[32:47]
	ds_read_b64_tr_b16 v[116:117], v168 offset:56320
	ds_read_b64_tr_b16 v[118:119], v168 offset:56832
	v_exp_f32_e32 v110, v110
	v_exp_f32_e32 v111, v111
	s_waitcnt lgkmcnt(14)
	v_mfma_f32_32x32x16_bf16 v[16:31], v[156:159], v[76:79], v[16:31]
	v_exp_f32_e32 v80, v80
	v_exp_f32_e32 v81, v81
	v_mfma_f32_32x32x16_bf16 v[0:15], v[156:159], v[112:115], v[0:15]
	v_exp_f32_e32 v82, v82
	v_exp_f32_e32 v83, v83
	v_mfma_f32_32x32x16_bf16 v[16:31], v[152:155], v[120:123], v[16:31]
	v_exp_f32_e32 v84, v84
	v_exp_f32_e32 v85, v85
	s_waitcnt lgkmcnt(12)
	v_mfma_f32_32x32x16_bf16 v[0:15], v[152:155], v[178:181], v[0:15]
	v_exp_f32_e32 v86, v86
	v_exp_f32_e32 v87, v87
	s_waitcnt lgkmcnt(8)
	v_mfma_f32_32x32x16_bf16 v[16:31], v[148:151], v[194:197], v[16:31]
	v_exp_f32_e32 v88, v88
	v_exp_f32_e32 v89, v89
	s_waitcnt lgkmcnt(4)
	v_mfma_f32_32x32x16_bf16 v[0:15], v[148:151], v[124:127], v[0:15]
	v_exp_f32_e32 v90, v90
	v_exp_f32_e32 v91, v91
	s_waitcnt lgkmcnt(2)
	v_mfma_f32_32x32x16_bf16 v[16:31], v[144:147], v[190:193], v[16:31]
	v_exp_f32_e32 v92, v92
	v_exp_f32_e32 v93, v93
	s_waitcnt lgkmcnt(0)
	v_mfma_f32_32x32x16_bf16 v[0:15], v[144:147], v[116:119], v[0:15]
	v_exp_f32_e32 v94, v94
	v_exp_f32_e32 v95, v95
	s_waitcnt vmcnt(2) lgkmcnt(0)
	s_barrier
; #define WAIT_BAR(N) asm volatile("s_waitcnt vmcnt(" #N ") lgkmcnt(0)\n\ts_barrier":::"memory")
;   #define RESC() do{ if(!NOMAX&&resc){ asm volatile("s_waitcnt lgkmcnt(0)":::"memory"); \
;       _Pragma("unroll") for(int d_=0;d_<2*VM;++d_) _Pragma("unroll") for(int r=0;r<16;++r)o[d_][r]*=wsf[crow(r,hi)]; } }while(0)
;   #define ROT() do{sl_prev=sl_cur;sl_cur=sl_next;sl_next=(sl_next==(NSLOT-1)*SLOTB)?0:sl_next+SLOTB;}while(0)
;   #define ENDW(tt) do{ if((tt)+3<NT){ if constexpr(VM==2){WAIT_BAR(3);}else{WAIT_BAR(2);} } else if((tt)+2<NT){ if constexpr(VM==2){WAIT_BAR(2);}else{WAIT_BAR(1);} } else {WAIT_BAR(0);} }while(0)
; template<int THRL,int VM,bool NOMAX> __device__ __forceinline__ void attn_unit(const bf16*Qb,const bf16*__restrict__ Kh,const bf16*__restrict__ Vh,bf16*Ob,const int NT,const int sp,float*wscr,char*shm){
;     ...
;   int t=1;
;   for(;t+5<NT;t+=2){
;     STEP(pB0,pB1,pA0,pA1,t,true,true,true);     if constexpr(VM==2){WAIT_BAR(3);}else{WAIT_BAR(2);} RESC(); ROT();
;     STEP(pA0,pA1,pB0,pB1,t+1,true,true,true);   if constexpr(VM==2){WAIT_BAR(3);}else{WAIT_BAR(2);} RESC(); ROT();
;   }
;     ...
;   for(;t+1<NT;t+=2){
;     STEP(pB0,pB1,pA0,pA1,t,(t+3<NT),(t+1<NT),(t+1<NT));       ENDW(t);   RESC(); ROT();
;     STEP(pA0,pA1,pB0,pB1,t+1,(t+4<NT),(t+2<NT),(t+2<NT));     ENDW(t+1); RESC(); ROT();
;   }
	ds_read_b64_tr_b16 v[178:179], v168 offset:57344
	ds_read_b64_tr_b16 v[180:181], v168 offset:57856
	v_add_f32_e32 v76, v96, v97
	ds_read_b128 v[72:75], v188
	v_add_f32_e32 v76, v98, v76
	v_add_f32_e32 v76, v99, v76
	v_add_f32_e32 v76, v100, v76
	v_add_f32_e32 v76, v101, v76
	v_cvt_pk_bf16_f32 v156, v96, v97
	v_cvt_pk_bf16_f32 v157, v98, v99
	s_waitcnt lgkmcnt(0)
	v_mfma_f32_32x32x16_bf16 v[112:127], v[68:71], v[72:75], 0
	ds_read_b64_tr_b16 v[96:97], v168 offset:61440
	ds_read_b64_tr_b16 v[98:99], v168 offset:61952
	ds_read_b128 v[68:71], v188
	v_add_f32_e32 v72, v102, v76
	v_add_f32_e32 v72, v103, v72
	v_add_f32_e32 v72, v104, v72
	v_add_f32_e32 v144, v105, v72
	s_waitcnt lgkmcnt(0)
	v_mfma_f32_32x32x16_bf16 v[64:79], v[64:67], v[68:71], 0
	v_cvt_pk_bf16_f32 v158, v100, v101
	v_cvt_pk_bf16_f32 v159, v102, v103
	ds_read_b64_tr_b16 v[100:101], v168 offset:58368
	ds_read_b64_tr_b16 v[102:103], v168 offset:58880
	ds_read_b128 v[190:193], v188 offset:1024
	v_add_f32_e32 v144, v106, v144
	v_add_f32_e32 v144, v107, v144
	v_add_f32_e32 v144, v108, v144
	v_add_f32_e32 v144, v109, v144
	v_cvt_pk_bf16_f32 v152, v104, v105
	v_cvt_pk_bf16_f32 v153, v106, v107
	s_waitcnt lgkmcnt(0)
	v_mfma_f32_32x32x16_bf16 v[112:127], v[164:167], v[190:193], v[112:127]
	ds_read_b64_tr_b16 v[104:105], v168 offset:62464
	ds_read_b64_tr_b16 v[106:107], v168 offset:62976
	ds_read_b128 v[164:167], v188 offset:1024
	v_add_f32_e32 v144, v110, v144
	v_add_f32_e32 v144, v111, v144
	v_add_f32_e32 v144, v80, v144
	v_add_f32_e32 v144, v81, v144
	s_waitcnt lgkmcnt(0)
	v_mfma_f32_32x32x16_bf16 v[64:79], v[140:143], v[164:167], v[64:79]
	v_cvt_pk_bf16_f32 v154, v108, v109
	v_cvt_pk_bf16_f32 v155, v110, v111
	ds_read_b64_tr_b16 v[108:109], v168 offset:59392
	ds_read_b64_tr_b16 v[110:111], v168 offset:59904
	ds_read_b128 v[140:143], v188 offset:2048
	v_add_f32_e32 v144, v82, v144
	v_add_f32_e32 v144, v83, v144
	v_add_f32_e32 v144, v84, v144
	v_add_f32_e32 v144, v85, v144
	v_cvt_pk_bf16_f32 v148, v80, v81
	v_cvt_pk_bf16_f32 v149, v82, v83
	s_waitcnt lgkmcnt(0)
	v_mfma_f32_32x32x16_bf16 v[112:127], v[160:163], v[140:143], v[112:127]
	ds_read_b64_tr_b16 v[190:191], v168 offset:63488
	ds_read_b64_tr_b16 v[192:193], v168 offset:64000
	ds_read_b128 v[80:83], v188 offset:2048
	v_add_f32_e32 v140, v86, v144
	v_add_f32_e32 v140, v87, v140
	v_add_f32_e32 v140, v88, v140
	v_add_f32_e32 v140, v89, v140
	s_waitcnt lgkmcnt(0)
	v_mfma_f32_32x32x16_bf16 v[64:79], v[132:135], v[80:83], v[64:79]
	v_cvt_pk_bf16_f32 v150, v84, v85
	v_cvt_pk_bf16_f32 v151, v86, v87
	ds_read_b64_tr_b16 v[84:85], v168 offset:60416
	ds_read_b64_tr_b16 v[86:87], v168 offset:60928
	ds_read_b128 v[80:83], v188 offset:3072
	v_add_f32_e32 v132, v90, v140
	v_add_f32_e32 v132, v91, v132
	v_add_f32_e32 v132, v92, v132
	v_add_f32_e32 v132, v93, v132
	v_cvt_pk_bf16_f32 v144, v88, v89
	v_cvt_pk_bf16_f32 v145, v90, v91
	s_waitcnt lgkmcnt(0)
	v_mfma_f32_32x32x16_bf16 v[112:127], v[136:139], v[80:83], v[112:127]
	ds_read_b64_tr_b16 v[88:89], v168 offset:64512
	ds_read_b64_tr_b16 v[90:91], v168 offset:65024
	ds_read_b128 v[80:83], v188 offset:3072
	v_add_f32_e32 v132, v94, v132
	v_add_f32_e32 v132, v95, v132
	v_add_f32_e32 v132, 0, v132
	v_cvt_pk_bf16_f32 v146, v92, v93
	s_waitcnt lgkmcnt(0)
	v_mfma_f32_32x32x16_bf16 v[64:79], v[128:131], v[80:83], v[64:79]
	v_cvt_pk_bf16_f32 v147, v94, v95
	v_lshl_add_u64 v[80:81], v[170:171], 0, s[62:63]
	s_mov_b32 s16, m0
	s_mov_b32 m0, s17
	s_nop 0
	global_load_lds_dwordx4 v[80:81], off
	s_mov_b32 m0, s16
	v_lshl_add_u64 v[80:81], v[172:173], 0, s[62:63]
	s_mov_b32 s16, m0
	s_mov_b32 m0, s35
	s_nop 0
	global_load_lds_dwordx4 v[80:81], off
	s_mov_b32 m0, s16
	v_add_f32_e32 v174, v174, v132
	v_mfma_f32_32x32x16_bf16 v[48:63], v[156:159], v[178:181], v[48:63]
	ds_read_b64_tr_b16 v[92:93], v177 offset:40960
	ds_read_b64_tr_b16 v[94:95], v177 offset:41472
	v_exp_f32_e32 v112, v112
	v_exp_f32_e32 v113, v113
	v_mfma_f32_32x32x16_bf16 v[32:47], v[156:159], v[96:99], v[32:47]
	ds_read_b64_tr_b16 v[170:171], v177 offset:45056
	ds_read_b64_tr_b16 v[172:173], v177 offset:45568
	v_exp_f32_e32 v114, v114
	v_exp_f32_e32 v115, v115
	ds_read_b128 v[80:83], v234 offset:8192
	ds_read_b128 v[96:99], v234 offset:12288
	v_mfma_f32_32x32x16_bf16 v[48:63], v[152:155], v[100:103], v[48:63]
	ds_read_b64_tr_b16 v[178:179], v177 offset:41984
	ds_read_b64_tr_b16 v[180:181], v177 offset:42496
	v_exp_f32_e32 v116, v116
	v_exp_f32_e32 v117, v117
	ds_read_b128 v[164:167], v235 offset:8192
	ds_read_b128 v[140:143], v235 offset:12288
	v_mfma_f32_32x32x16_bf16 v[32:47], v[152:155], v[104:107], v[32:47]
	ds_read_b64_tr_b16 v[100:101], v177 offset:46080
	ds_read_b64_tr_b16 v[102:103], v177 offset:46592
	v_exp_f32_e32 v118, v118
	v_exp_f32_e32 v119, v119
	ds_read_b128 v[160:163], v236 offset:8192
	ds_read_b128 v[132:135], v236 offset:12288
	v_mfma_f32_32x32x16_bf16 v[48:63], v[148:151], v[108:111], v[48:63]
	ds_read_b64_tr_b16 v[104:105], v177 offset:43008
	ds_read_b64_tr_b16 v[106:107], v177 offset:43520
	v_exp_f32_e32 v120, v120
	v_exp_f32_e32 v121, v121
	ds_read_b128 v[136:139], v237 offset:8192
	ds_read_b128 v[128:131], v237 offset:12288
	v_mfma_f32_32x32x16_bf16 v[32:47], v[148:151], v[190:193], v[32:47]
	ds_read_b64_tr_b16 v[108:109], v177 offset:47104
	ds_read_b64_tr_b16 v[110:111], v177 offset:47616
	v_exp_f32_e32 v122, v122
	v_exp_f32_e32 v123, v123
	v_mfma_f32_32x32x16_bf16 v[48:63], v[144:147], v[84:87], v[48:63]
	ds_read_b64_tr_b16 v[190:191], v177 offset:44032
	ds_read_b64_tr_b16 v[192:193], v177 offset:44544
	v_exp_f32_e32 v124, v124
	v_exp_f32_e32 v125, v125
	v_mfma_f32_32x32x16_bf16 v[32:47], v[144:147], v[88:91], v[32:47]
	ds_read_b64_tr_b16 v[84:85], v177 offset:48128
	ds_read_b64_tr_b16 v[86:87], v177 offset:48640
	v_exp_f32_e32 v126, v126
	v_exp_f32_e32 v127, v127
	s_waitcnt lgkmcnt(14)
	v_mfma_f32_32x32x16_bf16 v[16:31], v[156:159], v[92:95], v[16:31]
	v_exp_f32_e32 v64, v64
	v_exp_f32_e32 v65, v65
	v_mfma_f32_32x32x16_bf16 v[0:15], v[156:159], v[170:173], v[0:15]
	v_exp_f32_e32 v66, v66
	v_exp_f32_e32 v67, v67
	v_mfma_f32_32x32x16_bf16 v[16:31], v[152:155], v[178:181], v[16:31]
	v_exp_f32_e32 v68, v68
	v_exp_f32_e32 v69, v69
	s_waitcnt lgkmcnt(12)
	v_mfma_f32_32x32x16_bf16 v[0:15], v[152:155], v[100:103], v[0:15]
	v_exp_f32_e32 v70, v70
	v_exp_f32_e32 v71, v71
	s_waitcnt lgkmcnt(8)
	v_mfma_f32_32x32x16_bf16 v[16:31], v[148:151], v[104:107], v[16:31]
	v_exp_f32_e32 v72, v72
	v_exp_f32_e32 v73, v73
	s_waitcnt lgkmcnt(4)
	v_mfma_f32_32x32x16_bf16 v[0:15], v[148:151], v[108:111], v[0:15]
	v_exp_f32_e32 v74, v74
	v_exp_f32_e32 v75, v75
	s_waitcnt lgkmcnt(2)
	v_mfma_f32_32x32x16_bf16 v[16:31], v[144:147], v[190:193], v[16:31]
	v_exp_f32_e32 v76, v76
	v_exp_f32_e32 v77, v77
	s_waitcnt lgkmcnt(0)
	v_mfma_f32_32x32x16_bf16 v[0:15], v[144:147], v[84:87], v[0:15]
	v_exp_f32_e32 v78, v78
	v_exp_f32_e32 v79, v79
	s_waitcnt vmcnt(0) lgkmcnt(0)
	s_barrier
;   #define RESC() do{ if(!NOMAX&&resc){ asm volatile("s_waitcnt lgkmcnt(0)":::"memory"); \
;       _Pragma("unroll") for(int d_=0;d_<2*VM;++d_) _Pragma("unroll") for(int r=0;r<16;++r)o[d_][r]*=wsf[crow(r,hi)]; } }while(0)
; template<int THRL,int VM,bool NOMAX> __device__ __forceinline__ void attn_unit(const bf16*Qb,const bf16*__restrict__ Kh,const bf16*__restrict__ Vh,bf16*Ob,const int NT,const int sp,float*wscr,char*shm){
;     ...
;   STEP(pB0,pB1,pA0,pA1,NT-1,false,false,false); RESC();
	ds_read_b64_tr_b16 v[170:171], v168 offset:24576
	ds_read_b64_tr_b16 v[172:173], v168 offset:25088
	v_add_f32_e32 v88, v112, v113
	ds_read_b128 v[84:87], v188
	v_add_f32_e32 v88, v114, v88
	v_add_f32_e32 v88, v115, v88
	v_add_f32_e32 v88, v116, v88
	v_add_f32_e32 v104, v117, v88
	v_cvt_pk_bf16_f32 v156, v112, v113
	v_cvt_pk_bf16_f32 v157, v114, v115
	s_waitcnt lgkmcnt(0)
	v_mfma_f32_32x32x16_bf16 v[80:95], v[80:83], v[84:87], 0
	ds_read_b64_tr_b16 v[112:113], v168 offset:28672
	ds_read_b64_tr_b16 v[114:115], v168 offset:29184
	ds_read_b128 v[100:103], v188
	v_add_f32_e32 v104, v118, v104
	v_add_f32_e32 v104, v119, v104
	v_add_f32_e32 v104, v120, v104
	v_add_f32_e32 v144, v121, v104
	v_cvt_pk_bf16_f32 v158, v116, v117
	v_cvt_pk_bf16_f32 v159, v118, v119
	s_waitcnt lgkmcnt(0)
	v_mfma_f32_32x32x16_bf16 v[96:111], v[96:99], v[100:103], 0
	ds_read_b64_tr_b16 v[116:117], v168 offset:25600
	ds_read_b64_tr_b16 v[118:119], v168 offset:26112
	ds_read_b128 v[178:181], v188 offset:1024
	v_add_f32_e32 v144, v122, v144
	v_add_f32_e32 v144, v123, v144
	v_add_f32_e32 v144, v124, v144
	v_add_f32_e32 v144, v125, v144
	v_cvt_pk_bf16_f32 v152, v120, v121
	v_cvt_pk_bf16_f32 v153, v122, v123
	s_waitcnt lgkmcnt(0)
	v_mfma_f32_32x32x16_bf16 v[80:95], v[164:167], v[178:181], v[80:95]
	ds_read_b64_tr_b16 v[120:121], v168 offset:29696
	ds_read_b64_tr_b16 v[122:123], v168 offset:30208
	ds_read_b128 v[164:167], v188 offset:1024
	v_add_f32_e32 v144, v126, v144
	v_add_f32_e32 v144, v127, v144
	v_add_f32_e32 v144, v64, v144
	v_add_f32_e32 v144, v65, v144
	v_cvt_pk_bf16_f32 v154, v124, v125
	v_cvt_pk_bf16_f32 v155, v126, v127
	s_waitcnt lgkmcnt(0)
	v_mfma_f32_32x32x16_bf16 v[96:111], v[140:143], v[164:167], v[96:111]
	ds_read_b64_tr_b16 v[124:125], v168 offset:26624
	ds_read_b64_tr_b16 v[126:127], v168 offset:27136
	ds_read_b128 v[140:143], v188 offset:2048
	v_add_f32_e32 v144, v66, v144
	v_add_f32_e32 v144, v67, v144
	v_add_f32_e32 v144, v68, v144
	v_add_f32_e32 v144, v69, v144
	v_cvt_pk_bf16_f32 v148, v64, v65
	v_cvt_pk_bf16_f32 v149, v66, v67
	s_waitcnt lgkmcnt(0)
	v_mfma_f32_32x32x16_bf16 v[80:95], v[160:163], v[140:143], v[80:95]
	ds_read_b64_tr_b16 v[64:65], v168 offset:30720
	ds_read_b64_tr_b16 v[66:67], v168 offset:31232
	ds_read_b128 v[140:143], v188 offset:2048
	v_add_f32_e32 v144, v70, v144
	v_add_f32_e32 v144, v71, v144
	v_add_f32_e32 v144, v72, v144
	v_add_f32_e32 v144, v73, v144
	v_cvt_pk_bf16_f32 v150, v68, v69
	v_cvt_pk_bf16_f32 v151, v70, v71
	s_waitcnt lgkmcnt(0)
	v_mfma_f32_32x32x16_bf16 v[96:111], v[132:135], v[140:143], v[96:111]
	ds_read_b64_tr_b16 v[68:69], v168 offset:27648
	ds_read_b64_tr_b16 v[70:71], v168 offset:28160
	ds_read_b128 v[132:135], v188 offset:3072
	v_add_f32_e32 v140, v74, v144
	v_add_f32_e32 v140, v75, v140
	v_add_f32_e32 v140, v76, v140
	v_add_f32_e32 v140, v77, v140
	v_cvt_pk_bf16_f32 v144, v72, v73
	v_cvt_pk_bf16_f32 v145, v74, v75
	s_waitcnt lgkmcnt(0)
	v_mfma_f32_32x32x16_bf16 v[80:95], v[136:139], v[132:135], v[80:95]
	ds_read_b64_tr_b16 v[72:73], v168 offset:31744
	ds_read_b64_tr_b16 v[74:75], v168 offset:32256
	ds_read_b128 v[132:135], v188 offset:3072
	v_add_f32_e32 v136, v78, v140
	v_add_f32_e32 v136, v79, v136
	v_add_f32_e32 v136, 0, v136
	v_cvt_pk_bf16_f32 v146, v76, v77
	v_cvt_pk_bf16_f32 v147, v78, v79
	s_waitcnt lgkmcnt(0)
	v_mfma_f32_32x32x16_bf16 v[96:111], v[128:131], v[132:135], v[96:111]
	v_mfma_f32_32x32x16_bf16 v[48:63], v[156:159], v[170:173], v[48:63]
	ds_read_b64_tr_b16 v[76:77], v168 offset:32768
	ds_read_b64_tr_b16 v[78:79], v168 offset:33280
	v_exp_f32_e32 v80, v80
	v_exp_f32_e32 v81, v81
	v_mfma_f32_32x32x16_bf16 v[32:47], v[156:159], v[112:115], v[32:47]
	ds_read_b64_tr_b16 v[128:129], v168 offset:36864
	ds_read_b64_tr_b16 v[130:131], v168 offset:37376
	v_exp_f32_e32 v82, v82
	v_exp_f32_e32 v83, v83
	v_mfma_f32_32x32x16_bf16 v[48:63], v[152:155], v[116:119], v[48:63]
	ds_read_b64_tr_b16 v[112:113], v168 offset:33792
	ds_read_b64_tr_b16 v[114:115], v168 offset:34304
	v_exp_f32_e32 v84, v84
	v_exp_f32_e32 v85, v85
	v_mfma_f32_32x32x16_bf16 v[32:47], v[152:155], v[120:123], v[32:47]
	ds_read_b64_tr_b16 v[116:117], v168 offset:37888
	ds_read_b64_tr_b16 v[118:119], v168 offset:38400
	v_exp_f32_e32 v86, v86
	v_exp_f32_e32 v87, v87
	v_mfma_f32_32x32x16_bf16 v[48:63], v[148:151], v[124:127], v[48:63]
	ds_read_b64_tr_b16 v[120:121], v168 offset:34816
	ds_read_b64_tr_b16 v[122:123], v168 offset:35328
	v_exp_f32_e32 v88, v88
	v_exp_f32_e32 v89, v89
	v_mfma_f32_32x32x16_bf16 v[32:47], v[148:151], v[64:67], v[32:47]
	ds_read_b64_tr_b16 v[124:125], v168 offset:38912
	ds_read_b64_tr_b16 v[126:127], v168 offset:39424
	v_exp_f32_e32 v90, v90
	v_exp_f32_e32 v91, v91
	v_mfma_f32_32x32x16_bf16 v[48:63], v[144:147], v[68:71], v[48:63]
	ds_read_b64_tr_b16 v[64:65], v168 offset:35840
	ds_read_b64_tr_b16 v[66:67], v168 offset:36352
	v_exp_f32_e32 v92, v92
	v_exp_f32_e32 v93, v93
	v_mfma_f32_32x32x16_bf16 v[32:47], v[144:147], v[72:75], v[32:47]
	ds_read_b64_tr_b16 v[68:69], v168 offset:39936
	ds_read_b64_tr_b16 v[70:71], v168 offset:40448
	v_exp_f32_e32 v94, v94
	v_exp_f32_e32 v95, v95
	s_waitcnt lgkmcnt(14)
	v_mfma_f32_32x32x16_bf16 v[16:31], v[156:159], v[76:79], v[16:31]
	v_exp_f32_e32 v96, v96
	v_exp_f32_e32 v97, v97
	s_waitcnt lgkmcnt(12)
; #define SBAR() __builtin_amdgcn_sched_barrier(0)
;   #define PKW(P,B) cvtpk_s(P[B],P[B+1])
; __device__ __forceinline__ void pv(f32x16*o,int vb,bf16x8 pa0,bf16x8 pa1,bf16x8 pa2,bf16x8 pa3){
;   #pragma unroll
;   for(int d0=0;d0<2;++d0){s16x4 lo[4],hi[4];
;     #pragma unroll
;     for(int ks=0;ks<4;++ks){
;       asm volatile("ds_read_b64_tr_b16 %0,%1 offset:%c2":"=&v"(lo[ks]):"v"(vb),"i"(d0*4096+ks*1024):"memory");
;       asm volatile("ds_read_b64_tr_b16 %0,%1 offset:%c2":"=&v"(hi[ks]):"v"(vb),"i"(d0*4096+ks*1024+512):"memory");}
;     asm volatile("s_waitcnt lgkmcnt(0)":::"memory");SBAR();
;     ...
;     o[d0]=__builtin_amdgcn_mfma_f32_32x32x16_bf16(pa0,PK(0),o[d0],0,0,0);
;     o[d0]=__builtin_amdgcn_mfma_f32_32x32x16_bf16(pa1,PK(1),o[d0],0,0,0);
;     o[d0]=__builtin_amdgcn_mfma_f32_32x32x16_bf16(pa2,PK(2),o[d0],0,0,0);
;     o[d0]=__builtin_amdgcn_mfma_f32_32x32x16_bf16(pa3,PK(3),o[d0],0,0,0);
;     ...
;   }
; }
; template<int THRL,int VM,bool NOMAX> __device__ __forceinline__ void attn_unit(const bf16*Qb,const bf16*__restrict__ Kh,const bf16*__restrict__ Vh,bf16*Ob,const int NT,const int sp,float*wscr,char*shm){
;     ...
;   { float sacc=pB0[0]+pB0[1]; _Pragma("unroll") for(int r=2;r<16;++r)sacc+=pB0[r]; _Pragma("unroll") for(int r=0;r<16;++r)sacc+=pB1[r]; l_reg+=sacc;
;     pw0=(u32x4){PKW(pB0,0),PKW(pB0,2),PKW(pB0,4),PKW(pB0,6)};pw1=(u32x4){PKW(pB0,8),PKW(pB0,10),PKW(pB0,12),PKW(pB0,14)};pw2=(u32x4){PKW(pB1,0),PKW(pB1,2),PKW(pB1,4),PKW(pB1,6)};pw3=(u32x4){PKW(pB1,8),PKW(pB1,10),PKW(pB1,12),PKW(pB1,14)};
;     SBAR(); pv(o,vb0+VM*sl_cur,PAF(0),PAF(1),PAF(2),PAF(3)); if constexpr(VM==2) pv(o+2,vb0+VM*sl_cur+8192,PAF(0),PAF(1),PAF(2),PAF(3)); }
;     ...
;   {auto rr=__builtin_amdgcn_permlane32_swap(__float_as_uint(l_reg),__float_as_uint(l_reg),false,false);l_reg=__uint_as_float(rr[0])+__uint_as_float(rr[1]);}
;   if(hi==0)wsf[32+r32]=l_reg;asm volatile("s_waitcnt lgkmcnt(0)":::"memory");
	v_mfma_f32_32x32x16_bf16 v[0:15], v[156:159], v[128:131], v[0:15]
	v_exp_f32_e32 v98, v98
	v_exp_f32_e32 v99, v99
	s_waitcnt lgkmcnt(10)
	v_mfma_f32_32x32x16_bf16 v[16:31], v[152:155], v[112:115], v[16:31]
	v_exp_f32_e32 v100, v100
	v_exp_f32_e32 v101, v101
	s_waitcnt lgkmcnt(8)
	v_mfma_f32_32x32x16_bf16 v[0:15], v[152:155], v[116:119], v[0:15]
	v_exp_f32_e32 v102, v102
	v_exp_f32_e32 v103, v103
	s_waitcnt lgkmcnt(6)
	v_mfma_f32_32x32x16_bf16 v[16:31], v[148:151], v[120:123], v[16:31]
	v_exp_f32_e32 v104, v104
	v_exp_f32_e32 v105, v105
	s_waitcnt lgkmcnt(4)
	v_mfma_f32_32x32x16_bf16 v[0:15], v[148:151], v[124:127], v[0:15]
	v_exp_f32_e32 v106, v106
	v_exp_f32_e32 v107, v107
	s_waitcnt lgkmcnt(2)
	v_mfma_f32_32x32x16_bf16 v[16:31], v[144:147], v[64:67], v[16:31]
	v_exp_f32_e32 v108, v108
	v_exp_f32_e32 v109, v109
	s_waitcnt lgkmcnt(0)
	v_mfma_f32_32x32x16_bf16 v[0:15], v[144:147], v[68:71], v[0:15]
	v_exp_f32_e32 v110, v110
	v_exp_f32_e32 v111, v111
	v_add_f32_e32 v64, v80, v81
	v_add_f32_e32 v64, v82, v64
	v_add_f32_e32 v64, v83, v64
	v_add_f32_e32 v64, v84, v64
	v_add_f32_e32 v64, v85, v64
	v_add_f32_e32 v64, v86, v64
	v_add_f32_e32 v64, v87, v64
	v_add_f32_e32 v64, v88, v64
	v_add_f32_e32 v64, v89, v64
	v_add_f32_e32 v64, v90, v64
	v_add_f32_e32 v64, v91, v64
	v_add_f32_e32 v64, v92, v64
	v_add_f32_e32 v64, v93, v64
	v_add_f32_e32 v64, v94, v64
	v_add_f32_e32 v64, v95, v64
	v_add_f32_e32 v64, v64, v96
	v_add_f32_e32 v64, v97, v64
	v_add_f32_e32 v64, v98, v64
	v_add_f32_e32 v64, v99, v64
	v_add_f32_e32 v64, v100, v64
	v_add_f32_e32 v64, v101, v64
	v_add_f32_e32 v64, v102, v64
	v_add_f32_e32 v64, v103, v64
	v_add_f32_e32 v64, v104, v64
	v_add_f32_e32 v64, v105, v64
	v_add_f32_e32 v64, v106, v64
	v_add_f32_e32 v64, v107, v64
	v_add_f32_e32 v64, v108, v64
	v_add_f32_e32 v64, v109, v64
	v_add_f32_e32 v64, v110, v64
	v_add_f32_e32 v64, v111, v64
	v_add_f32_e32 v65, v174, v136
	v_add_f32_e32 v64, v65, v64
	v_cvt_pk_bf16_f32 v66, v80, v81
	v_cvt_pk_bf16_f32 v67, v82, v83
	v_cvt_pk_bf16_f32 v68, v84, v85
	v_cvt_pk_bf16_f32 v69, v86, v87
	v_cvt_pk_bf16_f32 v70, v88, v89
	v_cvt_pk_bf16_f32 v71, v90, v91
	v_cvt_pk_bf16_f32 v72, v92, v93
	v_cvt_pk_bf16_f32 v73, v94, v95
	v_cvt_pk_bf16_f32 v74, v96, v97
	v_cvt_pk_bf16_f32 v75, v98, v99
	v_cvt_pk_bf16_f32 v76, v100, v101
	v_cvt_pk_bf16_f32 v77, v102, v103
	v_cvt_pk_bf16_f32 v78, v104, v105
	v_cvt_pk_bf16_f32 v79, v106, v107
	v_cvt_pk_bf16_f32 v80, v108, v109
	v_cvt_pk_bf16_f32 v81, v110, v111
	v_add_u32_e32 v65, 0x4000, v176
	ds_read_b64_tr_b16 v[82:83],v65 offset:0
	ds_read_b64_tr_b16 v[84:85],v65 offset:512
	ds_read_b64_tr_b16 v[86:87],v65 offset:1024
	ds_read_b64_tr_b16 v[88:89],v65 offset:1536
	ds_read_b64_tr_b16 v[90:91],v65 offset:2048
	ds_read_b64_tr_b16 v[92:93],v65 offset:2560
	ds_read_b64_tr_b16 v[94:95],v65 offset:3072
	ds_read_b64_tr_b16 v[96:97],v65 offset:3584
	s_waitcnt lgkmcnt(0)
	s_nop 0
	v_mfma_f32_32x32x16_bf16 v[48:63], v[66:69], v[82:85], v[48:63]
	ds_read_b64_tr_b16 v[82:83],v65 offset:4096
	ds_read_b64_tr_b16 v[84:85],v65 offset:4608
	v_mfma_f32_32x32x16_bf16 v[48:63], v[70:73], v[86:89], v[48:63]
	ds_read_b64_tr_b16 v[86:87],v65 offset:5120
	ds_read_b64_tr_b16 v[88:89],v65 offset:5632
	v_mfma_f32_32x32x16_bf16 v[48:63], v[74:77], v[90:93], v[48:63]
	ds_read_b64_tr_b16 v[90:91],v65 offset:6144
	ds_read_b64_tr_b16 v[92:93],v65 offset:6656
	ds_read_b64_tr_b16 v[98:99],v65 offset:7168
	ds_read_b64_tr_b16 v[100:101],v65 offset:7680
	s_waitcnt lgkmcnt(0)
	v_mfma_f32_32x32x16_bf16 v[48:63], v[78:81], v[94:97], v[48:63]
	v_mfma_f32_32x32x16_bf16 v[32:47], v[66:69], v[82:85], v[32:47]
	v_add_u32_e32 v65, 0x6000, v176
	ds_read_b64_tr_b16 v[82:83],v65 offset:0
	ds_read_b64_tr_b16 v[84:85],v65 offset:512
	v_mfma_f32_32x32x16_bf16 v[32:47], v[70:73], v[86:89], v[32:47]
	ds_read_b64_tr_b16 v[86:87],v65 offset:1024
	ds_read_b64_tr_b16 v[88:89],v65 offset:1536
	v_mfma_f32_32x32x16_bf16 v[32:47], v[74:77], v[90:93], v[32:47]
	ds_read_b64_tr_b16 v[90:91],v65 offset:2048
	ds_read_b64_tr_b16 v[92:93],v65 offset:2560
	ds_read_b64_tr_b16 v[94:95],v65 offset:3072
	ds_read_b64_tr_b16 v[96:97],v65 offset:3584
	s_waitcnt lgkmcnt(0)
	v_mfma_f32_32x32x16_bf16 v[32:47], v[78:81], v[98:101], v[32:47]
	v_mfma_f32_32x32x16_bf16 v[16:31], v[66:69], v[82:85], v[16:31]
	ds_read_b64_tr_b16 v[82:83],v65 offset:4096
	ds_read_b64_tr_b16 v[84:85],v65 offset:4608
	v_mfma_f32_32x32x16_bf16 v[16:31], v[70:73], v[86:89], v[16:31]
	ds_read_b64_tr_b16 v[86:87],v65 offset:5120
	ds_read_b64_tr_b16 v[88:89],v65 offset:5632
	v_mfma_f32_32x32x16_bf16 v[16:31], v[74:77], v[90:93], v[16:31]
	ds_read_b64_tr_b16 v[90:91],v65 offset:6144
	ds_read_b64_tr_b16 v[92:93],v65 offset:6656
	ds_read_b64_tr_b16 v[98:99],v65 offset:7168
	ds_read_b64_tr_b16 v[100:101],v65 offset:7680
	s_waitcnt lgkmcnt(0)
	v_mfma_f32_32x32x16_bf16 v[16:31], v[78:81], v[94:97], v[16:31]
	v_mfma_f32_32x32x16_bf16 v[0:15], v[66:69], v[82:85], v[0:15]
	v_mov_b32_e32 v65, v64
	s_nop 1
	v_permlane32_swap_b32_e32 v64, v65
	v_cmp_gt_u32_e32 vcc, 32, v187
	v_mfma_f32_32x32x16_bf16 v[0:15], v[70:73], v[86:89], v[0:15]
	v_mfma_f32_32x32x16_bf16 v[0:15], v[74:77], v[90:93], v[0:15]
	v_mfma_f32_32x32x16_bf16 v[0:15], v[78:81], v[98:101], v[0:15]
	s_and_saveexec_b64 s[16:17], vcc
	s_cbranch_execz .LBB0_859
	v_add_f32_e32 v64, v64, v65
	v_lshl_add_u32 v65, v186, 2, s34
	ds_write_b32 v65, v64 offset:128
	s_branch .LBB0_859

; #define WAIT_BAR(N) asm volatile("s_waitcnt vmcnt(" #N ") lgkmcnt(0)\n\ts_barrier":::"memory")
;   #define RESC() do{ if(!NOMAX&&resc){ asm volatile("s_waitcnt lgkmcnt(0)":::"memory"); \
;       _Pragma("unroll") for(int d_=0;d_<2*VM;++d_) _Pragma("unroll") for(int r=0;r<16;++r)o[d_][r]*=wsf[crow(r,hi)]; } }while(0)
;   #define ROT() do{sl_prev=sl_cur;sl_cur=sl_next;sl_next=(sl_next==(NSLOT-1)*SLOTB)?0:sl_next+SLOTB;}while(0)
; template<int THRL,int VM,bool NOMAX> __device__ __forceinline__ void attn_unit(const bf16*Qb,const bf16*__restrict__ Kh,const bf16*__restrict__ Vh,bf16*Ob,const int NT,const int sp,float*wscr,char*shm){
;     ...
;   int t=1;
;   for(;t+5<NT;t+=2){
;     STEP(pB0,pB1,pA0,pA1,t,true,true,true);     if constexpr(VM==2){WAIT_BAR(3);}else{WAIT_BAR(2);} RESC(); ROT();
;     STEP(pA0,pA1,pB0,pB1,t+1,true,true,true);   if constexpr(VM==2){WAIT_BAR(3);}else{WAIT_BAR(2);} RESC(); ROT();
;   }
.LBB0_874:
	v_mfma_f32_32x32x16_bf16 v[112:127], v[100:103], v[218:221], 0
	v_lshl_add_u32 v206, s89, 1, v188
	ds_read_b64_tr_b16 v[194:195], v206 offset:24576
	ds_read_b64_tr_b16 v[196:197], v206 offset:25088
	v_add_f32_e32 v108, v80, v81
	v_add_f32_e32 v108, v82, v108
	v_add_f32_e32 v108, v83, v108
	v_add_f32_e32 v108, v84, v108
	v_add_f32_e32 v108, v85, v108
	v_cvt_pk_bf16_f32 v156, v80, v81
	v_cvt_pk_bf16_f32 v157, v82, v83
	ds_read_b64_tr_b16 v[80:81], v206 offset:28672
	ds_read_b64_tr_b16 v[82:83], v206 offset:29184
	v_add_f32_e32 v104, v86, v108
	v_add_f32_e32 v104, v87, v104
	v_add_f32_e32 v104, v88, v104
	v_add_f32_e32 v144, v89, v104
	v_mfma_f32_32x32x16_bf16 v[96:111], v[96:99], v[218:221], 0
	v_cvt_pk_bf16_f32 v158, v84, v85
	v_cvt_pk_bf16_f32 v159, v86, v87
	ds_read_b64_tr_b16 v[84:85], v206 offset:25600
	ds_read_b64_tr_b16 v[86:87], v206 offset:26112
	v_add_f32_e32 v144, v90, v144
	v_add_f32_e32 v144, v91, v144
	v_add_f32_e32 v144, v92, v144
	v_add_f32_e32 v144, v93, v144
	v_cvt_pk_bf16_f32 v152, v88, v89
	v_cvt_pk_bf16_f32 v153, v90, v91
	v_mfma_f32_32x32x16_bf16 v[112:127], v[164:167], v[222:225], v[112:127]
	ds_read_b64_tr_b16 v[88:89], v206 offset:29696
	ds_read_b64_tr_b16 v[90:91], v206 offset:30208
	v_add_f32_e32 v144, v94, v144
	v_add_f32_e32 v144, v95, v144
	v_add_f32_e32 v144, v64, v144
	v_add_f32_e32 v144, v65, v144
	v_mfma_f32_32x32x16_bf16 v[96:111], v[160:163], v[222:225], v[96:111]
	v_cvt_pk_bf16_f32 v154, v92, v93
	v_cvt_pk_bf16_f32 v155, v94, v95
	ds_read_b64_tr_b16 v[92:93], v206 offset:26624
	ds_read_b64_tr_b16 v[94:95], v206 offset:27136
	v_add_f32_e32 v144, v66, v144
	v_add_f32_e32 v144, v67, v144
	v_add_f32_e32 v144, v68, v144
	v_add_f32_e32 v144, v69, v144
	v_cvt_pk_bf16_f32 v148, v64, v65
	v_cvt_pk_bf16_f32 v149, v66, v67
	v_mfma_f32_32x32x16_bf16 v[112:127], v[140:143], v[226:229], v[112:127]
	ds_read_b64_tr_b16 v[198:199], v206 offset:30720
	ds_read_b64_tr_b16 v[200:201], v206 offset:31232
	v_add_f32_e32 v140, v70, v144
	v_add_f32_e32 v140, v71, v140
	v_add_f32_e32 v140, v72, v140
	v_add_f32_e32 v140, v73, v140
	v_mfma_f32_32x32x16_bf16 v[96:111], v[136:139], v[226:229], v[96:111]
	v_cvt_pk_bf16_f32 v150, v68, v69
	v_cvt_pk_bf16_f32 v151, v70, v71
	ds_read_b64_tr_b16 v[202:203], v206 offset:27648
	ds_read_b64_tr_b16 v[204:205], v206 offset:28160
	v_add_f32_e32 v68, v74, v140
	v_add_f32_e32 v68, v75, v68
	v_add_f32_e32 v68, v76, v68
	v_add_f32_e32 v68, v77, v68
	v_cvt_pk_bf16_f32 v144, v72, v73
	v_cvt_pk_bf16_f32 v145, v74, v75
	v_mfma_f32_32x32x16_bf16 v[112:127], v[132:135], v[230:233], v[112:127]
	ds_read_b64_tr_b16 v[72:73], v206 offset:31744
	ds_read_b64_tr_b16 v[74:75], v206 offset:32256
	v_add_f32_e32 v68, v78, v68
	v_add_f32_e32 v68, v79, v68
	v_add_f32_e32 v68, 0, v68
	v_cvt_pk_bf16_f32 v146, v76, v77
	v_mfma_f32_32x32x16_bf16 v[96:111], v[128:131], v[230:233], v[96:111]
	v_cvt_pk_bf16_f32 v147, v78, v79
	s_add_i32 s88, s87, s17
	v_lshl_add_u64 v[64:65], v[180:181], 0, s[56:57]
	s_mov_b32 s89, m0
	s_mov_b32 m0, s88
	s_nop 0
	global_load_lds_dwordx4 v[64:65], off
	s_mov_b32 m0, s89
	s_lshl_b32 s88, s86, 1
	v_lshl_add_u64 v[64:65], v[178:179], 0, s[56:57]
	s_add_i32 s88, s88, s16
	s_mov_b32 s89, m0
	s_mov_b32 m0, s88
	s_nop 0
	global_load_lds_dwordx4 v[64:65], off
	s_mov_b32 m0, s89
	v_lshl_add_u64 v[64:65], v[176:177], 0, s[56:57]
	s_addk_i32 s88, 0x2000
	s_mov_b32 s89, m0
	s_mov_b32 m0, s88
	s_nop 0
	global_load_lds_dwordx4 v[64:65], off
	s_mov_b32 m0, s89
	v_add_f32_e32 v193, v193, v68
	s_waitcnt lgkmcnt(12)
	v_mfma_f32_32x32x16_bf16 v[48:63], v[156:159], v[194:197], v[48:63]
	ds_read_b64_tr_b16 v[76:77], v206 offset:32768
	ds_read_b64_tr_b16 v[78:79], v206 offset:33280
	v_exp_f32_e32 v112, v112
	v_exp_f32_e32 v113, v113
	v_mfma_f32_32x32x16_bf16 v[32:47], v[156:159], v[80:83], v[32:47]
	ds_read_b64_tr_b16 v[194:195], v206 offset:36864
	ds_read_b64_tr_b16 v[196:197], v206 offset:37376
	v_exp_f32_e32 v114, v114
	v_exp_f32_e32 v115, v115
	v_add_u32_e32 v242, s86, v234
	v_add_u32_e32 v243, s86, v235
	v_add_u32_e32 v244, s86, v236
	v_add_u32_e32 v245, s86, v237
	ds_read_b128 v[68:71], v242
	ds_read_b128 v[64:67], v242 offset:4096
	s_waitcnt lgkmcnt(14)
	v_mfma_f32_32x32x16_bf16 v[48:63], v[152:155], v[84:87], v[48:63]
	ds_read_b64_tr_b16 v[80:81], v206 offset:33792
	ds_read_b64_tr_b16 v[82:83], v206 offset:34304
	v_exp_f32_e32 v116, v116
	v_exp_f32_e32 v117, v117
	ds_read_b128 v[164:167], v243
	ds_read_b128 v[140:143], v243 offset:4096
	v_mfma_f32_32x32x16_bf16 v[32:47], v[152:155], v[88:91], v[32:47]
	ds_read_b64_tr_b16 v[84:85], v206 offset:37888
	ds_read_b64_tr_b16 v[86:87], v206 offset:38400
	v_exp_f32_e32 v118, v118
	v_exp_f32_e32 v119, v119
	ds_read_b128 v[160:163], v244
	ds_read_b128 v[132:135], v244 offset:4096
	s_waitcnt lgkmcnt(14)
	v_mfma_f32_32x32x16_bf16 v[48:63], v[148:151], v[92:95], v[48:63]
	ds_read_b64_tr_b16 v[88:89], v206 offset:34816
	ds_read_b64_tr_b16 v[90:91], v206 offset:35328
	v_exp_f32_e32 v120, v120
	v_exp_f32_e32 v121, v121
	ds_read_b128 v[136:139], v245
	ds_read_b128 v[128:131], v245 offset:4096
	v_mfma_f32_32x32x16_bf16 v[32:47], v[148:151], v[198:201], v[32:47]
	ds_read_b64_tr_b16 v[92:93], v206 offset:38912
	ds_read_b64_tr_b16 v[94:95], v206 offset:39424
	v_exp_f32_e32 v122, v122
	v_exp_f32_e32 v123, v123
	s_waitcnt lgkmcnt(14)
	v_mfma_f32_32x32x16_bf16 v[48:63], v[144:147], v[202:205], v[48:63]
	ds_read_b64_tr_b16 v[198:199], v206 offset:35840
	ds_read_b64_tr_b16 v[200:201], v206 offset:36352
	v_exp_f32_e32 v124, v124
	v_exp_f32_e32 v125, v125
	v_mfma_f32_32x32x16_bf16 v[32:47], v[144:147], v[72:75], v[32:47]
	ds_read_b64_tr_b16 v[202:203], v206 offset:39936
	ds_read_b64_tr_b16 v[204:205], v206 offset:40448
	v_exp_f32_e32 v126, v126
	v_exp_f32_e32 v127, v127
	s_waitcnt lgkmcnt(14)
	v_mfma_f32_32x32x16_bf16 v[16:31], v[156:159], v[76:79], v[16:31]
	v_exp_f32_e32 v96, v96
	v_exp_f32_e32 v97, v97
	v_mfma_f32_32x32x16_bf16 v[0:15], v[156:159], v[194:197], v[0:15]
	v_exp_f32_e32 v98, v98
	v_exp_f32_e32 v99, v99
	v_mfma_f32_32x32x16_bf16 v[16:31], v[152:155], v[80:83], v[16:31]
	v_exp_f32_e32 v100, v100
	v_exp_f32_e32 v101, v101
	s_waitcnt lgkmcnt(12)
	v_mfma_f32_32x32x16_bf16 v[0:15], v[152:155], v[84:87], v[0:15]
	v_exp_f32_e32 v102, v102
	v_exp_f32_e32 v103, v103
	s_waitcnt lgkmcnt(8)
	v_mfma_f32_32x32x16_bf16 v[16:31], v[148:151], v[88:91], v[16:31]
	v_exp_f32_e32 v104, v104
	v_exp_f32_e32 v105, v105
	s_waitcnt lgkmcnt(4)
	v_mfma_f32_32x32x16_bf16 v[0:15], v[148:151], v[92:95], v[0:15]
	v_exp_f32_e32 v106, v106
	v_exp_f32_e32 v107, v107
	s_waitcnt lgkmcnt(2)
	v_mfma_f32_32x32x16_bf16 v[16:31], v[144:147], v[198:201], v[16:31]
	v_exp_f32_e32 v108, v108
	v_exp_f32_e32 v109, v109
	s_waitcnt lgkmcnt(0)
	v_mfma_f32_32x32x16_bf16 v[0:15], v[144:147], v[202:205], v[0:15]
	v_exp_f32_e32 v110, v110
	v_exp_f32_e32 v111, v111
	s_waitcnt vmcnt(3) lgkmcnt(0)
	s_barrier
; #define WAIT_BAR(N) asm volatile("s_waitcnt vmcnt(" #N ") lgkmcnt(0)\n\ts_barrier":::"memory")
;   #define RESC() do{ if(!NOMAX&&resc){ asm volatile("s_waitcnt lgkmcnt(0)":::"memory"); \
;       _Pragma("unroll") for(int d_=0;d_<2*VM;++d_) _Pragma("unroll") for(int r=0;r<16;++r)o[d_][r]*=wsf[crow(r,hi)]; } }while(0)
;   #define ROT() do{sl_prev=sl_cur;sl_cur=sl_next;sl_next=(sl_next==(NSLOT-1)*SLOTB)?0:sl_next+SLOTB;}while(0)
; template<int THRL,int VM,bool NOMAX> __device__ __forceinline__ void attn_unit(const bf16*Qb,const bf16*__restrict__ Kh,const bf16*__restrict__ Vh,bf16*Ob,const int NT,const int sp,float*wscr,char*shm){
;     ...
;   int t=1;
;   for(;t+5<NT;t+=2){
;     STEP(pB0,pB1,pA0,pA1,t,true,true,true);     if constexpr(VM==2){WAIT_BAR(3);}else{WAIT_BAR(2);} RESC(); ROT();
;     STEP(pA0,pA1,pB0,pB1,t+1,true,true,true);   if constexpr(VM==2){WAIT_BAR(3);}else{WAIT_BAR(2);} RESC(); ROT();
;   }
	v_mfma_f32_32x32x16_bf16 v[80:95], v[68:71], v[218:221], 0
	s_add_i32 s88, s86, 0x2000
	s_cmpk_lg_i32 s86, 0x4000
	s_cselect_b32 s88, s88, 0
	v_lshl_add_u32 v206, s87, 1, v188
	ds_read_b64_tr_b16 v[194:195], v206 offset:24576
	ds_read_b64_tr_b16 v[196:197], v206 offset:25088
	v_add_f32_e32 v76, v112, v113
	v_add_f32_e32 v76, v114, v76
	v_add_f32_e32 v76, v115, v76
	v_add_f32_e32 v76, v116, v76
	v_add_f32_e32 v76, v117, v76
	v_cvt_pk_bf16_f32 v156, v112, v113
	v_cvt_pk_bf16_f32 v157, v114, v115
	ds_read_b64_tr_b16 v[112:113], v206 offset:28672
	ds_read_b64_tr_b16 v[114:115], v206 offset:29184
	v_add_f32_e32 v72, v118, v76
	v_add_f32_e32 v72, v119, v72
	v_add_f32_e32 v72, v120, v72
	v_add_f32_e32 v144, v121, v72
	v_mfma_f32_32x32x16_bf16 v[64:79], v[64:67], v[218:221], 0
	v_cvt_pk_bf16_f32 v158, v116, v117
	v_cvt_pk_bf16_f32 v159, v118, v119
	ds_read_b64_tr_b16 v[116:117], v206 offset:25600
	ds_read_b64_tr_b16 v[118:119], v206 offset:26112
	v_add_f32_e32 v144, v122, v144
	v_add_f32_e32 v144, v123, v144
	v_add_f32_e32 v144, v124, v144
	v_add_f32_e32 v144, v125, v144
	v_mfma_f32_32x32x16_bf16 v[80:95], v[164:167], v[222:225], v[80:95]
	v_cvt_pk_bf16_f32 v152, v120, v121
	v_cvt_pk_bf16_f32 v153, v122, v123
	ds_read_b64_tr_b16 v[120:121], v206 offset:29696
	ds_read_b64_tr_b16 v[122:123], v206 offset:30208
	v_add_f32_e32 v144, v126, v144
	v_add_f32_e32 v144, v127, v144
	v_add_f32_e32 v144, v96, v144
	v_add_f32_e32 v144, v97, v144
	v_mfma_f32_32x32x16_bf16 v[64:79], v[140:143], v[222:225], v[64:79]
	v_cvt_pk_bf16_f32 v154, v124, v125
	v_cvt_pk_bf16_f32 v155, v126, v127
	ds_read_b64_tr_b16 v[124:125], v206 offset:26624
	ds_read_b64_tr_b16 v[126:127], v206 offset:27136
	v_add_f32_e32 v144, v98, v144
	v_add_f32_e32 v144, v99, v144
	v_add_f32_e32 v144, v100, v144
	v_add_f32_e32 v144, v101, v144
	v_mfma_f32_32x32x16_bf16 v[80:95], v[160:163], v[226:229], v[80:95]
	v_cvt_pk_bf16_f32 v148, v96, v97
	v_cvt_pk_bf16_f32 v149, v98, v99
	ds_read_b64_tr_b16 v[198:199], v206 offset:30720
	ds_read_b64_tr_b16 v[200:201], v206 offset:31232
	v_add_f32_e32 v140, v102, v144
	v_add_f32_e32 v140, v103, v140
	v_add_f32_e32 v140, v104, v140
	v_add_f32_e32 v140, v105, v140
	v_mfma_f32_32x32x16_bf16 v[64:79], v[132:135], v[226:229], v[64:79]
	v_cvt_pk_bf16_f32 v150, v100, v101
	v_cvt_pk_bf16_f32 v151, v102, v103
	ds_read_b64_tr_b16 v[202:203], v206 offset:27648
	ds_read_b64_tr_b16 v[204:205], v206 offset:28160
	v_add_f32_e32 v100, v106, v140
	v_add_f32_e32 v100, v107, v100
	v_add_f32_e32 v100, v108, v100
	v_add_f32_e32 v100, v109, v100
	v_mfma_f32_32x32x16_bf16 v[80:95], v[136:139], v[230:233], v[80:95]
	v_cvt_pk_bf16_f32 v144, v104, v105
	v_cvt_pk_bf16_f32 v145, v106, v107
	ds_read_b64_tr_b16 v[104:105], v206 offset:31744
	ds_read_b64_tr_b16 v[106:107], v206 offset:32256
	v_add_f32_e32 v100, v110, v100
	v_add_f32_e32 v100, v111, v100
	v_add_f32_e32 v100, 0, v100
	v_cvt_pk_bf16_f32 v146, v108, v109
	v_mfma_f32_32x32x16_bf16 v[64:79], v[128:131], v[230:233], v[64:79]
	v_cvt_pk_bf16_f32 v147, v110, v111
	s_add_i32 s87, s86, s17
	s_mov_b32 s89, m0
	s_mov_b32 m0, s87
	s_nop 0
	global_load_lds_dwordx4 v[180:181], off
	s_mov_b32 m0, s89
	s_lshl_b32 s87, s88, 1
	s_add_i32 s87, s87, s16
	s_mov_b32 s89, m0
	s_mov_b32 m0, s87
	s_nop 0
	global_load_lds_dwordx4 v[178:179], off
	s_mov_b32 m0, s89
	s_addk_i32 s87, 0x2000
	s_mov_b32 s89, m0
	s_mov_b32 m0, s87
	s_nop 0
	global_load_lds_dwordx4 v[176:177], off
	s_mov_b32 m0, s89
	v_add_f32_e32 v193, v193, v100
	s_waitcnt lgkmcnt(12)
	v_mfma_f32_32x32x16_bf16 v[48:63], v[156:159], v[194:197], v[48:63]
	ds_read_b64_tr_b16 v[108:109], v206 offset:32768
	ds_read_b64_tr_b16 v[110:111], v206 offset:33280
	v_exp_f32_e32 v80, v80
	v_exp_f32_e32 v81, v81
	v_mfma_f32_32x32x16_bf16 v[32:47], v[156:159], v[112:115], v[32:47]
	ds_read_b64_tr_b16 v[194:195], v206 offset:36864
	ds_read_b64_tr_b16 v[196:197], v206 offset:37376
	v_exp_f32_e32 v82, v82
	v_exp_f32_e32 v83, v83
	v_add_u32_e32 v242, s88, v234
	v_add_u32_e32 v243, s88, v235
	v_add_u32_e32 v244, s88, v236
	v_add_u32_e32 v245, s88, v237
	ds_read_b128 v[100:103], v242
	ds_read_b128 v[96:99], v242 offset:4096
	s_waitcnt lgkmcnt(14)
	v_mfma_f32_32x32x16_bf16 v[48:63], v[152:155], v[116:119], v[48:63]
	ds_read_b64_tr_b16 v[112:113], v206 offset:33792
	ds_read_b64_tr_b16 v[114:115], v206 offset:34304
	v_exp_f32_e32 v84, v84
	v_exp_f32_e32 v85, v85
	ds_read_b128 v[164:167], v243
	ds_read_b128 v[160:163], v243 offset:4096
	v_mfma_f32_32x32x16_bf16 v[32:47], v[152:155], v[120:123], v[32:47]
	ds_read_b64_tr_b16 v[116:117], v206 offset:37888
	ds_read_b64_tr_b16 v[118:119], v206 offset:38400
	v_exp_f32_e32 v86, v86
	v_exp_f32_e32 v87, v87
	ds_read_b128 v[140:143], v244
	ds_read_b128 v[136:139], v244 offset:4096
	s_waitcnt lgkmcnt(14)
	v_mfma_f32_32x32x16_bf16 v[48:63], v[148:151], v[124:127], v[48:63]
	ds_read_b64_tr_b16 v[120:121], v206 offset:34816
	ds_read_b64_tr_b16 v[122:123], v206 offset:35328
	v_exp_f32_e32 v88, v88
	v_exp_f32_e32 v89, v89
	ds_read_b128 v[132:135], v245
	ds_read_b128 v[128:131], v245 offset:4096
	v_mfma_f32_32x32x16_bf16 v[32:47], v[148:151], v[198:201], v[32:47]
	ds_read_b64_tr_b16 v[124:125], v206 offset:38912
	ds_read_b64_tr_b16 v[126:127], v206 offset:39424
	v_exp_f32_e32 v90, v90
	v_exp_f32_e32 v91, v91
	s_waitcnt lgkmcnt(14)
	v_mfma_f32_32x32x16_bf16 v[48:63], v[144:147], v[202:205], v[48:63]
	ds_read_b64_tr_b16 v[198:199], v206 offset:35840
	ds_read_b64_tr_b16 v[200:201], v206 offset:36352
	v_exp_f32_e32 v92, v92
	v_exp_f32_e32 v93, v93
	v_mfma_f32_32x32x16_bf16 v[32:47], v[144:147], v[104:107], v[32:47]
	ds_read_b64_tr_b16 v[202:203], v206 offset:39936
	ds_read_b64_tr_b16 v[204:205], v206 offset:40448
	v_exp_f32_e32 v94, v94
	v_exp_f32_e32 v95, v95
	s_waitcnt lgkmcnt(14)
; #define WAIT_BAR(N) asm volatile("s_waitcnt vmcnt(" #N ") lgkmcnt(0)\n\ts_barrier":::"memory")
;   #define RESC() do{ if(!NOMAX&&resc){ asm volatile("s_waitcnt lgkmcnt(0)":::"memory"); \
;       _Pragma("unroll") for(int d_=0;d_<2*VM;++d_) _Pragma("unroll") for(int r=0;r<16;++r)o[d_][r]*=wsf[crow(r,hi)]; } }while(0)
;   #define ROT() do{sl_prev=sl_cur;sl_cur=sl_next;sl_next=(sl_next==(NSLOT-1)*SLOTB)?0:sl_next+SLOTB;}while(0)
;   #define ENDW(tt) do{ if((tt)+3<NT){ if constexpr(VM==2){WAIT_BAR(3);}else{WAIT_BAR(2);} } else if((tt)+2<NT){ if constexpr(VM==2){WAIT_BAR(2);}else{WAIT_BAR(1);} } else {WAIT_BAR(0);} }while(0)
; template<int THRL,int VM,bool NOMAX> __device__ __forceinline__ void attn_unit(const bf16*Qb,const bf16*__restrict__ Kh,const bf16*__restrict__ Vh,bf16*Ob,const int NT,const int sp,float*wscr,char*shm){
;     ...
;   for(;t+5<NT;t+=2){
;     STEP(pB0,pB1,pA0,pA1,t,true,true,true);     if constexpr(VM==2){WAIT_BAR(3);}else{WAIT_BAR(2);} RESC(); ROT();
;     STEP(pA0,pA1,pB0,pB1,t+1,true,true,true);   if constexpr(VM==2){WAIT_BAR(3);}else{WAIT_BAR(2);} RESC(); ROT();
;   }
;     ...
;   for(;t+1<NT;t+=2){
;     STEP(pB0,pB1,pA0,pA1,t,(t+3<NT),(t+1<NT),(t+1<NT));       ENDW(t);   RESC(); ROT();
;     STEP(pA0,pA1,pB0,pB1,t+1,(t+4<NT),(t+2<NT),(t+2<NT));     ENDW(t+1); RESC(); ROT();
;   }
	v_mfma_f32_32x32x16_bf16 v[16:31], v[156:159], v[108:111], v[16:31]
	v_exp_f32_e32 v64, v64
	v_exp_f32_e32 v65, v65
	v_mfma_f32_32x32x16_bf16 v[0:15], v[156:159], v[194:197], v[0:15]
	v_exp_f32_e32 v66, v66
	v_exp_f32_e32 v67, v67
	v_mfma_f32_32x32x16_bf16 v[16:31], v[152:155], v[112:115], v[16:31]
	v_exp_f32_e32 v68, v68
	v_exp_f32_e32 v69, v69
	s_waitcnt lgkmcnt(12)
	v_mfma_f32_32x32x16_bf16 v[0:15], v[152:155], v[116:119], v[0:15]
	v_exp_f32_e32 v70, v70
	v_exp_f32_e32 v71, v71
	s_waitcnt lgkmcnt(8)
	v_mfma_f32_32x32x16_bf16 v[16:31], v[148:151], v[120:123], v[16:31]
	v_exp_f32_e32 v72, v72
	v_exp_f32_e32 v73, v73
	s_waitcnt lgkmcnt(4)
	v_mfma_f32_32x32x16_bf16 v[0:15], v[148:151], v[124:127], v[0:15]
	v_exp_f32_e32 v74, v74
	v_exp_f32_e32 v75, v75
	s_waitcnt lgkmcnt(2)
	v_mfma_f32_32x32x16_bf16 v[16:31], v[144:147], v[198:201], v[16:31]
	v_exp_f32_e32 v76, v76
	v_exp_f32_e32 v77, v77
	s_waitcnt lgkmcnt(0)
	v_mfma_f32_32x32x16_bf16 v[0:15], v[144:147], v[202:205], v[0:15]
	v_exp_f32_e32 v78, v78
	v_exp_f32_e32 v79, v79
	s_add_i32 s90, s88, 0x2000
	s_cmpk_lg_i32 s88, 0x4000
	s_mov_b32 s89, s86
	s_cselect_b32 s86, s90, 0
	s_add_i32 s85, s85, 2
	v_lshl_add_u64 v[176:177], v[176:177], 0, s[58:59]
	v_lshl_add_u64 v[178:179], v[178:179], 0, s[58:59]
	v_lshl_add_u64 v[180:181], v[180:181], 0, s[58:59]
	s_mov_b32 s87, s88
	s_cmp_lt_u32 s85, 57
	s_waitcnt vmcnt(3) lgkmcnt(0)
	s_barrier
	s_cbranch_scc1 .LBB0_874
	s_and_b32 s34, s34, 0x3fffffc0
	s_lshl_b32 s34, s34, 2
	s_add_i32 s34, s34, 0
	s_add_i32 s34, s34, 0x12000
	s_cmp_lg_u32 0, -1
	s_cselect_b32 s85, 0, 0
	s_add_i32 s86, s85, 0x6000
	v_add_u32_e32 v104, s86, v191
	v_add3_u32 v176, v104, v190, v192
	v_add_u32_e32 v177, 0x6000, v188
	ds_read_b64_tr_b16 v[178:179], v188 offset:40960
	ds_read_b64_tr_b16 v[180:181], v188 offset:41472
	v_add_f32_e32 v108, v80, v81
	ds_read_b128 v[104:107], v168
	v_add_f32_e32 v108, v82, v108
	v_add_f32_e32 v108, v83, v108
	v_add_f32_e32 v108, v84, v108
	v_add_f32_e32 v108, v85, v108
	v_cvt_pk_bf16_f32 v156, v80, v81
	v_cvt_pk_bf16_f32 v157, v82, v83
	s_waitcnt lgkmcnt(0)
	v_mfma_f32_32x32x16_bf16 v[112:127], v[100:103], v[104:107], 0
	ds_read_b64_tr_b16 v[80:81], v188 offset:45056
	ds_read_b64_tr_b16 v[82:83], v188 offset:45568
	ds_read_b128 v[100:103], v168
	v_add_f32_e32 v104, v86, v108
	v_add_f32_e32 v104, v87, v104
	v_add_f32_e32 v104, v88, v104
	v_add_f32_e32 v144, v89, v104
	v_cvt_pk_bf16_f32 v158, v84, v85
	v_cvt_pk_bf16_f32 v159, v86, v87
	s_waitcnt lgkmcnt(0)
	v_mfma_f32_32x32x16_bf16 v[96:111], v[96:99], v[100:103], 0
	ds_read_b64_tr_b16 v[84:85], v188 offset:41984
	ds_read_b64_tr_b16 v[86:87], v188 offset:42496
	ds_read_b128 v[194:197], v168 offset:1024
	v_add_f32_e32 v144, v90, v144
	v_add_f32_e32 v144, v91, v144
	v_add_f32_e32 v144, v92, v144
	v_add_f32_e32 v144, v93, v144
	v_cvt_pk_bf16_f32 v152, v88, v89
	v_cvt_pk_bf16_f32 v153, v90, v91
	s_waitcnt lgkmcnt(0)
	v_mfma_f32_32x32x16_bf16 v[112:127], v[164:167], v[194:197], v[112:127]
	ds_read_b64_tr_b16 v[88:89], v188 offset:46080
	ds_read_b64_tr_b16 v[90:91], v188 offset:46592
	ds_read_b128 v[164:167], v168 offset:1024
	v_add_f32_e32 v144, v94, v144
	v_add_f32_e32 v144, v95, v144
	v_add_f32_e32 v144, v64, v144
	v_add_f32_e32 v144, v65, v144
	v_cvt_pk_bf16_f32 v154, v92, v93
	v_cvt_pk_bf16_f32 v155, v94, v95
	s_waitcnt lgkmcnt(0)
	v_mfma_f32_32x32x16_bf16 v[96:111], v[160:163], v[164:167], v[96:111]
	ds_read_b64_tr_b16 v[194:195], v188 offset:43008
	ds_read_b64_tr_b16 v[196:197], v188 offset:43520
	ds_read_b128 v[92:95], v168 offset:2048
	v_add_f32_e32 v144, v66, v144
	v_add_f32_e32 v144, v67, v144
	v_add_f32_e32 v144, v68, v144
	v_add_f32_e32 v144, v69, v144
	v_cvt_pk_bf16_f32 v148, v64, v65
	v_cvt_pk_bf16_f32 v149, v66, v67
	s_waitcnt lgkmcnt(0)
	v_mfma_f32_32x32x16_bf16 v[112:127], v[140:143], v[92:95], v[112:127]
	ds_read_b64_tr_b16 v[140:141], v188 offset:47104
	ds_read_b64_tr_b16 v[142:143], v188 offset:47616
	ds_read_b128 v[64:67], v168 offset:2048
	v_add_f32_e32 v92, v70, v144
	v_add_f32_e32 v92, v71, v92
	v_add_f32_e32 v92, v72, v92
	v_add_f32_e32 v92, v73, v92
	v_cvt_pk_bf16_f32 v150, v68, v69
	v_cvt_pk_bf16_f32 v151, v70, v71
	s_waitcnt lgkmcnt(0)
	v_mfma_f32_32x32x16_bf16 v[96:111], v[136:139], v[64:67], v[96:111]
	ds_read_b64_tr_b16 v[136:137], v188 offset:44032
	ds_read_b64_tr_b16 v[138:139], v188 offset:44544
	ds_read_b128 v[64:67], v168 offset:3072
	v_add_f32_e32 v68, v74, v92
	v_add_f32_e32 v68, v75, v68
	v_add_f32_e32 v68, v76, v68
	v_add_f32_e32 v68, v77, v68
	v_cvt_pk_bf16_f32 v144, v72, v73
	v_cvt_pk_bf16_f32 v145, v74, v75
	s_waitcnt lgkmcnt(0)
	v_mfma_f32_32x32x16_bf16 v[112:127], v[132:135], v[64:67], v[112:127]
	ds_read_b64_tr_b16 v[72:73], v188 offset:48128
	ds_read_b64_tr_b16 v[74:75], v188 offset:48640
	ds_read_b128 v[64:67], v168 offset:3072
	v_add_f32_e32 v68, v78, v68
	v_add_f32_e32 v68, v79, v68
	v_add_f32_e32 v68, 0, v68
	v_cvt_pk_bf16_f32 v146, v76, v77
	v_cvt_pk_bf16_f32 v147, v78, v79
	s_waitcnt lgkmcnt(0)
; #define WAIT_BAR(N) asm volatile("s_waitcnt vmcnt(" #N ") lgkmcnt(0)\n\ts_barrier":::"memory")
;   #define RESC() do{ if(!NOMAX&&resc){ asm volatile("s_waitcnt lgkmcnt(0)":::"memory"); \
;       _Pragma("unroll") for(int d_=0;d_<2*VM;++d_) _Pragma("unroll") for(int r=0;r<16;++r)o[d_][r]*=wsf[crow(r,hi)]; } }while(0)
;   #define ROT() do{sl_prev=sl_cur;sl_cur=sl_next;sl_next=(sl_next==(NSLOT-1)*SLOTB)?0:sl_next+SLOTB;}while(0)
;   #define ENDW(tt) do{ if((tt)+3<NT){ if constexpr(VM==2){WAIT_BAR(3);}else{WAIT_BAR(2);} } else if((tt)+2<NT){ if constexpr(VM==2){WAIT_BAR(2);}else{WAIT_BAR(1);} } else {WAIT_BAR(0);} }while(0)
; template<int THRL,int VM,bool NOMAX> __device__ __forceinline__ void attn_unit(const bf16*Qb,const bf16*__restrict__ Kh,const bf16*__restrict__ Vh,bf16*Ob,const int NT,const int sp,float*wscr,char*shm){
;     ...
;   int t=1;
;   for(;t+5<NT;t+=2){
;     STEP(pB0,pB1,pA0,pA1,t,true,true,true);     if constexpr(VM==2){WAIT_BAR(3);}else{WAIT_BAR(2);} RESC(); ROT();
;     STEP(pA0,pA1,pB0,pB1,t+1,true,true,true);   if constexpr(VM==2){WAIT_BAR(3);}else{WAIT_BAR(2);} RESC(); ROT();
;   }
;     ...
;   for(;t+1<NT;t+=2){
;     STEP(pB0,pB1,pA0,pA1,t,(t+3<NT),(t+1<NT),(t+1<NT));       ENDW(t);   RESC(); ROT();
;     STEP(pA0,pA1,pB0,pB1,t+1,(t+4<NT),(t+2<NT),(t+2<NT));     ENDW(t+1); RESC(); ROT();
;   }
	v_mfma_f32_32x32x16_bf16 v[96:111], v[128:131], v[64:67], v[96:111]
	s_add_i32 s85, s85, s35
	v_lshl_add_u64 v[64:65], v[174:175], 0, s[60:61]
	s_add_i32 s35, s85, 0x4000
	s_mov_b32 s86, m0
	s_mov_b32 m0, s35
	s_nop 0
	global_load_lds_dwordx4 v[64:65], off
	s_mov_b32 m0, s86
	v_lshl_add_u64 v[64:65], v[170:171], 0, s[62:63]
	s_mov_b32 s35, m0
	s_mov_b32 m0, s16
	s_nop 0
	global_load_lds_dwordx4 v[64:65], off
	s_mov_b32 m0, s35
	v_lshl_add_u64 v[64:65], v[172:173], 0, s[62:63]
	s_add_i32 s35, s16, 0x2000
	s_mov_b32 s86, m0
	s_mov_b32 m0, s35
	s_nop 0
	global_load_lds_dwordx4 v[64:65], off
	s_mov_b32 m0, s86
	v_add_f32_e32 v198, v193, v68
	v_mfma_f32_32x32x16_bf16 v[48:63], v[156:159], v[178:181], v[48:63]
	ds_read_b64_tr_b16 v[76:77], v188 offset:49152
	ds_read_b64_tr_b16 v[78:79], v188 offset:49664
	v_exp_f32_e32 v112, v112
	v_exp_f32_e32 v113, v113
	v_mfma_f32_32x32x16_bf16 v[32:47], v[156:159], v[80:83], v[32:47]
	ds_read_b64_tr_b16 v[128:129], v188 offset:53248
	ds_read_b64_tr_b16 v[130:131], v188 offset:53760
	v_exp_f32_e32 v114, v114
	v_exp_f32_e32 v115, v115
	ds_read_b128 v[68:71], v234
	ds_read_b128 v[64:67], v234 offset:4096
	v_mfma_f32_32x32x16_bf16 v[48:63], v[152:155], v[84:87], v[48:63]
	ds_read_b64_tr_b16 v[132:133], v188 offset:50176
	ds_read_b64_tr_b16 v[134:135], v188 offset:50688
	v_exp_f32_e32 v116, v116
	v_exp_f32_e32 v117, v117
	ds_read_b128 v[164:167], v235
	ds_read_b128 v[92:95], v235 offset:4096
	v_mfma_f32_32x32x16_bf16 v[32:47], v[152:155], v[88:91], v[32:47]
	ds_read_b64_tr_b16 v[178:179], v188 offset:54272
	ds_read_b64_tr_b16 v[180:181], v188 offset:54784
	v_exp_f32_e32 v118, v118
	v_exp_f32_e32 v119, v119
	ds_read_b128 v[160:163], v236
	ds_read_b128 v[84:87], v236 offset:4096
	v_mfma_f32_32x32x16_bf16 v[48:63], v[148:151], v[194:197], v[48:63]
	ds_read_b64_tr_b16 v[190:191], v188 offset:51200
	ds_read_b64_tr_b16 v[192:193], v188 offset:51712
	v_exp_f32_e32 v120, v120
	v_exp_f32_e32 v121, v121
	ds_read_b128 v[88:91], v237
	ds_read_b128 v[80:83], v237 offset:4096
	v_mfma_f32_32x32x16_bf16 v[32:47], v[148:151], v[140:143], v[32:47]
	ds_read_b64_tr_b16 v[194:195], v188 offset:55296
	ds_read_b64_tr_b16 v[196:197], v188 offset:55808
	v_exp_f32_e32 v122, v122
	v_exp_f32_e32 v123, v123
	v_mfma_f32_32x32x16_bf16 v[48:63], v[144:147], v[136:139], v[48:63]
	ds_read_b64_tr_b16 v[140:141], v188 offset:52224
	ds_read_b64_tr_b16 v[142:143], v188 offset:52736
	v_exp_f32_e32 v124, v124
	v_exp_f32_e32 v125, v125
	v_mfma_f32_32x32x16_bf16 v[32:47], v[144:147], v[72:75], v[32:47]
	ds_read_b64_tr_b16 v[136:137], v188 offset:56320
	ds_read_b64_tr_b16 v[138:139], v188 offset:56832
	v_exp_f32_e32 v126, v126
	v_exp_f32_e32 v127, v127
	s_waitcnt lgkmcnt(14)
	v_mfma_f32_32x32x16_bf16 v[16:31], v[156:159], v[76:79], v[16:31]
	v_exp_f32_e32 v96, v96
	v_exp_f32_e32 v97, v97
	v_mfma_f32_32x32x16_bf16 v[0:15], v[156:159], v[128:131], v[0:15]
	v_exp_f32_e32 v98, v98
	v_exp_f32_e32 v99, v99
	v_mfma_f32_32x32x16_bf16 v[16:31], v[152:155], v[132:135], v[16:31]
	v_exp_f32_e32 v100, v100
	v_exp_f32_e32 v101, v101
	s_waitcnt lgkmcnt(12)
	v_mfma_f32_32x32x16_bf16 v[0:15], v[152:155], v[178:181], v[0:15]
	v_exp_f32_e32 v102, v102
	v_exp_f32_e32 v103, v103
	s_waitcnt lgkmcnt(8)
	v_mfma_f32_32x32x16_bf16 v[16:31], v[148:151], v[190:193], v[16:31]
	v_exp_f32_e32 v104, v104
	v_exp_f32_e32 v105, v105
	s_waitcnt lgkmcnt(4)
	v_mfma_f32_32x32x16_bf16 v[0:15], v[148:151], v[194:197], v[0:15]
	v_exp_f32_e32 v106, v106
	v_exp_f32_e32 v107, v107
	s_waitcnt lgkmcnt(2)
	v_mfma_f32_32x32x16_bf16 v[16:31], v[144:147], v[140:143], v[16:31]
	v_exp_f32_e32 v108, v108
	v_exp_f32_e32 v109, v109
	s_waitcnt lgkmcnt(0)
	v_mfma_f32_32x32x16_bf16 v[0:15], v[144:147], v[136:139], v[0:15]
	v_exp_f32_e32 v110, v110
	v_exp_f32_e32 v111, v111
	s_waitcnt vmcnt(3) lgkmcnt(0)
	s_barrier
	ds_read_b64_tr_b16 v[178:179], v188 offset:57344
	ds_read_b64_tr_b16 v[180:181], v188 offset:57856
	v_add_f32_e32 v76, v112, v113
	ds_read_b128 v[72:75], v168
	v_add_f32_e32 v76, v114, v76
	v_add_f32_e32 v76, v115, v76
	v_add_f32_e32 v76, v116, v76
	v_add_f32_e32 v76, v117, v76
	v_cvt_pk_bf16_f32 v156, v112, v113
	v_cvt_pk_bf16_f32 v157, v114, v115
	s_waitcnt lgkmcnt(0)
	v_mfma_f32_32x32x16_bf16 v[128:143], v[68:71], v[72:75], 0
	ds_read_b64_tr_b16 v[112:113], v188 offset:61440
	ds_read_b64_tr_b16 v[114:115], v188 offset:61952
	ds_read_b128 v[68:71], v168
	v_add_f32_e32 v72, v118, v76
	v_add_f32_e32 v72, v119, v72
	v_add_f32_e32 v72, v120, v72
	v_add_f32_e32 v144, v121, v72
	s_waitcnt lgkmcnt(0)
	v_mfma_f32_32x32x16_bf16 v[64:79], v[64:67], v[68:71], 0
	v_cvt_pk_bf16_f32 v158, v116, v117
	v_cvt_pk_bf16_f32 v159, v118, v119
	ds_read_b64_tr_b16 v[116:117], v188 offset:58368
	ds_read_b64_tr_b16 v[118:119], v188 offset:58880
	ds_read_b128 v[190:193], v168 offset:1024
	v_add_f32_e32 v144, v122, v144
	v_add_f32_e32 v144, v123, v144
	v_add_f32_e32 v144, v124, v144
	v_add_f32_e32 v144, v125, v144
	v_cvt_pk_bf16_f32 v152, v120, v121
	v_cvt_pk_bf16_f32 v153, v122, v123
	s_waitcnt lgkmcnt(0)
	v_mfma_f32_32x32x16_bf16 v[128:143], v[164:167], v[190:193], v[128:143]
	ds_read_b64_tr_b16 v[120:121], v188 offset:62464
	ds_read_b64_tr_b16 v[122:123], v188 offset:62976
	ds_read_b128 v[164:167], v168 offset:1024
	v_add_f32_e32 v144, v126, v144
	v_add_f32_e32 v144, v127, v144
	v_add_f32_e32 v144, v96, v144
	v_add_f32_e32 v144, v97, v144
	s_waitcnt lgkmcnt(0)
	v_mfma_f32_32x32x16_bf16 v[64:79], v[92:95], v[164:167], v[64:79]
	v_cvt_pk_bf16_f32 v154, v124, v125
	v_cvt_pk_bf16_f32 v155, v126, v127
	ds_read_b64_tr_b16 v[92:93], v188 offset:59392
	ds_read_b64_tr_b16 v[94:95], v188 offset:59904
	ds_read_b128 v[124:127], v168 offset:2048
	v_add_f32_e32 v144, v98, v144
	v_add_f32_e32 v144, v99, v144
	v_add_f32_e32 v144, v100, v144
	v_add_f32_e32 v144, v101, v144
	v_cvt_pk_bf16_f32 v148, v96, v97
	v_cvt_pk_bf16_f32 v149, v98, v99
	s_waitcnt lgkmcnt(0)
	v_mfma_f32_32x32x16_bf16 v[128:143], v[160:163], v[124:127], v[128:143]
	ds_read_b64_tr_b16 v[96:97], v188 offset:63488
	ds_read_b64_tr_b16 v[98:99], v188 offset:64000
	ds_read_b128 v[124:127], v168 offset:2048
	v_add_f32_e32 v144, v102, v144
	v_add_f32_e32 v144, v103, v144
	v_add_f32_e32 v144, v104, v144
	v_add_f32_e32 v144, v105, v144
	s_waitcnt lgkmcnt(0)
	v_mfma_f32_32x32x16_bf16 v[64:79], v[84:87], v[124:127], v[64:79]
	v_cvt_pk_bf16_f32 v150, v100, v101
	v_cvt_pk_bf16_f32 v151, v102, v103
	ds_read_b64_tr_b16 v[100:101], v188 offset:60416
	ds_read_b64_tr_b16 v[102:103], v188 offset:60928
	ds_read_b128 v[84:87], v168 offset:3072
	v_add_f32_e32 v124, v106, v144
	v_add_f32_e32 v124, v107, v124
	v_add_f32_e32 v124, v108, v124
	v_add_f32_e32 v124, v109, v124
	v_cvt_pk_bf16_f32 v144, v104, v105
	v_cvt_pk_bf16_f32 v145, v106, v107
	s_waitcnt lgkmcnt(0)
	v_mfma_f32_32x32x16_bf16 v[128:143], v[88:91], v[84:87], v[128:143]
	ds_read_b64_tr_b16 v[88:89], v188 offset:64512
	ds_read_b64_tr_b16 v[90:91], v188 offset:65024
	ds_read_b128 v[84:87], v168 offset:3072
	v_add_f32_e32 v104, v110, v124
	v_add_f32_e32 v104, v111, v104
	v_add_f32_e32 v104, 0, v104
	v_cvt_pk_bf16_f32 v146, v108, v109
	s_waitcnt lgkmcnt(0)
	v_mfma_f32_32x32x16_bf16 v[64:79], v[80:83], v[84:87], v[64:79]
	v_cvt_pk_bf16_f32 v147, v110, v111
	v_lshl_add_u64 v[80:81], v[174:175], 0, s[64:65]
	s_mov_b32 s86, m0
	s_mov_b32 m0, s17
	s_nop 0
	global_load_lds_dwordx4 v[80:81], off
	s_mov_b32 m0, s86
	v_lshl_add_u64 v[80:81], v[170:171], 0, s[66:67]
	s_add_i32 s17, s85, 0xa000
	s_mov_b32 s86, m0
	s_mov_b32 m0, s17
	s_nop 0
	global_load_lds_dwordx4 v[80:81], off
	s_mov_b32 m0, s86
	v_lshl_add_u64 v[80:81], v[172:173], 0, s[66:67]
	s_add_i32 s17, s85, 0xc000
	s_mov_b32 s86, m0
	s_mov_b32 m0, s17
	s_nop 0
	global_load_lds_dwordx4 v[80:81], off
	s_mov_b32 m0, s86
	v_add_f32_e32 v198, v198, v104
	v_mfma_f32_32x32x16_bf16 v[48:63], v[156:159], v[178:181], v[48:63]
	ds_read_b64_tr_b16 v[104:105], v177 offset:40960
	ds_read_b64_tr_b16 v[106:107], v177 offset:41472
	v_exp_f32_e32 v128, v128
	v_exp_f32_e32 v129, v129
	v_mfma_f32_32x32x16_bf16 v[32:47], v[156:159], v[112:115], v[32:47]
	ds_read_b64_tr_b16 v[108:109], v177 offset:45056
	ds_read_b64_tr_b16 v[110:111], v177 offset:45568
	v_exp_f32_e32 v130, v130
	v_exp_f32_e32 v131, v131
	ds_read_b128 v[84:87], v234 offset:8192
	ds_read_b128 v[80:83], v234 offset:12288
	v_mfma_f32_32x32x16_bf16 v[48:63], v[152:155], v[116:119], v[48:63]
	ds_read_b64_tr_b16 v[178:179], v177 offset:41984
	ds_read_b64_tr_b16 v[180:181], v177 offset:42496
	v_exp_f32_e32 v132, v132
	v_exp_f32_e32 v133, v133
	ds_read_b128 v[164:167], v235 offset:8192
	ds_read_b128 v[124:127], v235 offset:12288
	v_mfma_f32_32x32x16_bf16 v[32:47], v[152:155], v[120:123], v[32:47]
	ds_read_b64_tr_b16 v[190:191], v177 offset:46080
	ds_read_b64_tr_b16 v[192:193], v177 offset:46592
	v_exp_f32_e32 v134, v134
	v_exp_f32_e32 v135, v135
	ds_read_b128 v[160:163], v236 offset:8192
	ds_read_b128 v[116:119], v236 offset:12288
	v_mfma_f32_32x32x16_bf16 v[48:63], v[148:151], v[92:95], v[48:63]
	ds_read_b64_tr_b16 v[194:195], v177 offset:43008
	ds_read_b64_tr_b16 v[196:197], v177 offset:43520
	v_exp_f32_e32 v136, v136
	v_exp_f32_e32 v137, v137
	ds_read_b128 v[120:123], v237 offset:8192
	ds_read_b128 v[112:115], v237 offset:12288
	v_mfma_f32_32x32x16_bf16 v[32:47], v[148:151], v[96:99], v[32:47]
	ds_read_b64_tr_b16 v[92:93], v177 offset:47104
	ds_read_b64_tr_b16 v[94:95], v177 offset:47616
	v_exp_f32_e32 v138, v138
	v_exp_f32_e32 v139, v139
	v_mfma_f32_32x32x16_bf16 v[48:63], v[144:147], v[100:103], v[48:63]
	ds_read_b64_tr_b16 v[96:97], v177 offset:44032
	ds_read_b64_tr_b16 v[98:99], v177 offset:44544
	v_exp_f32_e32 v140, v140
	v_exp_f32_e32 v141, v141
	v_mfma_f32_32x32x16_bf16 v[32:47], v[144:147], v[88:91], v[32:47]
	ds_read_b64_tr_b16 v[100:101], v177 offset:48128
	ds_read_b64_tr_b16 v[102:103], v177 offset:48640
	v_exp_f32_e32 v142, v142
	v_exp_f32_e32 v143, v143
	s_waitcnt lgkmcnt(14)
	v_mfma_f32_32x32x16_bf16 v[16:31], v[156:159], v[104:107], v[16:31]
	v_exp_f32_e32 v64, v64
	v_exp_f32_e32 v65, v65
	v_mfma_f32_32x32x16_bf16 v[0:15], v[156:159], v[108:111], v[0:15]
	v_exp_f32_e32 v66, v66
	v_exp_f32_e32 v67, v67
	v_mfma_f32_32x32x16_bf16 v[16:31], v[152:155], v[178:181], v[16:31]
	v_exp_f32_e32 v68, v68
	v_exp_f32_e32 v69, v69
	s_waitcnt lgkmcnt(12)
	v_mfma_f32_32x32x16_bf16 v[0:15], v[152:155], v[190:193], v[0:15]
	v_exp_f32_e32 v70, v70
	v_exp_f32_e32 v71, v71
	s_waitcnt lgkmcnt(8)
	v_mfma_f32_32x32x16_bf16 v[16:31], v[148:151], v[194:197], v[16:31]
	v_exp_f32_e32 v72, v72
	v_exp_f32_e32 v73, v73
	s_waitcnt lgkmcnt(4)
	v_mfma_f32_32x32x16_bf16 v[0:15], v[148:151], v[92:95], v[0:15]
	v_exp_f32_e32 v74, v74
	v_exp_f32_e32 v75, v75
	s_waitcnt lgkmcnt(2)
	v_mfma_f32_32x32x16_bf16 v[16:31], v[144:147], v[96:99], v[16:31]
	v_exp_f32_e32 v76, v76
	v_exp_f32_e32 v77, v77
	s_waitcnt lgkmcnt(0)
	v_mfma_f32_32x32x16_bf16 v[0:15], v[144:147], v[100:103], v[0:15]
	v_exp_f32_e32 v78, v78
	v_exp_f32_e32 v79, v79
	s_waitcnt vmcnt(3) lgkmcnt(0)
	s_barrier
	ds_read_b64_tr_b16 v[178:179], v188 offset:24576
	ds_read_b64_tr_b16 v[180:181], v188 offset:25088
	v_add_f32_e32 v92, v128, v129
	ds_read_b128 v[88:91], v168
	v_add_f32_e32 v92, v130, v92
	v_add_f32_e32 v92, v131, v92
	v_add_f32_e32 v92, v132, v92
	v_add_f32_e32 v92, v133, v92
	v_cvt_pk_bf16_f32 v156, v128, v129
	v_cvt_pk_bf16_f32 v157, v130, v131
	s_waitcnt lgkmcnt(0)
	v_mfma_f32_32x32x16_bf16 v[96:111], v[84:87], v[88:91], 0
	ds_read_b64_tr_b16 v[128:129], v188 offset:28672
	ds_read_b64_tr_b16 v[130:131], v188 offset:29184
	ds_read_b128 v[84:87], v168
	v_add_f32_e32 v88, v134, v92
	v_add_f32_e32 v88, v135, v88
	v_add_f32_e32 v88, v136, v88
	v_add_f32_e32 v144, v137, v88
	v_cvt_pk_bf16_f32 v158, v132, v133
	v_cvt_pk_bf16_f32 v159, v134, v135
	s_waitcnt lgkmcnt(0)
	v_mfma_f32_32x32x16_bf16 v[80:95], v[80:83], v[84:87], 0
	ds_read_b64_tr_b16 v[132:133], v188 offset:25600
	ds_read_b64_tr_b16 v[134:135], v188 offset:26112
	ds_read_b128 v[190:193], v168 offset:1024
	v_add_f32_e32 v144, v138, v144
	v_add_f32_e32 v144, v139, v144
	v_add_f32_e32 v144, v140, v144
	v_add_f32_e32 v144, v141, v144
	v_cvt_pk_bf16_f32 v152, v136, v137
	v_cvt_pk_bf16_f32 v153, v138, v139
	s_waitcnt lgkmcnt(0)
	v_mfma_f32_32x32x16_bf16 v[96:111], v[164:167], v[190:193], v[96:111]
	ds_read_b64_tr_b16 v[136:137], v188 offset:29696
	ds_read_b64_tr_b16 v[138:139], v188 offset:30208
	ds_read_b128 v[164:167], v168 offset:1024
	v_add_f32_e32 v144, v142, v144
	v_add_f32_e32 v144, v143, v144
	v_add_f32_e32 v144, v64, v144
	v_add_f32_e32 v144, v65, v144
	v_cvt_pk_bf16_f32 v154, v140, v141
	v_cvt_pk_bf16_f32 v155, v142, v143
	s_waitcnt lgkmcnt(0)
	v_mfma_f32_32x32x16_bf16 v[80:95], v[124:127], v[164:167], v[80:95]
	ds_read_b64_tr_b16 v[124:125], v188 offset:26624
	ds_read_b64_tr_b16 v[126:127], v188 offset:27136
	ds_read_b128 v[140:143], v168 offset:2048
	v_add_f32_e32 v144, v66, v144
	v_add_f32_e32 v144, v67, v144
	v_add_f32_e32 v144, v68, v144
	v_add_f32_e32 v144, v69, v144
	v_cvt_pk_bf16_f32 v148, v64, v65
	v_cvt_pk_bf16_f32 v149, v66, v67
	s_waitcnt lgkmcnt(0)
	v_mfma_f32_32x32x16_bf16 v[96:111], v[160:163], v[140:143], v[96:111]
	ds_read_b64_tr_b16 v[190:191], v188 offset:30720
	ds_read_b64_tr_b16 v[192:193], v188 offset:31232
	ds_read_b128 v[64:67], v168 offset:2048
	v_add_f32_e32 v140, v70, v144
	v_add_f32_e32 v140, v71, v140
	v_add_f32_e32 v140, v72, v140
	v_add_f32_e32 v140, v73, v140
	v_cvt_pk_bf16_f32 v150, v68, v69
	v_cvt_pk_bf16_f32 v151, v70, v71
	s_waitcnt lgkmcnt(0)
	v_mfma_f32_32x32x16_bf16 v[80:95], v[116:119], v[64:67], v[80:95]
	ds_read_b64_tr_b16 v[116:117], v188 offset:27648
	ds_read_b64_tr_b16 v[118:119], v188 offset:28160
	ds_read_b128 v[64:67], v168 offset:3072
	v_add_f32_e32 v68, v74, v140
	v_add_f32_e32 v68, v75, v68
	v_add_f32_e32 v68, v76, v68
	v_add_f32_e32 v68, v77, v68
	v_cvt_pk_bf16_f32 v144, v72, v73
	v_cvt_pk_bf16_f32 v145, v74, v75
	s_waitcnt lgkmcnt(0)
	v_mfma_f32_32x32x16_bf16 v[96:111], v[120:123], v[64:67], v[96:111]
	ds_read_b64_tr_b16 v[72:73], v188 offset:31744
	ds_read_b64_tr_b16 v[74:75], v188 offset:32256
	ds_read_b128 v[64:67], v168 offset:3072
	v_add_f32_e32 v68, v78, v68
	v_add_f32_e32 v68, v79, v68
	v_add_f32_e32 v68, 0, v68
	v_cvt_pk_bf16_f32 v146, v76, v77
	v_cvt_pk_bf16_f32 v147, v78, v79
	s_waitcnt lgkmcnt(0)
	v_mfma_f32_32x32x16_bf16 v[80:95], v[112:115], v[64:67], v[80:95]
	v_lshl_add_u64 v[64:65], v[170:171], 0, s[60:61]
	s_add_i32 s17, s85, 0xe000
	s_mov_b32 s86, m0
	s_mov_b32 m0, s17
	s_nop 0
	global_load_lds_dwordx4 v[64:65], off
	s_mov_b32 m0, s86
	v_lshl_add_u64 v[64:65], v[172:173], 0, s[60:61]
	s_add_i32 s85, s85, 0x10000
	s_mov_b32 s17, m0
	s_mov_b32 m0, s85
	s_nop 0
	global_load_lds_dwordx4 v[64:65], off
	s_mov_b32 m0, s17
	v_add_f32_e32 v174, v198, v68
	v_mfma_f32_32x32x16_bf16 v[48:63], v[156:159], v[178:181], v[48:63]
	ds_read_b64_tr_b16 v[76:77], v188 offset:32768
	ds_read_b64_tr_b16 v[78:79], v188 offset:33280
	v_exp_f32_e32 v96, v96
	v_exp_f32_e32 v97, v97
	v_mfma_f32_32x32x16_bf16 v[32:47], v[156:159], v[128:131], v[32:47]
	ds_read_b64_tr_b16 v[112:113], v188 offset:36864
	ds_read_b64_tr_b16 v[114:115], v188 offset:37376
	v_exp_f32_e32 v98, v98
	v_exp_f32_e32 v99, v99
	ds_read_b128 v[68:71], v234 offset:16384
	ds_read_b128 v[64:67], v234 offset:20480
	v_mfma_f32_32x32x16_bf16 v[48:63], v[152:155], v[132:135], v[48:63]
	ds_read_b64_tr_b16 v[120:121], v188 offset:33792
	ds_read_b64_tr_b16 v[122:123], v188 offset:34304
	v_exp_f32_e32 v100, v100
	v_exp_f32_e32 v101, v101
	ds_read_b128 v[164:167], v235 offset:16384
	ds_read_b128 v[140:143], v235 offset:20480
	v_mfma_f32_32x32x16_bf16 v[32:47], v[152:155], v[136:139], v[32:47]
	ds_read_b64_tr_b16 v[178:179], v188 offset:37888
	ds_read_b64_tr_b16 v[180:181], v188 offset:38400
	v_exp_f32_e32 v102, v102
	v_exp_f32_e32 v103, v103
	ds_read_b128 v[160:163], v236 offset:16384
	ds_read_b128 v[132:135], v236 offset:20480
	v_mfma_f32_32x32x16_bf16 v[48:63], v[148:151], v[124:127], v[48:63]
	ds_read_b64_tr_b16 v[194:195], v188 offset:34816
	ds_read_b64_tr_b16 v[196:197], v188 offset:35328
	v_exp_f32_e32 v104, v104
	v_exp_f32_e32 v105, v105
	ds_read_b128 v[136:139], v237 offset:16384
	ds_read_b128 v[128:131], v237 offset:20480
	v_mfma_f32_32x32x16_bf16 v[32:47], v[148:151], v[190:193], v[32:47]
	ds_read_b64_tr_b16 v[124:125], v188 offset:38912
	ds_read_b64_tr_b16 v[126:127], v188 offset:39424
	v_exp_f32_e32 v106, v106
	v_exp_f32_e32 v107, v107
	v_mfma_f32_32x32x16_bf16 v[48:63], v[144:147], v[116:119], v[48:63]
	ds_read_b64_tr_b16 v[190:191], v188 offset:35840
	ds_read_b64_tr_b16 v[192:193], v188 offset:36352
	v_exp_f32_e32 v108, v108
	v_exp_f32_e32 v109, v109
	v_mfma_f32_32x32x16_bf16 v[32:47], v[144:147], v[72:75], v[32:47]
	ds_read_b64_tr_b16 v[116:117], v188 offset:39936
	ds_read_b64_tr_b16 v[118:119], v188 offset:40448
	v_exp_f32_e32 v110, v110
	v_exp_f32_e32 v111, v111
	s_waitcnt lgkmcnt(14)
	v_mfma_f32_32x32x16_bf16 v[16:31], v[156:159], v[76:79], v[16:31]
	v_exp_f32_e32 v80, v80
	v_exp_f32_e32 v81, v81
	v_mfma_f32_32x32x16_bf16 v[0:15], v[156:159], v[112:115], v[0:15]
	v_exp_f32_e32 v82, v82
	v_exp_f32_e32 v83, v83
	v_mfma_f32_32x32x16_bf16 v[16:31], v[152:155], v[120:123], v[16:31]
	v_exp_f32_e32 v84, v84
	v_exp_f32_e32 v85, v85
	s_waitcnt lgkmcnt(12)
	v_mfma_f32_32x32x16_bf16 v[0:15], v[152:155], v[178:181], v[0:15]
	v_exp_f32_e32 v86, v86
	v_exp_f32_e32 v87, v87
	s_waitcnt lgkmcnt(8)
	v_mfma_f32_32x32x16_bf16 v[16:31], v[148:151], v[194:197], v[16:31]
	v_exp_f32_e32 v88, v88
	v_exp_f32_e32 v89, v89
	s_waitcnt lgkmcnt(4)
	v_mfma_f32_32x32x16_bf16 v[0:15], v[148:151], v[124:127], v[0:15]
	v_exp_f32_e32 v90, v90
	v_exp_f32_e32 v91, v91
	s_waitcnt lgkmcnt(2)
	v_mfma_f32_32x32x16_bf16 v[16:31], v[144:147], v[190:193], v[16:31]
	v_exp_f32_e32 v92, v92
	v_exp_f32_e32 v93, v93
	s_waitcnt lgkmcnt(0)
	v_mfma_f32_32x32x16_bf16 v[0:15], v[144:147], v[116:119], v[0:15]
	v_exp_f32_e32 v94, v94
	v_exp_f32_e32 v95, v95
	s_waitcnt vmcnt(2) lgkmcnt(0)
	s_barrier
	ds_read_b64_tr_b16 v[178:179], v188 offset:40960
	ds_read_b64_tr_b16 v[180:181], v188 offset:41472
	v_add_f32_e32 v76, v96, v97
	ds_read_b128 v[72:75], v168
	v_add_f32_e32 v76, v98, v76
	v_add_f32_e32 v76, v99, v76
	v_add_f32_e32 v76, v100, v76
	v_add_f32_e32 v76, v101, v76
	v_cvt_pk_bf16_f32 v156, v96, v97
	v_cvt_pk_bf16_f32 v157, v98, v99
	s_waitcnt lgkmcnt(0)
	v_mfma_f32_32x32x16_bf16 v[112:127], v[68:71], v[72:75], 0
	ds_read_b64_tr_b16 v[96:97], v188 offset:45056
	ds_read_b64_tr_b16 v[98:99], v188 offset:45568
	ds_read_b128 v[68:71], v168
	v_add_f32_e32 v72, v102, v76
	v_add_f32_e32 v72, v103, v72
	v_add_f32_e32 v72, v104, v72
	v_add_f32_e32 v144, v105, v72
	s_waitcnt lgkmcnt(0)
	v_mfma_f32_32x32x16_bf16 v[64:79], v[64:67], v[68:71], 0
	v_cvt_pk_bf16_f32 v158, v100, v101
	v_cvt_pk_bf16_f32 v159, v102, v103
	ds_read_b64_tr_b16 v[100:101], v188 offset:41984
	ds_read_b64_tr_b16 v[102:103], v188 offset:42496
	ds_read_b128 v[190:193], v168 offset:1024
	v_add_f32_e32 v144, v106, v144
	v_add_f32_e32 v144, v107, v144
	v_add_f32_e32 v144, v108, v144
	v_add_f32_e32 v144, v109, v144
	v_cvt_pk_bf16_f32 v152, v104, v105
	v_cvt_pk_bf16_f32 v153, v106, v107
	s_waitcnt lgkmcnt(0)
	v_mfma_f32_32x32x16_bf16 v[112:127], v[164:167], v[190:193], v[112:127]
	ds_read_b64_tr_b16 v[104:105], v188 offset:46080
	ds_read_b64_tr_b16 v[106:107], v188 offset:46592
	ds_read_b128 v[164:167], v168 offset:1024
	v_add_f32_e32 v144, v110, v144
	v_add_f32_e32 v144, v111, v144
	v_add_f32_e32 v144, v80, v144
	v_add_f32_e32 v144, v81, v144
	s_waitcnt lgkmcnt(0)
	v_mfma_f32_32x32x16_bf16 v[64:79], v[140:143], v[164:167], v[64:79]
	v_cvt_pk_bf16_f32 v154, v108, v109
	v_cvt_pk_bf16_f32 v155, v110, v111
	ds_read_b64_tr_b16 v[108:109], v188 offset:43008
	ds_read_b64_tr_b16 v[110:111], v188 offset:43520
	ds_read_b128 v[140:143], v168 offset:2048
	v_add_f32_e32 v144, v82, v144
	v_add_f32_e32 v144, v83, v144
	v_add_f32_e32 v144, v84, v144
	v_add_f32_e32 v144, v85, v144
	v_cvt_pk_bf16_f32 v148, v80, v81
	v_cvt_pk_bf16_f32 v149, v82, v83
	s_waitcnt lgkmcnt(0)
	v_mfma_f32_32x32x16_bf16 v[112:127], v[160:163], v[140:143], v[112:127]
	ds_read_b64_tr_b16 v[190:191], v188 offset:47104
	ds_read_b64_tr_b16 v[192:193], v188 offset:47616
	ds_read_b128 v[80:83], v168 offset:2048
	v_add_f32_e32 v140, v86, v144
	v_add_f32_e32 v140, v87, v140
	v_add_f32_e32 v140, v88, v140
	v_add_f32_e32 v140, v89, v140
	s_waitcnt lgkmcnt(0)
	v_mfma_f32_32x32x16_bf16 v[64:79], v[132:135], v[80:83], v[64:79]
	v_cvt_pk_bf16_f32 v150, v84, v85
	v_cvt_pk_bf16_f32 v151, v86, v87
	ds_read_b64_tr_b16 v[84:85], v188 offset:44032
	ds_read_b64_tr_b16 v[86:87], v188 offset:44544
	ds_read_b128 v[80:83], v168 offset:3072
	v_add_f32_e32 v132, v90, v140
	v_add_f32_e32 v132, v91, v132
	v_add_f32_e32 v132, v92, v132
	v_add_f32_e32 v132, v93, v132
	v_cvt_pk_bf16_f32 v144, v88, v89
	v_cvt_pk_bf16_f32 v145, v90, v91
	s_waitcnt lgkmcnt(0)
	v_mfma_f32_32x32x16_bf16 v[112:127], v[136:139], v[80:83], v[112:127]
	ds_read_b64_tr_b16 v[88:89], v188 offset:48128
	ds_read_b64_tr_b16 v[90:91], v188 offset:48640
	ds_read_b128 v[80:83], v168 offset:3072
	v_add_f32_e32 v132, v94, v132
	v_add_f32_e32 v132, v95, v132
	v_add_f32_e32 v132, 0, v132
	v_cvt_pk_bf16_f32 v146, v92, v93
	s_waitcnt lgkmcnt(0)
	v_mfma_f32_32x32x16_bf16 v[64:79], v[128:131], v[80:83], v[64:79]
	v_cvt_pk_bf16_f32 v147, v94, v95
	v_lshl_add_u64 v[80:81], v[170:171], 0, s[64:65]
	s_mov_b32 s17, m0
	s_mov_b32 m0, s16
	s_nop 0
	global_load_lds_dwordx4 v[80:81], off
	s_mov_b32 m0, s17
	v_lshl_add_u64 v[80:81], v[172:173], 0, s[64:65]
	s_mov_b32 s16, m0
	s_mov_b32 m0, s35
	s_nop 0
	global_load_lds_dwordx4 v[80:81], off
	s_mov_b32 m0, s16
	v_add_f32_e32 v174, v174, v132
	v_mfma_f32_32x32x16_bf16 v[48:63], v[156:159], v[178:181], v[48:63]
	ds_read_b64_tr_b16 v[92:93], v188 offset:49152
	ds_read_b64_tr_b16 v[94:95], v188 offset:49664
	v_exp_f32_e32 v112, v112
	v_exp_f32_e32 v113, v113
	v_mfma_f32_32x32x16_bf16 v[32:47], v[156:159], v[96:99], v[32:47]
	ds_read_b64_tr_b16 v[170:171], v188 offset:53248
	ds_read_b64_tr_b16 v[172:173], v188 offset:53760
	v_exp_f32_e32 v114, v114
	v_exp_f32_e32 v115, v115
	ds_read_b128 v[80:83], v234
	ds_read_b128 v[96:99], v234 offset:4096
	v_mfma_f32_32x32x16_bf16 v[48:63], v[152:155], v[100:103], v[48:63]
	ds_read_b64_tr_b16 v[178:179], v188 offset:50176
	ds_read_b64_tr_b16 v[180:181], v188 offset:50688
	v_exp_f32_e32 v116, v116
	v_exp_f32_e32 v117, v117
	ds_read_b128 v[164:167], v235
	ds_read_b128 v[140:143], v235 offset:4096
	v_mfma_f32_32x32x16_bf16 v[32:47], v[152:155], v[104:107], v[32:47]
	ds_read_b64_tr_b16 v[100:101], v188 offset:54272
	ds_read_b64_tr_b16 v[102:103], v188 offset:54784
	v_exp_f32_e32 v118, v118
	v_exp_f32_e32 v119, v119
	ds_read_b128 v[160:163], v236
	ds_read_b128 v[132:135], v236 offset:4096
	v_mfma_f32_32x32x16_bf16 v[48:63], v[148:151], v[108:111], v[48:63]
	ds_read_b64_tr_b16 v[104:105], v188 offset:51200
	ds_read_b64_tr_b16 v[106:107], v188 offset:51712
	v_exp_f32_e32 v120, v120
	v_exp_f32_e32 v121, v121
	ds_read_b128 v[136:139], v237
	ds_read_b128 v[128:131], v237 offset:4096
	v_mfma_f32_32x32x16_bf16 v[32:47], v[148:151], v[190:193], v[32:47]
	ds_read_b64_tr_b16 v[108:109], v188 offset:55296
	ds_read_b64_tr_b16 v[110:111], v188 offset:55808
	v_exp_f32_e32 v122, v122
	v_exp_f32_e32 v123, v123
	v_mfma_f32_32x32x16_bf16 v[48:63], v[144:147], v[84:87], v[48:63]
	ds_read_b64_tr_b16 v[190:191], v188 offset:52224
	ds_read_b64_tr_b16 v[192:193], v188 offset:52736
	v_exp_f32_e32 v124, v124
	v_exp_f32_e32 v125, v125
	v_mfma_f32_32x32x16_bf16 v[32:47], v[144:147], v[88:91], v[32:47]
	ds_read_b64_tr_b16 v[84:85], v188 offset:56320
	ds_read_b64_tr_b16 v[86:87], v188 offset:56832
	v_exp_f32_e32 v126, v126
	v_exp_f32_e32 v127, v127
	s_waitcnt lgkmcnt(14)
	v_mfma_f32_32x32x16_bf16 v[16:31], v[156:159], v[92:95], v[16:31]
	v_exp_f32_e32 v64, v64
	v_exp_f32_e32 v65, v65
	v_mfma_f32_32x32x16_bf16 v[0:15], v[156:159], v[170:173], v[0:15]
	v_exp_f32_e32 v66, v66
	v_exp_f32_e32 v67, v67
	v_mfma_f32_32x32x16_bf16 v[16:31], v[152:155], v[178:181], v[16:31]
	v_exp_f32_e32 v68, v68
	v_exp_f32_e32 v69, v69
	s_waitcnt lgkmcnt(12)
	v_mfma_f32_32x32x16_bf16 v[0:15], v[152:155], v[100:103], v[0:15]
	v_exp_f32_e32 v70, v70
	v_exp_f32_e32 v71, v71
	s_waitcnt lgkmcnt(8)
	v_mfma_f32_32x32x16_bf16 v[16:31], v[148:151], v[104:107], v[16:31]
	v_exp_f32_e32 v72, v72
	v_exp_f32_e32 v73, v73
	s_waitcnt lgkmcnt(4)
	v_mfma_f32_32x32x16_bf16 v[0:15], v[148:151], v[108:111], v[0:15]
	v_exp_f32_e32 v74, v74
	v_exp_f32_e32 v75, v75
	s_waitcnt lgkmcnt(2)
	v_mfma_f32_32x32x16_bf16 v[16:31], v[144:147], v[190:193], v[16:31]
	v_exp_f32_e32 v76, v76
	v_exp_f32_e32 v77, v77
	s_waitcnt lgkmcnt(0)
	v_mfma_f32_32x32x16_bf16 v[0:15], v[144:147], v[84:87], v[0:15]
	v_exp_f32_e32 v78, v78
	v_exp_f32_e32 v79, v79
	s_waitcnt vmcnt(0) lgkmcnt(0)
	s_barrier
	ds_read_b64_tr_b16 v[170:171], v188 offset:57344
	ds_read_b64_tr_b16 v[172:173], v188 offset:57856
	v_add_f32_e32 v88, v112, v113
	ds_read_b128 v[84:87], v168
	v_add_f32_e32 v88, v114, v88
	v_add_f32_e32 v88, v115, v88
	v_add_f32_e32 v88, v116, v88
	v_add_f32_e32 v104, v117, v88
	v_cvt_pk_bf16_f32 v156, v112, v113
	v_cvt_pk_bf16_f32 v157, v114, v115
	s_waitcnt lgkmcnt(0)
	v_mfma_f32_32x32x16_bf16 v[80:95], v[80:83], v[84:87], 0
	ds_read_b64_tr_b16 v[112:113], v188 offset:61440
	ds_read_b64_tr_b16 v[114:115], v188 offset:61952
	ds_read_b128 v[100:103], v168
	v_add_f32_e32 v104, v118, v104
	v_add_f32_e32 v104, v119, v104
	v_add_f32_e32 v104, v120, v104
	v_add_f32_e32 v144, v121, v104
	v_cvt_pk_bf16_f32 v158, v116, v117
	v_cvt_pk_bf16_f32 v159, v118, v119
	s_waitcnt lgkmcnt(0)
	v_mfma_f32_32x32x16_bf16 v[96:111], v[96:99], v[100:103], 0
	ds_read_b64_tr_b16 v[116:117], v188 offset:58368
	ds_read_b64_tr_b16 v[118:119], v188 offset:58880
	ds_read_b128 v[178:181], v168 offset:1024
	v_add_f32_e32 v144, v122, v144
	v_add_f32_e32 v144, v123, v144
	v_add_f32_e32 v144, v124, v144
	v_add_f32_e32 v144, v125, v144
	v_cvt_pk_bf16_f32 v152, v120, v121
	v_cvt_pk_bf16_f32 v153, v122, v123
	s_waitcnt lgkmcnt(0)
	v_mfma_f32_32x32x16_bf16 v[80:95], v[164:167], v[178:181], v[80:95]
	ds_read_b64_tr_b16 v[120:121], v188 offset:62464
	ds_read_b64_tr_b16 v[122:123], v188 offset:62976
	ds_read_b128 v[164:167], v168 offset:1024
	v_add_f32_e32 v144, v126, v144
	v_add_f32_e32 v144, v127, v144
	v_add_f32_e32 v144, v64, v144
	v_add_f32_e32 v144, v65, v144
	v_cvt_pk_bf16_f32 v154, v124, v125
	v_cvt_pk_bf16_f32 v155, v126, v127
	s_waitcnt lgkmcnt(0)
	v_mfma_f32_32x32x16_bf16 v[96:111], v[140:143], v[164:167], v[96:111]
	ds_read_b64_tr_b16 v[124:125], v188 offset:59392
	ds_read_b64_tr_b16 v[126:127], v188 offset:59904
	ds_read_b128 v[140:143], v168 offset:2048
	v_add_f32_e32 v144, v66, v144
	v_add_f32_e32 v144, v67, v144
	v_add_f32_e32 v144, v68, v144
	v_add_f32_e32 v144, v69, v144
	v_cvt_pk_bf16_f32 v148, v64, v65
	v_cvt_pk_bf16_f32 v149, v66, v67
	s_waitcnt lgkmcnt(0)
	v_mfma_f32_32x32x16_bf16 v[80:95], v[160:163], v[140:143], v[80:95]
	ds_read_b64_tr_b16 v[64:65], v188 offset:63488
	ds_read_b64_tr_b16 v[66:67], v188 offset:64000
	ds_read_b128 v[140:143], v168 offset:2048
	v_add_f32_e32 v144, v70, v144
	v_add_f32_e32 v144, v71, v144
	v_add_f32_e32 v144, v72, v144
	v_add_f32_e32 v144, v73, v144
	v_cvt_pk_bf16_f32 v150, v68, v69
	v_cvt_pk_bf16_f32 v151, v70, v71
	s_waitcnt lgkmcnt(0)
	v_mfma_f32_32x32x16_bf16 v[96:111], v[132:135], v[140:143], v[96:111]
	ds_read_b64_tr_b16 v[68:69], v188 offset:60416
	ds_read_b64_tr_b16 v[70:71], v188 offset:60928
	ds_read_b128 v[132:135], v168 offset:3072
	v_add_f32_e32 v140, v74, v144
	v_add_f32_e32 v140, v75, v140
	v_add_f32_e32 v140, v76, v140
	v_add_f32_e32 v140, v77, v140
	v_cvt_pk_bf16_f32 v144, v72, v73
	v_cvt_pk_bf16_f32 v145, v74, v75
	s_waitcnt lgkmcnt(0)
	v_mfma_f32_32x32x16_bf16 v[80:95], v[136:139], v[132:135], v[80:95]
	ds_read_b64_tr_b16 v[72:73], v188 offset:64512
	ds_read_b64_tr_b16 v[74:75], v188 offset:65024
	ds_read_b128 v[132:135], v168 offset:3072
	v_add_f32_e32 v136, v78, v140
	v_add_f32_e32 v136, v79, v136
	v_add_f32_e32 v136, 0, v136
	v_cvt_pk_bf16_f32 v146, v76, v77
	v_cvt_pk_bf16_f32 v147, v78, v79
	s_waitcnt lgkmcnt(0)
	v_mfma_f32_32x32x16_bf16 v[96:111], v[128:131], v[132:135], v[96:111]
	v_mfma_f32_32x32x16_bf16 v[48:63], v[156:159], v[170:173], v[48:63]
	ds_read_b64_tr_b16 v[76:77], v177 offset:40960
	ds_read_b64_tr_b16 v[78:79], v177 offset:41472
	v_exp_f32_e32 v80, v80
	v_exp_f32_e32 v81, v81
	v_mfma_f32_32x32x16_bf16 v[32:47], v[156:159], v[112:115], v[32:47]
	ds_read_b64_tr_b16 v[128:129], v177 offset:45056
	ds_read_b64_tr_b16 v[130:131], v177 offset:45568
	v_exp_f32_e32 v82, v82
	v_exp_f32_e32 v83, v83
	v_mfma_f32_32x32x16_bf16 v[48:63], v[152:155], v[116:119], v[48:63]
	ds_read_b64_tr_b16 v[112:113], v177 offset:41984
	ds_read_b64_tr_b16 v[114:115], v177 offset:42496
	v_exp_f32_e32 v84, v84
	v_exp_f32_e32 v85, v85
	v_mfma_f32_32x32x16_bf16 v[32:47], v[152:155], v[120:123], v[32:47]
	ds_read_b64_tr_b16 v[116:117], v177 offset:46080
	ds_read_b64_tr_b16 v[118:119], v177 offset:46592
	v_exp_f32_e32 v86, v86
	v_exp_f32_e32 v87, v87
	v_mfma_f32_32x32x16_bf16 v[48:63], v[148:151], v[124:127], v[48:63]
	ds_read_b64_tr_b16 v[120:121], v177 offset:43008
	ds_read_b64_tr_b16 v[122:123], v177 offset:43520
	v_exp_f32_e32 v88, v88
	v_exp_f32_e32 v89, v89
	v_mfma_f32_32x32x16_bf16 v[32:47], v[148:151], v[64:67], v[32:47]
	ds_read_b64_tr_b16 v[124:125], v177 offset:47104
	ds_read_b64_tr_b16 v[126:127], v177 offset:47616
	v_exp_f32_e32 v90, v90
	v_exp_f32_e32 v91, v91
	v_mfma_f32_32x32x16_bf16 v[48:63], v[144:147], v[68:71], v[48:63]
	ds_read_b64_tr_b16 v[64:65], v177 offset:44032
	ds_read_b64_tr_b16 v[66:67], v177 offset:44544
	v_exp_f32_e32 v92, v92
	v_exp_f32_e32 v93, v93
	v_mfma_f32_32x32x16_bf16 v[32:47], v[144:147], v[72:75], v[32:47]
	ds_read_b64_tr_b16 v[68:69], v177 offset:48128
	ds_read_b64_tr_b16 v[70:71], v177 offset:48640
	v_exp_f32_e32 v94, v94
	v_exp_f32_e32 v95, v95
	s_waitcnt lgkmcnt(14)
	v_mfma_f32_32x32x16_bf16 v[16:31], v[156:159], v[76:79], v[16:31]
	v_exp_f32_e32 v96, v96
	v_exp_f32_e32 v97, v97
	s_waitcnt lgkmcnt(12)
; #define SBAR() __builtin_amdgcn_sched_barrier(0)
; __device__ __forceinline__ void pv(f32x16*o,int vb,bf16x8 pa0,bf16x8 pa1,bf16x8 pa2,bf16x8 pa3){
;   #pragma unroll
;   for(int d0=0;d0<2;++d0){s16x4 lo[4],hi[4];
;     #pragma unroll
;     for(int ks=0;ks<4;++ks){
;       asm volatile("ds_read_b64_tr_b16 %0,%1 offset:%c2":"=&v"(lo[ks]):"v"(vb),"i"(d0*4096+ks*1024):"memory");
;       asm volatile("ds_read_b64_tr_b16 %0,%1 offset:%c2":"=&v"(hi[ks]):"v"(vb),"i"(d0*4096+ks*1024+512):"memory");}
;     asm volatile("s_waitcnt lgkmcnt(0)":::"memory");SBAR();
;     ...
;     o[d0]=__builtin_amdgcn_mfma_f32_32x32x16_bf16(pa0,PK(0),o[d0],0,0,0);
;     o[d0]=__builtin_amdgcn_mfma_f32_32x32x16_bf16(pa1,PK(1),o[d0],0,0,0);
;     o[d0]=__builtin_amdgcn_mfma_f32_32x32x16_bf16(pa2,PK(2),o[d0],0,0,0);
;     o[d0]=__builtin_amdgcn_mfma_f32_32x32x16_bf16(pa3,PK(3),o[d0],0,0,0);
;     ...
;   }
; }
; template<int THRL,int VM,bool NOMAX> __device__ __forceinline__ void attn_unit(const bf16*Qb,const bf16*__restrict__ Kh,const bf16*__restrict__ Vh,bf16*Ob,const int NT,const int sp,float*wscr,char*shm){
;     ...
;   int t=1;
;   for(;t+5<NT;t+=2){
;     STEP(pB0,pB1,pA0,pA1,t,true,true,true);     if constexpr(VM==2){WAIT_BAR(3);}else{WAIT_BAR(2);} RESC(); ROT();
;     STEP(pA0,pA1,pB0,pB1,t+1,true,true,true);   if constexpr(VM==2){WAIT_BAR(3);}else{WAIT_BAR(2);} RESC(); ROT();
;   }
;     ...
;   for(;t+1<NT;t+=2){
;     STEP(pB0,pB1,pA0,pA1,t,(t+3<NT),(t+1<NT),(t+1<NT));       ENDW(t);   RESC(); ROT();
;     STEP(pA0,pA1,pB0,pB1,t+1,(t+4<NT),(t+2<NT),(t+2<NT));     ENDW(t+1); RESC(); ROT();
;   }
;   STEP(pB0,pB1,pA0,pA1,NT-1,false,false,false); RESC();
;   { float sacc=pB0[0]+pB0[1]; _Pragma("unroll") for(int r=2;r<16;++r)sacc+=pB0[r]; _Pragma("unroll") for(int r=0;r<16;++r)sacc+=pB1[r]; l_reg+=sacc;
;     pw0=(u32x4){PKW(pB0,0),PKW(pB0,2),PKW(pB0,4),PKW(pB0,6)};pw1=(u32x4){PKW(pB0,8),PKW(pB0,10),PKW(pB0,12),PKW(pB0,14)};pw2=(u32x4){PKW(pB1,0),PKW(pB1,2),PKW(pB1,4),PKW(pB1,6)};pw3=(u32x4){PKW(pB1,8),PKW(pB1,10),PKW(pB1,12),PKW(pB1,14)};
;     SBAR(); pv(o,vb0+VM*sl_cur,PAF(0),PAF(1),PAF(2),PAF(3)); if constexpr(VM==2) pv(o+2,vb0+VM*sl_cur+8192,PAF(0),PAF(1),PAF(2),PAF(3)); }
;     ...
;   {auto rr=__builtin_amdgcn_permlane32_swap(__float_as_uint(l_reg),__float_as_uint(l_reg),false,false);l_reg=__uint_as_float(rr[0])+__uint_as_float(rr[1]);}
;   if(hi==0)wsf[32+r32]=l_reg;asm volatile("s_waitcnt lgkmcnt(0)":::"memory");
	v_mfma_f32_32x32x16_bf16 v[0:15], v[156:159], v[128:131], v[0:15]
	v_exp_f32_e32 v98, v98
	v_exp_f32_e32 v99, v99
	s_waitcnt lgkmcnt(10)
	v_mfma_f32_32x32x16_bf16 v[16:31], v[152:155], v[112:115], v[16:31]
	v_exp_f32_e32 v100, v100
	v_exp_f32_e32 v101, v101
	s_waitcnt lgkmcnt(8)
	v_mfma_f32_32x32x16_bf16 v[0:15], v[152:155], v[116:119], v[0:15]
	v_exp_f32_e32 v102, v102
	v_exp_f32_e32 v103, v103
	s_waitcnt lgkmcnt(6)
	v_mfma_f32_32x32x16_bf16 v[16:31], v[148:151], v[120:123], v[16:31]
	v_exp_f32_e32 v104, v104
	v_exp_f32_e32 v105, v105
	s_waitcnt lgkmcnt(4)
	v_mfma_f32_32x32x16_bf16 v[0:15], v[148:151], v[124:127], v[0:15]
	v_exp_f32_e32 v106, v106
	v_exp_f32_e32 v107, v107
	s_waitcnt lgkmcnt(2)
	v_mfma_f32_32x32x16_bf16 v[16:31], v[144:147], v[64:67], v[16:31]
	v_exp_f32_e32 v108, v108
	v_exp_f32_e32 v109, v109
	s_waitcnt lgkmcnt(0)
	v_mfma_f32_32x32x16_bf16 v[0:15], v[144:147], v[68:71], v[0:15]
	v_exp_f32_e32 v110, v110
	v_exp_f32_e32 v111, v111
	v_add_f32_e32 v64, v80, v81
	v_add_f32_e32 v64, v82, v64
	v_add_f32_e32 v64, v83, v64
	v_add_f32_e32 v64, v84, v64
	v_add_f32_e32 v64, v85, v64
	v_add_f32_e32 v64, v86, v64
	v_add_f32_e32 v64, v87, v64
	v_add_f32_e32 v64, v88, v64
	v_add_f32_e32 v64, v89, v64
	v_add_f32_e32 v64, v90, v64
	v_add_f32_e32 v64, v91, v64
	v_add_f32_e32 v64, v92, v64
	v_add_f32_e32 v64, v93, v64
	v_add_f32_e32 v64, v94, v64
	v_add_f32_e32 v64, v95, v64
	v_add_f32_e32 v64, v64, v96
	v_add_f32_e32 v64, v97, v64
	v_add_f32_e32 v64, v98, v64
	v_add_f32_e32 v64, v99, v64
	v_add_f32_e32 v64, v100, v64
	v_add_f32_e32 v64, v101, v64
	v_add_f32_e32 v64, v102, v64
	v_add_f32_e32 v64, v103, v64
	v_add_f32_e32 v64, v104, v64
	v_add_f32_e32 v64, v105, v64
	v_add_f32_e32 v64, v106, v64
	v_add_f32_e32 v64, v107, v64
	v_add_f32_e32 v64, v108, v64
	v_add_f32_e32 v64, v109, v64
	v_add_f32_e32 v64, v110, v64
	v_add_f32_e32 v64, v111, v64
	v_add_f32_e32 v65, v174, v136
	v_add_f32_e32 v64, v65, v64
	v_cvt_pk_bf16_f32 v66, v80, v81
	v_cvt_pk_bf16_f32 v67, v82, v83
	v_cvt_pk_bf16_f32 v68, v84, v85
	v_cvt_pk_bf16_f32 v69, v86, v87
	v_cvt_pk_bf16_f32 v70, v88, v89
	v_cvt_pk_bf16_f32 v71, v90, v91
	v_cvt_pk_bf16_f32 v72, v92, v93
	v_cvt_pk_bf16_f32 v73, v94, v95
	v_cvt_pk_bf16_f32 v74, v96, v97
	v_cvt_pk_bf16_f32 v75, v98, v99
	v_cvt_pk_bf16_f32 v76, v100, v101
	v_cvt_pk_bf16_f32 v77, v102, v103
	v_cvt_pk_bf16_f32 v78, v104, v105
	v_cvt_pk_bf16_f32 v79, v106, v107
	v_cvt_pk_bf16_f32 v80, v108, v109
	v_cvt_pk_bf16_f32 v81, v110, v111
	ds_read_b64_tr_b16 v[82:83],v176 offset:0
	ds_read_b64_tr_b16 v[84:85],v176 offset:512
	ds_read_b64_tr_b16 v[86:87],v176 offset:1024
	ds_read_b64_tr_b16 v[88:89],v176 offset:1536
	ds_read_b64_tr_b16 v[90:91],v176 offset:2048
	ds_read_b64_tr_b16 v[92:93],v176 offset:2560
	ds_read_b64_tr_b16 v[94:95],v176 offset:3072
	ds_read_b64_tr_b16 v[96:97],v176 offset:3584
	s_waitcnt lgkmcnt(0)
	s_nop 0
	v_mfma_f32_32x32x16_bf16 v[48:63], v[66:69], v[82:85], v[48:63]
	ds_read_b64_tr_b16 v[82:83],v176 offset:4096
	ds_read_b64_tr_b16 v[84:85],v176 offset:4608
	v_mfma_f32_32x32x16_bf16 v[48:63], v[70:73], v[86:89], v[48:63]
	ds_read_b64_tr_b16 v[86:87],v176 offset:5120
	ds_read_b64_tr_b16 v[88:89],v176 offset:5632
	v_mfma_f32_32x32x16_bf16 v[48:63], v[74:77], v[90:93], v[48:63]
	ds_read_b64_tr_b16 v[90:91],v176 offset:6144
	ds_read_b64_tr_b16 v[92:93],v176 offset:6656
	ds_read_b64_tr_b16 v[98:99],v176 offset:7168
	ds_read_b64_tr_b16 v[100:101],v176 offset:7680
	s_waitcnt lgkmcnt(0)
	v_mfma_f32_32x32x16_bf16 v[48:63], v[78:81], v[94:97], v[48:63]
	v_mfma_f32_32x32x16_bf16 v[32:47], v[66:69], v[82:85], v[32:47]
	v_add_u32_e32 v65, 0x2000, v176
	ds_read_b64_tr_b16 v[82:83],v65 offset:0
	ds_read_b64_tr_b16 v[84:85],v65 offset:512
	v_mfma_f32_32x32x16_bf16 v[32:47], v[70:73], v[86:89], v[32:47]
	ds_read_b64_tr_b16 v[86:87],v65 offset:1024
	ds_read_b64_tr_b16 v[88:89],v65 offset:1536
	v_mfma_f32_32x32x16_bf16 v[32:47], v[74:77], v[90:93], v[32:47]
	ds_read_b64_tr_b16 v[90:91],v65 offset:2048
	ds_read_b64_tr_b16 v[92:93],v65 offset:2560
	ds_read_b64_tr_b16 v[94:95],v65 offset:3072
	ds_read_b64_tr_b16 v[96:97],v65 offset:3584
	s_waitcnt lgkmcnt(0)
	v_mfma_f32_32x32x16_bf16 v[32:47], v[78:81], v[98:101], v[32:47]
	v_mfma_f32_32x32x16_bf16 v[16:31], v[66:69], v[82:85], v[16:31]
	ds_read_b64_tr_b16 v[82:83],v65 offset:4096
	ds_read_b64_tr_b16 v[84:85],v65 offset:4608
	v_mfma_f32_32x32x16_bf16 v[16:31], v[70:73], v[86:89], v[16:31]
	ds_read_b64_tr_b16 v[86:87],v65 offset:5120
	ds_read_b64_tr_b16 v[88:89],v65 offset:5632
	v_mfma_f32_32x32x16_bf16 v[16:31], v[74:77], v[90:93], v[16:31]
	ds_read_b64_tr_b16 v[90:91],v65 offset:6144
	ds_read_b64_tr_b16 v[92:93],v65 offset:6656
	ds_read_b64_tr_b16 v[98:99],v65 offset:7168
	ds_read_b64_tr_b16 v[100:101],v65 offset:7680
	s_waitcnt lgkmcnt(0)
	v_mfma_f32_32x32x16_bf16 v[16:31], v[78:81], v[94:97], v[16:31]
	v_mfma_f32_32x32x16_bf16 v[0:15], v[66:69], v[82:85], v[0:15]
	v_mov_b32_e32 v65, v64
	s_nop 1
	v_permlane32_swap_b32_e32 v64, v65
	v_cmp_gt_u32_e32 vcc, 32, v187
	v_mfma_f32_32x32x16_bf16 v[0:15], v[70:73], v[86:89], v[0:15]
	v_mfma_f32_32x32x16_bf16 v[0:15], v[74:77], v[90:93], v[0:15]
	v_mfma_f32_32x32x16_bf16 v[0:15], v[78:81], v[98:101], v[0:15]
	s_and_saveexec_b64 s[16:17], vcc
	s_cbranch_execz .LBB0_870
	v_add_f32_e32 v64, v64, v65
	v_lshl_add_u32 v65, v186, 2, s34
	ds_write_b32 v65, v64 offset:128
	s_branch .LBB0_870

.LBB0_882:
	v_mfma_f32_32x32x16_bf16 v[96:111], v[84:87], v[156:159], 0
	v_add_u32_e32 v187, s54, v182
	ds_read_b64_tr_b16 v[188:189], v187 offset:24576
	ds_read_b64_tr_b16 v[190:191], v187 offset:25088
	v_add_f32_e32 v88, v64, v65
	v_add_f32_e32 v88, v66, v88
	v_add_f32_e32 v88, v67, v88
	v_add_f32_e32 v88, v68, v88
	v_add_f32_e32 v88, v69, v88
	v_cvt_pk_bf16_f32 v140, v64, v65
	v_cvt_pk_bf16_f32 v141, v66, v67
	ds_read_b64_tr_b16 v[64:65], v187 offset:28672
	ds_read_b64_tr_b16 v[66:67], v187 offset:29184
	v_add_f32_e32 v84, v70, v88
	v_add_f32_e32 v84, v71, v84
	v_add_f32_e32 v84, v72, v84
	v_add_f32_e32 v128, v73, v84
	s_waitcnt lgkmcnt(10)
	v_mfma_f32_32x32x16_bf16 v[80:95], v[80:83], v[156:159], 0
	v_cvt_pk_bf16_f32 v142, v68, v69
	v_cvt_pk_bf16_f32 v143, v70, v71
	ds_read_b64_tr_b16 v[68:69], v187 offset:25600
	ds_read_b64_tr_b16 v[70:71], v187 offset:26112
	v_add_f32_e32 v128, v74, v128
	v_add_f32_e32 v128, v75, v128
	v_add_f32_e32 v128, v76, v128
	v_add_f32_e32 v128, v77, v128
	v_cvt_pk_bf16_f32 v136, v72, v73
	v_cvt_pk_bf16_f32 v137, v74, v75
	s_waitcnt lgkmcnt(11)
	v_mfma_f32_32x32x16_bf16 v[96:111], v[164:167], v[152:155], v[96:111]
	ds_read_b64_tr_b16 v[72:73], v187 offset:29696
	ds_read_b64_tr_b16 v[74:75], v187 offset:30208
	s_waitcnt lgkmcnt(12)
	v_mfma_f32_32x32x16_bf16 v[80:95], v[160:163], v[152:155], v[80:95]
	v_add_f32_e32 v128, v78, v128
	v_add_f32_e32 v128, v79, v128
	v_add_f32_e32 v128, v48, v128
	v_add_f32_e32 v128, v49, v128
	v_cvt_pk_bf16_f32 v138, v76, v77
	v_cvt_pk_bf16_f32 v139, v78, v79
	ds_read_b64_tr_b16 v[76:77], v187 offset:26624
	ds_read_b64_tr_b16 v[78:79], v187 offset:27136
	v_add_f32_e32 v128, v50, v128
	v_add_f32_e32 v128, v51, v128
	v_add_f32_e32 v128, v52, v128
	v_add_f32_e32 v128, v53, v128
	v_cvt_pk_bf16_f32 v132, v48, v49
	v_cvt_pk_bf16_f32 v133, v50, v51
	s_waitcnt lgkmcnt(13)
	v_mfma_f32_32x32x16_bf16 v[96:111], v[124:127], v[148:151], v[96:111]
	ds_read_b64_tr_b16 v[48:49], v187 offset:30720
	ds_read_b64_tr_b16 v[50:51], v187 offset:31232
	s_waitcnt lgkmcnt(14)
	v_mfma_f32_32x32x16_bf16 v[80:95], v[120:123], v[148:151], v[80:95]
	v_add_f32_e32 v124, v54, v128
	v_add_f32_e32 v124, v55, v124
	v_add_f32_e32 v124, v56, v124
	v_add_f32_e32 v124, v57, v124
	v_cvt_pk_bf16_f32 v134, v52, v53
	v_cvt_pk_bf16_f32 v135, v54, v55
	ds_read_b64_tr_b16 v[52:53], v187 offset:27648
	ds_read_b64_tr_b16 v[54:55], v187 offset:28160
	v_add_f32_e32 v120, v58, v124
	v_add_f32_e32 v120, v59, v120
	v_add_f32_e32 v120, v60, v120
	v_add_f32_e32 v120, v61, v120
	v_cvt_pk_bf16_f32 v128, v56, v57
	v_cvt_pk_bf16_f32 v129, v58, v59
	s_waitcnt lgkmcnt(14)
	v_mfma_f32_32x32x16_bf16 v[96:111], v[116:119], v[144:147], v[96:111]
	ds_read_b64_tr_b16 v[56:57], v187 offset:31744
	ds_read_b64_tr_b16 v[58:59], v187 offset:32256
	v_mfma_f32_32x32x16_bf16 v[80:95], v[112:115], v[144:147], v[80:95]
	v_add_f32_e32 v116, v62, v120
	v_add_f32_e32 v116, v63, v116
	v_add_f32_e32 v116, 0, v116
	v_cvt_pk_bf16_f32 v130, v60, v61
	v_cvt_pk_bf16_f32 v131, v62, v63
	v_lshl_add_u64 v[60:61], v[176:177], 0, s[38:39]
	s_add_i32 s53, s52, s33
	s_mov_b32 s54, m0
	s_mov_b32 m0, s53
	s_nop 0
	global_load_lds_dwordx4 v[60:61], off
	s_mov_b32 m0, s54
	v_lshl_add_u64 v[60:61], v[174:175], 0, s[38:39]
	s_add_i32 s53, s35, s16
	s_mov_b32 s54, m0
	s_mov_b32 m0, s53
	s_nop 0
	global_load_lds_dwordx4 v[60:61], off
	s_mov_b32 m0, s54
	v_add_f32_e32 v202, v186, v116
	s_waitcnt lgkmcnt(14)
	v_mfma_f32_32x32x16_bf16 v[16:31], v[140:143], v[188:191], v[16:31]
	v_exp_f32_e32 v96, v96
	v_exp_f32_e32 v97, v97
	v_exp_f32_e32 v98, v98
	v_exp_f32_e32 v99, v99
	s_waitcnt lgkmcnt(12)
	v_mfma_f32_32x32x16_bf16 v[32:47], v[140:143], v[64:67], v[32:47]
	v_exp_f32_e32 v100, v100
	v_exp_f32_e32 v101, v101
	v_exp_f32_e32 v102, v102
	v_exp_f32_e32 v103, v103
	v_add_u32_e32 v242, s35, v234
	v_add_u32_e32 v243, s35, v235
	v_add_u32_e32 v244, s35, v236
	v_add_u32_e32 v245, s35, v237
	ds_read_b128 v[60:63], v242
	ds_read_b128 v[112:115], v242 offset:4096
	s_waitcnt lgkmcnt(12)
	v_mfma_f32_32x32x16_bf16 v[16:31], v[136:139], v[68:71], v[16:31]
	v_exp_f32_e32 v104, v104
	v_exp_f32_e32 v105, v105
	v_exp_f32_e32 v106, v106
	v_exp_f32_e32 v107, v107
	ds_read_b128 v[116:119], v243
	ds_read_b128 v[120:123], v243 offset:4096
	s_waitcnt lgkmcnt(12)
	v_mfma_f32_32x32x16_bf16 v[32:47], v[136:139], v[72:75], v[32:47]
	v_exp_f32_e32 v108, v108
	v_exp_f32_e32 v109, v109
	v_exp_f32_e32 v110, v110
	v_exp_f32_e32 v111, v111
	ds_read_b128 v[124:127], v244
	ds_read_b128 v[160:163], v244 offset:4096
	s_waitcnt lgkmcnt(12)
	v_mfma_f32_32x32x16_bf16 v[16:31], v[132:135], v[76:79], v[16:31]
	v_exp_f32_e32 v80, v80
	v_exp_f32_e32 v81, v81
	v_exp_f32_e32 v82, v82
	v_exp_f32_e32 v83, v83
	ds_read_b128 v[164:167], v245
	ds_read_b128 v[186:189], v245 offset:4096
	s_waitcnt lgkmcnt(12)
	v_mfma_f32_32x32x16_bf16 v[32:47], v[132:135], v[48:51], v[32:47]
	v_exp_f32_e32 v84, v84
	v_exp_f32_e32 v85, v85
	v_exp_f32_e32 v86, v86
	v_exp_f32_e32 v87, v87
	s_waitcnt lgkmcnt(10)
	v_mfma_f32_32x32x16_bf16 v[16:31], v[128:131], v[52:55], v[16:31]
	v_exp_f32_e32 v88, v88
	v_exp_f32_e32 v89, v89
	v_exp_f32_e32 v90, v90
	v_exp_f32_e32 v91, v91
	s_waitcnt lgkmcnt(8)
	v_mfma_f32_32x32x16_bf16 v[32:47], v[128:131], v[56:59], v[32:47]
	v_exp_f32_e32 v92, v92
	v_exp_f32_e32 v93, v93
	v_exp_f32_e32 v94, v94
	v_exp_f32_e32 v95, v95
	s_waitcnt vmcnt(2) lgkmcnt(0)
	s_barrier
; #define WAIT_BAR(N) asm volatile("s_waitcnt vmcnt(" #N ") lgkmcnt(0)\n\ts_barrier":::"memory")
;   #define RESC() do{ if(!NOMAX&&resc){ asm volatile("s_waitcnt lgkmcnt(0)":::"memory"); \
;       _Pragma("unroll") for(int d_=0;d_<2*VM;++d_) _Pragma("unroll") for(int r=0;r<16;++r)o[d_][r]*=wsf[crow(r,hi)]; } }while(0)
;   #define ROT() do{sl_prev=sl_cur;sl_cur=sl_next;sl_next=(sl_next==(NSLOT-1)*SLOTB)?0:sl_next+SLOTB;}while(0)
; template<int THRL,int VM,bool NOMAX> __device__ __forceinline__ void attn_unit(const bf16*Qb,const bf16*__restrict__ Kh,const bf16*__restrict__ Vh,bf16*Ob,const int NT,const int sp,float*wscr,char*shm){
;     ...
;   int t=1;
;   for(;t+5<NT;t+=2){
;     STEP(pB0,pB1,pA0,pA1,t,true,true,true);     if constexpr(VM==2){WAIT_BAR(3);}else{WAIT_BAR(2);} RESC(); ROT();
;     STEP(pA0,pA1,pB0,pB1,t+1,true,true,true);   if constexpr(VM==2){WAIT_BAR(3);}else{WAIT_BAR(2);} RESC(); ROT();
	v_mfma_f32_32x32x16_bf16 v[64:79], v[60:63], v[156:159], 0
	s_add_i32 s53, s35, 0x2000
	s_cmpk_lg_i32 s35, 0x4000
	s_cselect_b32 s53, s53, 0
	v_add_u32_e32 v203, s52, v182
	ds_read_b64_tr_b16 v[190:191], v203 offset:24576
	ds_read_b64_tr_b16 v[192:193], v203 offset:25088
	v_add_f32_e32 v48, v96, v97
	v_add_f32_e32 v48, v98, v48
	v_add_f32_e32 v48, v99, v48
	v_add_f32_e32 v48, v100, v48
	v_add_f32_e32 v48, v101, v48
	v_cvt_pk_bf16_f32 v140, v96, v97
	v_cvt_pk_bf16_f32 v141, v98, v99
	ds_read_b64_tr_b16 v[96:97], v203 offset:28672
	ds_read_b64_tr_b16 v[98:99], v203 offset:29184
	v_add_f32_e32 v48, v102, v48
	v_add_f32_e32 v48, v103, v48
	v_add_f32_e32 v48, v104, v48
	v_add_f32_e32 v128, v105, v48
	s_waitcnt lgkmcnt(10)
	v_mfma_f32_32x32x16_bf16 v[48:63], v[112:115], v[156:159], 0
	v_cvt_pk_bf16_f32 v142, v100, v101
	v_cvt_pk_bf16_f32 v143, v102, v103
	ds_read_b64_tr_b16 v[100:101], v203 offset:25600
	ds_read_b64_tr_b16 v[102:103], v203 offset:26112
	s_waitcnt lgkmcnt(11)
	v_mfma_f32_32x32x16_bf16 v[64:79], v[116:119], v[152:155], v[64:79]
	v_add_f32_e32 v112, v106, v128
	v_add_f32_e32 v112, v107, v112
	v_add_f32_e32 v112, v108, v112
	v_add_f32_e32 v112, v109, v112
	v_cvt_pk_bf16_f32 v136, v104, v105
	v_cvt_pk_bf16_f32 v137, v106, v107
	ds_read_b64_tr_b16 v[104:105], v203 offset:29696
	ds_read_b64_tr_b16 v[106:107], v203 offset:30208
	s_waitcnt lgkmcnt(12)
	v_mfma_f32_32x32x16_bf16 v[48:63], v[120:123], v[152:155], v[48:63]
	v_add_f32_e32 v112, v110, v112
	v_add_f32_e32 v112, v111, v112
	v_add_f32_e32 v112, v80, v112
	v_add_f32_e32 v112, v81, v112
	v_cvt_pk_bf16_f32 v138, v108, v109
	v_cvt_pk_bf16_f32 v139, v110, v111
	ds_read_b64_tr_b16 v[108:109], v203 offset:26624
	ds_read_b64_tr_b16 v[110:111], v203 offset:27136
	s_waitcnt lgkmcnt(13)
	v_mfma_f32_32x32x16_bf16 v[64:79], v[124:127], v[148:151], v[64:79]
	v_add_f32_e32 v112, v82, v112
	v_add_f32_e32 v112, v83, v112
	v_add_f32_e32 v112, v84, v112
	v_add_f32_e32 v112, v85, v112
	v_cvt_pk_bf16_f32 v132, v80, v81
	v_cvt_pk_bf16_f32 v133, v82, v83
	ds_read_b64_tr_b16 v[194:195], v203 offset:30720
	ds_read_b64_tr_b16 v[196:197], v203 offset:31232
	s_waitcnt lgkmcnt(14)
	v_mfma_f32_32x32x16_bf16 v[48:63], v[160:163], v[148:151], v[48:63]
	v_add_f32_e32 v80, v86, v112
	v_add_f32_e32 v80, v87, v80
	v_add_f32_e32 v80, v88, v80
	v_add_f32_e32 v80, v89, v80
	v_cvt_pk_bf16_f32 v134, v84, v85
	v_cvt_pk_bf16_f32 v135, v86, v87
	ds_read_b64_tr_b16 v[198:199], v203 offset:27648
	ds_read_b64_tr_b16 v[200:201], v203 offset:28160
	s_waitcnt lgkmcnt(14)
	v_mfma_f32_32x32x16_bf16 v[64:79], v[164:167], v[144:147], v[64:79]
	v_add_f32_e32 v80, v90, v80
	v_add_f32_e32 v80, v91, v80
	v_add_f32_e32 v80, v92, v80
	v_add_f32_e32 v80, v93, v80
	v_cvt_pk_bf16_f32 v128, v88, v89
	v_cvt_pk_bf16_f32 v129, v90, v91
	ds_read_b64_tr_b16 v[88:89], v203 offset:31744
	ds_read_b64_tr_b16 v[90:91], v203 offset:32256
	v_mfma_f32_32x32x16_bf16 v[48:63], v[186:189], v[144:147], v[48:63]
	v_add_f32_e32 v80, v94, v80
	v_add_f32_e32 v80, v95, v80
	v_add_f32_e32 v80, 0, v80
	v_cvt_pk_bf16_f32 v130, v92, v93
	v_cvt_pk_bf16_f32 v131, v94, v95
	s_add_i32 s52, s35, s33
	s_mov_b32 s54, m0
	s_mov_b32 m0, s52
	s_nop 0
	global_load_lds_dwordx4 v[176:177], off
	s_mov_b32 m0, s54
	s_add_i32 s52, s53, s16
	s_mov_b32 s54, m0
	s_mov_b32 m0, s52
	s_nop 0
	global_load_lds_dwordx4 v[174:175], off
	s_mov_b32 m0, s54
	v_add_f32_e32 v186, v202, v80
	s_waitcnt lgkmcnt(14)
	v_mfma_f32_32x32x16_bf16 v[16:31], v[140:143], v[190:193], v[16:31]
	v_exp_f32_e32 v64, v64
	v_exp_f32_e32 v65, v65
	v_exp_f32_e32 v66, v66
	v_exp_f32_e32 v67, v67
	s_waitcnt lgkmcnt(12)
	v_mfma_f32_32x32x16_bf16 v[32:47], v[140:143], v[96:99], v[32:47]
	v_exp_f32_e32 v68, v68
	v_exp_f32_e32 v69, v69
	v_exp_f32_e32 v70, v70
	v_exp_f32_e32 v71, v71
	v_add_u32_e32 v242, s53, v234
	v_add_u32_e32 v243, s53, v235
	v_add_u32_e32 v244, s53, v236
	v_add_u32_e32 v245, s53, v237
	ds_read_b128 v[84:87], v242
	ds_read_b128 v[80:83], v242 offset:4096
	s_waitcnt lgkmcnt(12)
	v_mfma_f32_32x32x16_bf16 v[16:31], v[136:139], v[100:103], v[16:31]
	v_exp_f32_e32 v72, v72
	v_exp_f32_e32 v73, v73
	v_exp_f32_e32 v74, v74
	v_exp_f32_e32 v75, v75
	ds_read_b128 v[164:167], v243
	ds_read_b128 v[160:163], v243 offset:4096
	s_waitcnt lgkmcnt(12)
	v_mfma_f32_32x32x16_bf16 v[32:47], v[136:139], v[104:107], v[32:47]
	v_exp_f32_e32 v76, v76
	v_exp_f32_e32 v77, v77
	v_exp_f32_e32 v78, v78
	v_exp_f32_e32 v79, v79
	ds_read_b128 v[124:127], v244
	ds_read_b128 v[120:123], v244 offset:4096
	s_waitcnt lgkmcnt(12)
	v_mfma_f32_32x32x16_bf16 v[16:31], v[132:135], v[108:111], v[16:31]
	v_exp_f32_e32 v48, v48
	v_exp_f32_e32 v49, v49
	v_exp_f32_e32 v50, v50
	v_exp_f32_e32 v51, v51
	ds_read_b128 v[116:119], v245
	ds_read_b128 v[112:115], v245 offset:4096
	s_waitcnt lgkmcnt(12)
	v_mfma_f32_32x32x16_bf16 v[32:47], v[132:135], v[194:197], v[32:47]
	v_exp_f32_e32 v52, v52
	v_exp_f32_e32 v53, v53
	v_exp_f32_e32 v54, v54
	v_exp_f32_e32 v55, v55
	s_waitcnt lgkmcnt(10)
	v_mfma_f32_32x32x16_bf16 v[16:31], v[128:131], v[198:201], v[16:31]
	v_exp_f32_e32 v56, v56
	v_exp_f32_e32 v57, v57
	v_exp_f32_e32 v58, v58
	v_exp_f32_e32 v59, v59
	s_waitcnt lgkmcnt(8)
	v_mfma_f32_32x32x16_bf16 v[32:47], v[128:131], v[88:91], v[32:47]
	v_exp_f32_e32 v60, v60
	v_exp_f32_e32 v61, v61
	v_exp_f32_e32 v62, v62
	v_exp_f32_e32 v63, v63
	s_add_i32 s55, s53, 0x2000
	s_cmpk_lg_i32 s53, 0x4000
	s_mov_b32 s54, s35
	s_cselect_b32 s35, s55, 0
	s_add_i32 s34, s34, 2
	v_lshl_add_u64 v[174:175], v[174:175], 0, s[8:9]
	v_lshl_add_u64 v[176:177], v[176:177], 0, s[8:9]
	s_mov_b32 s52, s53
	s_cmpk_lt_u32 s34, 0x79
	s_waitcnt vmcnt(2) lgkmcnt(0)
	s_barrier
	s_cbranch_scc1 .LBB0_882
	s_and_b32 s29, s29, 0x3fffffc0
	s_lshl_b32 s29, s29, 2
	s_add_i32 s29, s29, 0
	s_cmp_lg_u32 0, -1
	s_cselect_b32 s34, 0, 0
	s_add_i32 s35, s34, 0x6000
	v_add3_u32 v174, v185, s35, v184
	ds_read_b64_tr_b16 v[188:189], v182 offset:40960
	ds_read_b64_tr_b16 v[190:191], v182 offset:41472
	v_add_f32_e32 v88, v64, v65
	v_add_f32_e32 v88, v66, v88
	v_add_f32_e32 v88, v67, v88
	v_add_f32_e32 v88, v68, v88
	v_add_f32_e32 v88, v69, v88
	v_cvt_pk_bf16_f32 v140, v64, v65
	v_cvt_pk_bf16_f32 v141, v66, v67
	s_waitcnt lgkmcnt(9)
	v_mfma_f32_32x32x16_bf16 v[96:111], v[84:87], v[156:159], 0
	ds_read_b64_tr_b16 v[64:65], v182 offset:45056
	ds_read_b64_tr_b16 v[66:67], v182 offset:45568
	v_add_f32_e32 v84, v70, v88
	v_add_f32_e32 v84, v71, v84
	v_add_f32_e32 v84, v72, v84
	v_add_f32_e32 v128, v73, v84
	v_cvt_pk_bf16_f32 v142, v68, v69
	v_cvt_pk_bf16_f32 v143, v70, v71
	s_waitcnt lgkmcnt(10)
	v_mfma_f32_32x32x16_bf16 v[80:95], v[80:83], v[156:159], 0
	ds_read_b64_tr_b16 v[68:69], v182 offset:41984
	ds_read_b64_tr_b16 v[70:71], v182 offset:42496
	v_add_f32_e32 v128, v74, v128
	v_add_f32_e32 v128, v75, v128
	v_add_f32_e32 v128, v76, v128
	v_add_f32_e32 v128, v77, v128
	v_cvt_pk_bf16_f32 v136, v72, v73
	v_cvt_pk_bf16_f32 v137, v74, v75
	s_waitcnt lgkmcnt(11)
	v_mfma_f32_32x32x16_bf16 v[96:111], v[164:167], v[152:155], v[96:111]
	ds_read_b64_tr_b16 v[72:73], v182 offset:46080
	ds_read_b64_tr_b16 v[74:75], v182 offset:46592
	v_add_f32_e32 v128, v78, v128
	v_add_f32_e32 v128, v79, v128
	v_add_f32_e32 v128, v48, v128
	v_add_f32_e32 v128, v49, v128
	v_cvt_pk_bf16_f32 v138, v76, v77
	v_cvt_pk_bf16_f32 v139, v78, v79
	s_waitcnt lgkmcnt(12)
	v_mfma_f32_32x32x16_bf16 v[80:95], v[160:163], v[152:155], v[80:95]
	ds_read_b64_tr_b16 v[76:77], v182 offset:43008
	ds_read_b64_tr_b16 v[78:79], v182 offset:43520
	v_add_f32_e32 v128, v50, v128
	v_add_f32_e32 v128, v51, v128
	v_add_f32_e32 v128, v52, v128
	v_add_f32_e32 v128, v53, v128
	v_cvt_pk_bf16_f32 v132, v48, v49
	v_cvt_pk_bf16_f32 v133, v50, v51
	s_waitcnt lgkmcnt(13)
	v_mfma_f32_32x32x16_bf16 v[96:111], v[124:127], v[148:151], v[96:111]
	ds_read_b64_tr_b16 v[48:49], v182 offset:47104
	ds_read_b64_tr_b16 v[50:51], v182 offset:47616
	v_add_f32_e32 v124, v54, v128
	v_add_f32_e32 v124, v55, v124
	v_add_f32_e32 v124, v56, v124
	v_add_f32_e32 v124, v57, v124
	v_cvt_pk_bf16_f32 v134, v52, v53
	v_cvt_pk_bf16_f32 v135, v54, v55
	s_waitcnt lgkmcnt(14)
	v_mfma_f32_32x32x16_bf16 v[80:95], v[120:123], v[148:151], v[80:95]
	ds_read_b64_tr_b16 v[52:53], v182 offset:44032
	ds_read_b64_tr_b16 v[54:55], v182 offset:44544
	v_add_f32_e32 v120, v58, v124
	v_add_f32_e32 v120, v59, v120
	v_add_f32_e32 v120, v60, v120
	v_add_f32_e32 v120, v61, v120
	v_cvt_pk_bf16_f32 v128, v56, v57
	v_cvt_pk_bf16_f32 v129, v58, v59
	s_waitcnt lgkmcnt(14)
	v_mfma_f32_32x32x16_bf16 v[96:111], v[116:119], v[144:147], v[96:111]
	ds_read_b64_tr_b16 v[56:57], v182 offset:48128
	ds_read_b64_tr_b16 v[58:59], v182 offset:48640
	v_add_f32_e32 v116, v62, v120
	v_add_f32_e32 v116, v63, v116
	v_add_f32_e32 v116, 0, v116
	v_cvt_pk_bf16_f32 v130, v60, v61
	v_cvt_pk_bf16_f32 v131, v62, v63
	v_mfma_f32_32x32x16_bf16 v[80:95], v[112:115], v[144:147], v[80:95]
	v_lshl_add_u64 v[60:61], v[172:173], 0, s[40:41]
	s_mov_b32 s35, m0
	s_mov_b32 m0, s33
	s_nop 0
	global_load_lds_dwordx4 v[60:61], off
	s_mov_b32 m0, s35
	s_add_i32 s33, s34, s17
	v_lshl_add_u64 v[60:61], v[170:171], 0, s[42:43]
	s_add_i32 s17, s33, 0x8000
	s_mov_b32 s34, m0
	s_mov_b32 m0, s17
	s_nop 0
	global_load_lds_dwordx4 v[60:61], off
	s_mov_b32 m0, s34
	v_add_f32_e32 v175, v186, v116
	s_waitcnt lgkmcnt(14)
	v_mfma_f32_32x32x16_bf16 v[16:31], v[140:143], v[188:191], v[16:31]
	v_exp_f32_e32 v96, v96
	v_exp_f32_e32 v97, v97
	v_exp_f32_e32 v98, v98
	v_exp_f32_e32 v99, v99
	s_waitcnt lgkmcnt(12)
	v_mfma_f32_32x32x16_bf16 v[32:47], v[140:143], v[64:67], v[32:47]
	v_exp_f32_e32 v100, v100
	v_exp_f32_e32 v101, v101
	v_exp_f32_e32 v102, v102
	v_exp_f32_e32 v103, v103
	ds_read_b128 v[60:63], v234 offset:8192
	ds_read_b128 v[64:67], v234 offset:12288
	s_waitcnt lgkmcnt(12)
	v_mfma_f32_32x32x16_bf16 v[16:31], v[136:139], v[68:71], v[16:31]
	v_exp_f32_e32 v104, v104
	v_exp_f32_e32 v105, v105
	v_exp_f32_e32 v106, v106
	v_exp_f32_e32 v107, v107
	ds_read_b128 v[68:71], v235 offset:8192
	ds_read_b128 v[160:163], v235 offset:12288
	s_waitcnt lgkmcnt(12)
	v_mfma_f32_32x32x16_bf16 v[32:47], v[136:139], v[72:75], v[32:47]
	v_exp_f32_e32 v108, v108
	v_exp_f32_e32 v109, v109
	v_exp_f32_e32 v110, v110
	v_exp_f32_e32 v111, v111
	ds_read_b128 v[72:75], v236 offset:8192
	ds_read_b128 v[164:167], v236 offset:12288
	s_waitcnt lgkmcnt(12)
	v_mfma_f32_32x32x16_bf16 v[16:31], v[132:135], v[76:79], v[16:31]
	v_exp_f32_e32 v80, v80
	v_exp_f32_e32 v81, v81
	v_exp_f32_e32 v82, v82
	v_exp_f32_e32 v83, v83
	ds_read_b128 v[76:79], v237 offset:8192
	ds_read_b128 v[184:187], v237 offset:12288
	s_waitcnt lgkmcnt(12)
	v_mfma_f32_32x32x16_bf16 v[32:47], v[132:135], v[48:51], v[32:47]
	v_exp_f32_e32 v84, v84
	v_exp_f32_e32 v85, v85
	v_exp_f32_e32 v86, v86
	v_exp_f32_e32 v87, v87
	s_waitcnt lgkmcnt(10)
	v_mfma_f32_32x32x16_bf16 v[16:31], v[128:131], v[52:55], v[16:31]
	v_exp_f32_e32 v88, v88
	v_exp_f32_e32 v89, v89
	v_exp_f32_e32 v90, v90
	v_exp_f32_e32 v91, v91
	s_waitcnt lgkmcnt(8)
	v_mfma_f32_32x32x16_bf16 v[32:47], v[128:131], v[56:59], v[32:47]
	v_exp_f32_e32 v92, v92
	v_exp_f32_e32 v93, v93
	v_exp_f32_e32 v94, v94
	v_exp_f32_e32 v95, v95
	s_waitcnt vmcnt(2) lgkmcnt(0)
	s_barrier
	ds_read_b64_tr_b16 v[188:189], v182 offset:24576
	ds_read_b64_tr_b16 v[190:191], v182 offset:25088
	v_add_f32_e32 v48, v96, v97
	v_add_f32_e32 v48, v98, v48
	v_add_f32_e32 v48, v99, v48
	v_add_f32_e32 v48, v100, v48
	v_add_f32_e32 v48, v101, v48
	v_cvt_pk_bf16_f32 v140, v96, v97
	v_cvt_pk_bf16_f32 v141, v98, v99
	s_waitcnt lgkmcnt(9)
	v_mfma_f32_32x32x16_bf16 v[112:127], v[60:63], v[156:159], 0
	ds_read_b64_tr_b16 v[96:97], v182 offset:28672
	ds_read_b64_tr_b16 v[98:99], v182 offset:29184
	v_add_f32_e32 v48, v102, v48
	v_add_f32_e32 v48, v103, v48
	v_add_f32_e32 v48, v104, v48
	v_add_f32_e32 v128, v105, v48
	s_waitcnt lgkmcnt(10)
	v_mfma_f32_32x32x16_bf16 v[48:63], v[64:67], v[156:159], 0
	v_cvt_pk_bf16_f32 v142, v100, v101
	v_cvt_pk_bf16_f32 v143, v102, v103
	ds_read_b64_tr_b16 v[64:65], v182 offset:25600
	ds_read_b64_tr_b16 v[66:67], v182 offset:26112
	v_add_f32_e32 v100, v106, v128
	v_add_f32_e32 v100, v107, v100
	v_add_f32_e32 v100, v108, v100
	v_add_f32_e32 v100, v109, v100
	v_cvt_pk_bf16_f32 v136, v104, v105
	v_cvt_pk_bf16_f32 v137, v106, v107
	s_waitcnt lgkmcnt(11)
	v_mfma_f32_32x32x16_bf16 v[112:127], v[68:71], v[152:155], v[112:127]
	ds_read_b64_tr_b16 v[68:69], v182 offset:29696
	ds_read_b64_tr_b16 v[70:71], v182 offset:30208
	s_waitcnt lgkmcnt(12)
	v_mfma_f32_32x32x16_bf16 v[48:63], v[160:163], v[152:155], v[48:63]
	v_add_f32_e32 v100, v110, v100
	v_add_f32_e32 v100, v111, v100
	v_add_f32_e32 v100, v80, v100
	v_add_f32_e32 v104, v81, v100
	v_cvt_pk_bf16_f32 v138, v108, v109
	v_cvt_pk_bf16_f32 v139, v110, v111
	ds_read_b64_tr_b16 v[100:101], v182 offset:26624
	ds_read_b64_tr_b16 v[102:103], v182 offset:27136
	v_add_f32_e32 v104, v82, v104
	v_add_f32_e32 v104, v83, v104
	v_add_f32_e32 v104, v84, v104
	v_add_f32_e32 v104, v85, v104
	v_cvt_pk_bf16_f32 v132, v80, v81
	v_cvt_pk_bf16_f32 v133, v82, v83
	s_waitcnt lgkmcnt(13)
	v_mfma_f32_32x32x16_bf16 v[112:127], v[72:75], v[148:151], v[112:127]
	ds_read_b64_tr_b16 v[72:73], v182 offset:30720
	ds_read_b64_tr_b16 v[74:75], v182 offset:31232
	s_waitcnt lgkmcnt(14)
	v_mfma_f32_32x32x16_bf16 v[48:63], v[164:167], v[148:151], v[48:63]
	v_add_f32_e32 v80, v86, v104
	v_add_f32_e32 v80, v87, v80
	v_add_f32_e32 v80, v88, v80
	v_add_f32_e32 v104, v89, v80
	v_cvt_pk_bf16_f32 v134, v84, v85
	v_cvt_pk_bf16_f32 v135, v86, v87
	ds_read_b64_tr_b16 v[80:81], v182 offset:27648
	ds_read_b64_tr_b16 v[82:83], v182 offset:28160
	v_add_f32_e32 v84, v90, v104
	v_add_f32_e32 v84, v91, v84
	v_add_f32_e32 v84, v92, v84
	v_add_f32_e32 v84, v93, v84
	v_cvt_pk_bf16_f32 v128, v88, v89
	v_cvt_pk_bf16_f32 v129, v90, v91
	s_waitcnt lgkmcnt(14)
	v_mfma_f32_32x32x16_bf16 v[112:127], v[76:79], v[144:147], v[112:127]
	ds_read_b64_tr_b16 v[76:77], v182 offset:31744
	ds_read_b64_tr_b16 v[78:79], v182 offset:32256
	v_mfma_f32_32x32x16_bf16 v[48:63], v[184:187], v[144:147], v[48:63]
	v_add_f32_e32 v84, v94, v84
	v_add_f32_e32 v84, v95, v84
	v_add_f32_e32 v84, 0, v84
	v_cvt_pk_bf16_f32 v130, v92, v93
	v_cvt_pk_bf16_f32 v131, v94, v95
	s_nop 0
	v_add_f32_e32 v175, v175, v84
	v_lshl_add_u64 v[84:85], v[172:173], 0, s[44:45]
	s_add_i32 s34, s33, 0x2000
	s_mov_b32 s35, m0
	s_mov_b32 m0, s34
	s_nop 0
	global_load_lds_dwordx4 v[84:85], off
	s_mov_b32 m0, s35
	v_lshl_add_u64 v[84:85], v[170:171], 0, s[48:49]
	s_add_i32 s33, s33, 0xa000
	s_mov_b32 s34, m0
	s_mov_b32 m0, s33
	s_nop 0
	global_load_lds_dwordx4 v[84:85], off
	s_mov_b32 m0, s34
	s_waitcnt lgkmcnt(14)
	v_mfma_f32_32x32x16_bf16 v[16:31], v[140:143], v[188:191], v[16:31]
	v_exp_f32_e32 v112, v112
	v_exp_f32_e32 v113, v113
	v_exp_f32_e32 v114, v114
	v_exp_f32_e32 v115, v115
	s_waitcnt lgkmcnt(12)
	v_mfma_f32_32x32x16_bf16 v[32:47], v[140:143], v[96:99], v[32:47]
	v_exp_f32_e32 v116, v116
	v_exp_f32_e32 v117, v117
	v_exp_f32_e32 v118, v118
	v_exp_f32_e32 v119, v119
	ds_read_b128 v[84:87], v234 offset:16384
	ds_read_b128 v[96:99], v234 offset:20480
	s_waitcnt lgkmcnt(12)
	v_mfma_f32_32x32x16_bf16 v[16:31], v[136:139], v[64:67], v[16:31]
	v_exp_f32_e32 v120, v120
	v_exp_f32_e32 v121, v121
	v_exp_f32_e32 v122, v122
	v_exp_f32_e32 v123, v123
	ds_read_b128 v[104:107], v235 offset:16384
	ds_read_b128 v[108:111], v235 offset:20480
	s_waitcnt lgkmcnt(12)
	v_mfma_f32_32x32x16_bf16 v[32:47], v[136:139], v[68:71], v[32:47]
	v_exp_f32_e32 v124, v124
	v_exp_f32_e32 v125, v125
	v_exp_f32_e32 v126, v126
	v_exp_f32_e32 v127, v127
	ds_read_b128 v[160:163], v236 offset:16384
	ds_read_b128 v[164:167], v236 offset:20480
	s_waitcnt lgkmcnt(12)
	v_mfma_f32_32x32x16_bf16 v[16:31], v[132:135], v[100:103], v[16:31]
	v_exp_f32_e32 v48, v48
	v_exp_f32_e32 v49, v49
	v_exp_f32_e32 v50, v50
	v_exp_f32_e32 v51, v51
	ds_read_b128 v[100:103], v237 offset:16384
	ds_read_b128 v[184:187], v237 offset:20480
	s_waitcnt lgkmcnt(12)
	v_mfma_f32_32x32x16_bf16 v[32:47], v[132:135], v[72:75], v[32:47]
	v_exp_f32_e32 v52, v52
	v_exp_f32_e32 v53, v53
	v_exp_f32_e32 v54, v54
	v_exp_f32_e32 v55, v55
	s_waitcnt lgkmcnt(10)
	v_mfma_f32_32x32x16_bf16 v[16:31], v[128:131], v[80:83], v[16:31]
	v_exp_f32_e32 v56, v56
	v_exp_f32_e32 v57, v57
	v_exp_f32_e32 v58, v58
	v_exp_f32_e32 v59, v59
	s_waitcnt lgkmcnt(8)
	v_mfma_f32_32x32x16_bf16 v[32:47], v[128:131], v[76:79], v[32:47]
	v_exp_f32_e32 v60, v60
	v_exp_f32_e32 v61, v61
	v_exp_f32_e32 v62, v62
	v_exp_f32_e32 v63, v63
	s_waitcnt vmcnt(2) lgkmcnt(0)
	s_barrier
	ds_read_b64_tr_b16 v[188:189], v182 offset:32768
	ds_read_b64_tr_b16 v[190:191], v182 offset:33280
	v_add_f32_e32 v64, v112, v113
	v_add_f32_e32 v64, v114, v64
	v_add_f32_e32 v64, v115, v64
	v_add_f32_e32 v64, v116, v64
	v_add_f32_e32 v64, v117, v64
	v_cvt_pk_bf16_f32 v140, v112, v113
	v_cvt_pk_bf16_f32 v141, v114, v115
	s_waitcnt lgkmcnt(9)
	v_mfma_f32_32x32x16_bf16 v[80:95], v[84:87], v[156:159], 0
	ds_read_b64_tr_b16 v[112:113], v182 offset:36864
	ds_read_b64_tr_b16 v[114:115], v182 offset:37376
	v_add_f32_e32 v64, v118, v64
	v_add_f32_e32 v64, v119, v64
	v_add_f32_e32 v64, v120, v64
	v_add_f32_e32 v128, v121, v64
	v_cvt_pk_bf16_f32 v142, v116, v117
	v_cvt_pk_bf16_f32 v143, v118, v119
	s_waitcnt lgkmcnt(10)
	v_mfma_f32_32x32x16_bf16 v[64:79], v[96:99], v[156:159], 0
	ds_read_b64_tr_b16 v[96:97], v182 offset:33792
	ds_read_b64_tr_b16 v[98:99], v182 offset:34304
	v_add_f32_e32 v116, v122, v128
	v_add_f32_e32 v116, v123, v116
	v_add_f32_e32 v116, v124, v116
	v_add_f32_e32 v116, v125, v116
	v_cvt_pk_bf16_f32 v136, v120, v121
	v_cvt_pk_bf16_f32 v137, v122, v123
	s_waitcnt lgkmcnt(11)
	v_mfma_f32_32x32x16_bf16 v[80:95], v[104:107], v[152:155], v[80:95]
	ds_read_b64_tr_b16 v[104:105], v182 offset:37888
	ds_read_b64_tr_b16 v[106:107], v182 offset:38400
	v_add_f32_e32 v116, v126, v116
	v_add_f32_e32 v116, v127, v116
	v_add_f32_e32 v116, v48, v116
	v_add_f32_e32 v116, v49, v116
	v_cvt_pk_bf16_f32 v138, v124, v125
	v_cvt_pk_bf16_f32 v139, v126, v127
	s_waitcnt lgkmcnt(12)
	v_mfma_f32_32x32x16_bf16 v[64:79], v[108:111], v[152:155], v[64:79]
	ds_read_b64_tr_b16 v[108:109], v182 offset:34816
	ds_read_b64_tr_b16 v[110:111], v182 offset:35328
	v_add_f32_e32 v116, v50, v116
	v_add_f32_e32 v116, v51, v116
	v_add_f32_e32 v116, v52, v116
	v_add_f32_e32 v116, v53, v116
	v_cvt_pk_bf16_f32 v132, v48, v49
	v_cvt_pk_bf16_f32 v133, v50, v51
	s_waitcnt lgkmcnt(13)
	v_mfma_f32_32x32x16_bf16 v[80:95], v[160:163], v[148:151], v[80:95]
	ds_read_b64_tr_b16 v[48:49], v182 offset:38912
	ds_read_b64_tr_b16 v[50:51], v182 offset:39424
	v_add_f32_e32 v116, v54, v116
	v_add_f32_e32 v116, v55, v116
	v_add_f32_e32 v116, v56, v116
	v_add_f32_e32 v116, v57, v116
	v_cvt_pk_bf16_f32 v134, v52, v53
	v_cvt_pk_bf16_f32 v135, v54, v55
	s_waitcnt lgkmcnt(14)
	v_mfma_f32_32x32x16_bf16 v[64:79], v[164:167], v[148:151], v[64:79]
	ds_read_b64_tr_b16 v[52:53], v182 offset:35840
	ds_read_b64_tr_b16 v[54:55], v182 offset:36352
	v_add_f32_e32 v116, v58, v116
	v_add_f32_e32 v116, v59, v116
	v_add_f32_e32 v116, v60, v116
	v_add_f32_e32 v116, v61, v116
	v_cvt_pk_bf16_f32 v128, v56, v57
	v_cvt_pk_bf16_f32 v129, v58, v59
	s_waitcnt lgkmcnt(14)
	v_mfma_f32_32x32x16_bf16 v[80:95], v[100:103], v[144:147], v[80:95]
	ds_read_b64_tr_b16 v[56:57], v182 offset:39936
	ds_read_b64_tr_b16 v[58:59], v182 offset:40448
	v_add_f32_e32 v100, v62, v116
	v_add_f32_e32 v100, v63, v100
	v_add_f32_e32 v100, 0, v100
	v_cvt_pk_bf16_f32 v130, v60, v61
	v_cvt_pk_bf16_f32 v131, v62, v63
	v_mfma_f32_32x32x16_bf16 v[64:79], v[184:187], v[144:147], v[64:79]
	v_lshl_add_u64 v[60:61], v[170:171], 0, s[40:41]
	s_mov_b32 s33, m0
	s_mov_b32 m0, s16
	s_nop 0
	global_load_lds_dwordx4 v[60:61], off
	s_mov_b32 m0, s33
	v_add_f32_e32 v172, v175, v100
	s_waitcnt lgkmcnt(14)
	v_mfma_f32_32x32x16_bf16 v[16:31], v[140:143], v[188:191], v[16:31]
	v_exp_f32_e32 v80, v80
	v_exp_f32_e32 v81, v81
	v_exp_f32_e32 v82, v82
	v_exp_f32_e32 v83, v83
	s_waitcnt lgkmcnt(12)
	v_mfma_f32_32x32x16_bf16 v[32:47], v[140:143], v[112:115], v[32:47]
	v_exp_f32_e32 v84, v84
	v_exp_f32_e32 v85, v85
	v_exp_f32_e32 v86, v86
	v_exp_f32_e32 v87, v87
	ds_read_b128 v[60:63], v234
	ds_read_b128 v[112:115], v234 offset:4096
	s_waitcnt lgkmcnt(12)
	v_mfma_f32_32x32x16_bf16 v[16:31], v[136:139], v[96:99], v[16:31]
	v_exp_f32_e32 v88, v88
	v_exp_f32_e32 v89, v89
	v_exp_f32_e32 v90, v90
	v_exp_f32_e32 v91, v91
	ds_read_b128 v[116:119], v235
	ds_read_b128 v[120:123], v235 offset:4096
	s_waitcnt lgkmcnt(12)
	v_mfma_f32_32x32x16_bf16 v[32:47], v[136:139], v[104:107], v[32:47]
	v_exp_f32_e32 v92, v92
	v_exp_f32_e32 v93, v93
	v_exp_f32_e32 v94, v94
	v_exp_f32_e32 v95, v95
	ds_read_b128 v[124:127], v236
	ds_read_b128 v[160:163], v236 offset:4096
	s_waitcnt lgkmcnt(12)
	v_mfma_f32_32x32x16_bf16 v[16:31], v[132:135], v[108:111], v[16:31]
	v_exp_f32_e32 v64, v64
	v_exp_f32_e32 v65, v65
	v_exp_f32_e32 v66, v66
	v_exp_f32_e32 v67, v67
	ds_read_b128 v[164:167], v237
	ds_read_b128 v[184:187], v237 offset:4096
	s_waitcnt lgkmcnt(12)
	v_mfma_f32_32x32x16_bf16 v[32:47], v[132:135], v[48:51], v[32:47]
	v_exp_f32_e32 v68, v68
	v_exp_f32_e32 v69, v69
	v_exp_f32_e32 v70, v70
	v_exp_f32_e32 v71, v71
	s_waitcnt lgkmcnt(10)
	v_mfma_f32_32x32x16_bf16 v[16:31], v[128:131], v[52:55], v[16:31]
	v_exp_f32_e32 v72, v72
	v_exp_f32_e32 v73, v73
	v_exp_f32_e32 v74, v74
	v_exp_f32_e32 v75, v75
	s_waitcnt lgkmcnt(8)
	v_mfma_f32_32x32x16_bf16 v[32:47], v[128:131], v[56:59], v[32:47]
	v_exp_f32_e32 v76, v76
	v_exp_f32_e32 v77, v77
	v_exp_f32_e32 v78, v78
	v_exp_f32_e32 v79, v79
	s_waitcnt vmcnt(1) lgkmcnt(0)
	s_barrier
	ds_read_b64_tr_b16 v[188:189], v182 offset:40960
	ds_read_b64_tr_b16 v[190:191], v182 offset:41472
	v_add_f32_e32 v48, v80, v81
	v_add_f32_e32 v48, v82, v48
	v_add_f32_e32 v48, v83, v48
	v_add_f32_e32 v48, v84, v48
	v_add_f32_e32 v48, v85, v48
	v_cvt_pk_bf16_f32 v140, v80, v81
	v_cvt_pk_bf16_f32 v141, v82, v83
	s_waitcnt lgkmcnt(9)
	v_mfma_f32_32x32x16_bf16 v[96:111], v[60:63], v[156:159], 0
	ds_read_b64_tr_b16 v[80:81], v182 offset:45056
	ds_read_b64_tr_b16 v[82:83], v182 offset:45568
	v_add_f32_e32 v48, v86, v48
	v_add_f32_e32 v48, v87, v48
	v_add_f32_e32 v48, v88, v48
	v_add_f32_e32 v128, v89, v48
	s_waitcnt lgkmcnt(10)
	v_mfma_f32_32x32x16_bf16 v[48:63], v[112:115], v[156:159], 0
	v_cvt_pk_bf16_f32 v142, v84, v85
	v_cvt_pk_bf16_f32 v143, v86, v87
	ds_read_b64_tr_b16 v[84:85], v182 offset:41984
	ds_read_b64_tr_b16 v[86:87], v182 offset:42496
	v_add_f32_e32 v112, v90, v128
	v_add_f32_e32 v112, v91, v112
	v_add_f32_e32 v112, v92, v112
	v_add_f32_e32 v112, v93, v112
	v_cvt_pk_bf16_f32 v136, v88, v89
	v_cvt_pk_bf16_f32 v137, v90, v91
	s_waitcnt lgkmcnt(11)
	v_mfma_f32_32x32x16_bf16 v[96:111], v[116:119], v[152:155], v[96:111]
	ds_read_b64_tr_b16 v[88:89], v182 offset:46080
	ds_read_b64_tr_b16 v[90:91], v182 offset:46592
	s_waitcnt lgkmcnt(12)
	v_mfma_f32_32x32x16_bf16 v[48:63], v[120:123], v[152:155], v[48:63]
	v_add_f32_e32 v112, v94, v112
	v_add_f32_e32 v112, v95, v112
	v_add_f32_e32 v112, v64, v112
	v_add_f32_e32 v112, v65, v112
	v_cvt_pk_bf16_f32 v138, v92, v93
	v_cvt_pk_bf16_f32 v139, v94, v95
	ds_read_b64_tr_b16 v[92:93], v182 offset:43008
	ds_read_b64_tr_b16 v[94:95], v182 offset:43520
	v_add_f32_e32 v112, v66, v112
	v_add_f32_e32 v112, v67, v112
	v_add_f32_e32 v112, v68, v112
	v_add_f32_e32 v112, v69, v112
	v_cvt_pk_bf16_f32 v132, v64, v65
	v_cvt_pk_bf16_f32 v133, v66, v67
	s_waitcnt lgkmcnt(13)
	v_mfma_f32_32x32x16_bf16 v[96:111], v[124:127], v[148:151], v[96:111]
	ds_read_b64_tr_b16 v[64:65], v182 offset:47104
	ds_read_b64_tr_b16 v[66:67], v182 offset:47616
	s_waitcnt lgkmcnt(14)
	v_mfma_f32_32x32x16_bf16 v[48:63], v[160:163], v[148:151], v[48:63]
	v_add_f32_e32 v112, v70, v112
	v_add_f32_e32 v112, v71, v112
	v_add_f32_e32 v112, v72, v112
	v_add_f32_e32 v112, v73, v112
	v_cvt_pk_bf16_f32 v134, v68, v69
	v_cvt_pk_bf16_f32 v135, v70, v71
	ds_read_b64_tr_b16 v[68:69], v182 offset:44032
	ds_read_b64_tr_b16 v[70:71], v182 offset:44544
	v_add_f32_e32 v112, v74, v112
	v_add_f32_e32 v112, v75, v112
	v_add_f32_e32 v112, v76, v112
	v_add_f32_e32 v112, v77, v112
	v_cvt_pk_bf16_f32 v128, v72, v73
	v_cvt_pk_bf16_f32 v129, v74, v75
	s_waitcnt lgkmcnt(14)
	v_mfma_f32_32x32x16_bf16 v[96:111], v[164:167], v[144:147], v[96:111]
	ds_read_b64_tr_b16 v[72:73], v182 offset:48128
	ds_read_b64_tr_b16 v[74:75], v182 offset:48640
	v_mfma_f32_32x32x16_bf16 v[48:63], v[184:187], v[144:147], v[48:63]
	v_add_f32_e32 v112, v78, v112
	v_add_f32_e32 v112, v79, v112
	v_add_f32_e32 v112, 0, v112
	v_cvt_pk_bf16_f32 v130, v76, v77
	v_cvt_pk_bf16_f32 v131, v78, v79
	v_lshl_add_u64 v[76:77], v[170:171], 0, s[44:45]
	s_mov_b32 s16, m0
	s_mov_b32 m0, s17
	s_nop 0
	global_load_lds_dwordx4 v[76:77], off
	s_mov_b32 m0, s16
	v_add_f32_e32 v120, v172, v112
	s_waitcnt lgkmcnt(14)
	v_mfma_f32_32x32x16_bf16 v[16:31], v[140:143], v[188:191], v[16:31]
	v_exp_f32_e32 v96, v96
	v_exp_f32_e32 v97, v97
	v_exp_f32_e32 v98, v98
	v_exp_f32_e32 v99, v99
	s_waitcnt lgkmcnt(12)
	v_mfma_f32_32x32x16_bf16 v[32:47], v[140:143], v[80:83], v[32:47]
	v_exp_f32_e32 v100, v100
	v_exp_f32_e32 v101, v101
	v_exp_f32_e32 v102, v102
	v_exp_f32_e32 v103, v103
	ds_read_b128 v[76:79], v234 offset:8192
	ds_read_b128 v[80:83], v234 offset:12288
	s_waitcnt lgkmcnt(12)
	v_mfma_f32_32x32x16_bf16 v[16:31], v[136:139], v[84:87], v[16:31]
	v_exp_f32_e32 v104, v104
	v_exp_f32_e32 v105, v105
	v_exp_f32_e32 v106, v106
	v_exp_f32_e32 v107, v107
	ds_read_b128 v[122:125], v235 offset:8192
	ds_read_b128 v[160:163], v235 offset:12288
	s_waitcnt lgkmcnt(12)
	v_mfma_f32_32x32x16_bf16 v[32:47], v[136:139], v[88:91], v[32:47]
	v_exp_f32_e32 v108, v108
	v_exp_f32_e32 v109, v109
	v_exp_f32_e32 v110, v110
	v_exp_f32_e32 v111, v111
	ds_read_b128 v[164:167], v236 offset:8192
	ds_read_b128 v[170:173], v236 offset:12288
	s_waitcnt lgkmcnt(12)
	v_mfma_f32_32x32x16_bf16 v[16:31], v[132:135], v[92:95], v[16:31]
	v_exp_f32_e32 v48, v48
	v_exp_f32_e32 v49, v49
	v_exp_f32_e32 v50, v50
	v_exp_f32_e32 v51, v51
	ds_read_b128 v[184:187], v237 offset:8192
	ds_read_b128 v[188:191], v237 offset:12288
	s_waitcnt lgkmcnt(12)
	v_mfma_f32_32x32x16_bf16 v[32:47], v[132:135], v[64:67], v[32:47]
	v_exp_f32_e32 v52, v52
	v_exp_f32_e32 v53, v53
	v_exp_f32_e32 v54, v54
	v_exp_f32_e32 v55, v55
	s_waitcnt lgkmcnt(10)
	v_mfma_f32_32x32x16_bf16 v[16:31], v[128:131], v[68:71], v[16:31]
	v_exp_f32_e32 v56, v56
	v_exp_f32_e32 v57, v57
	v_exp_f32_e32 v58, v58
	v_exp_f32_e32 v59, v59
	s_waitcnt lgkmcnt(8)
	v_mfma_f32_32x32x16_bf16 v[32:47], v[128:131], v[72:75], v[32:47]
	v_exp_f32_e32 v60, v60
	v_exp_f32_e32 v61, v61
	v_exp_f32_e32 v62, v62
	v_exp_f32_e32 v63, v63
	s_waitcnt vmcnt(0) lgkmcnt(0)
	s_barrier
	ds_read_b64_tr_b16 v[112:113], v182 offset:24576
	ds_read_b64_tr_b16 v[114:115], v182 offset:25088
	v_add_f32_e32 v64, v96, v97
	v_add_f32_e32 v64, v98, v64
	v_add_f32_e32 v64, v99, v64
	v_add_f32_e32 v64, v100, v64
	v_add_f32_e32 v84, v101, v64
	v_cvt_pk_bf16_f32 v140, v96, v97
	v_cvt_pk_bf16_f32 v141, v98, v99
	s_waitcnt lgkmcnt(9)
	v_mfma_f32_32x32x16_bf16 v[64:79], v[76:79], v[156:159], 0
	ds_read_b64_tr_b16 v[96:97], v182 offset:28672
	ds_read_b64_tr_b16 v[98:99], v182 offset:29184
	v_add_f32_e32 v84, v102, v84
	v_add_f32_e32 v84, v103, v84
	v_add_f32_e32 v84, v104, v84
	v_add_f32_e32 v121, v105, v84
	v_cvt_pk_bf16_f32 v142, v100, v101
	v_cvt_pk_bf16_f32 v143, v102, v103
	s_waitcnt lgkmcnt(10)
	v_mfma_f32_32x32x16_bf16 v[80:95], v[80:83], v[156:159], 0
	ds_read_b64_tr_b16 v[116:117], v182 offset:25600
	ds_read_b64_tr_b16 v[118:119], v182 offset:26112
	v_add_f32_e32 v100, v106, v121
	v_add_f32_e32 v100, v107, v100
	v_add_f32_e32 v100, v108, v100
	v_add_f32_e32 v121, v109, v100
	v_cvt_pk_bf16_f32 v136, v104, v105
	v_cvt_pk_bf16_f32 v137, v106, v107
	s_waitcnt lgkmcnt(11)
	v_mfma_f32_32x32x16_bf16 v[64:79], v[122:125], v[152:155], v[64:79]
	ds_read_b64_tr_b16 v[100:101], v182 offset:29696
	ds_read_b64_tr_b16 v[102:103], v182 offset:30208
	v_add_f32_e32 v104, v110, v121
	v_add_f32_e32 v104, v111, v104
	v_add_f32_e32 v104, v48, v104
	v_add_f32_e32 v121, v49, v104
	v_cvt_pk_bf16_f32 v138, v108, v109
	v_cvt_pk_bf16_f32 v139, v110, v111
	s_waitcnt lgkmcnt(12)
	v_mfma_f32_32x32x16_bf16 v[80:95], v[160:163], v[152:155], v[80:95]
	ds_read_b64_tr_b16 v[104:105], v182 offset:26624
	ds_read_b64_tr_b16 v[106:107], v182 offset:27136
	v_add_f32_e32 v108, v50, v121
	v_add_f32_e32 v108, v51, v108
	v_add_f32_e32 v108, v52, v108
	v_add_f32_e32 v108, v53, v108
	v_cvt_pk_bf16_f32 v132, v48, v49
	v_cvt_pk_bf16_f32 v133, v50, v51
	s_waitcnt lgkmcnt(13)
	v_mfma_f32_32x32x16_bf16 v[64:79], v[164:167], v[148:151], v[64:79]
	ds_read_b64_tr_b16 v[48:49], v182 offset:30720
	ds_read_b64_tr_b16 v[50:51], v182 offset:31232
	v_add_f32_e32 v108, v54, v108
	v_add_f32_e32 v108, v55, v108
	v_add_f32_e32 v108, v56, v108
	v_add_f32_e32 v121, v57, v108
	v_cvt_pk_bf16_f32 v134, v52, v53
	v_cvt_pk_bf16_f32 v135, v54, v55
	s_waitcnt lgkmcnt(14)
	v_mfma_f32_32x32x16_bf16 v[80:95], v[170:173], v[148:151], v[80:95]
	ds_read_b64_tr_b16 v[108:109], v182 offset:27648
	ds_read_b64_tr_b16 v[110:111], v182 offset:28160
	v_add_f32_e32 v52, v58, v121
	v_add_f32_e32 v52, v59, v52
	v_add_f32_e32 v52, v60, v52
	v_add_f32_e32 v121, v61, v52
	v_cvt_pk_bf16_f32 v128, v56, v57
	v_cvt_pk_bf16_f32 v129, v58, v59
	s_waitcnt lgkmcnt(14)
	v_mfma_f32_32x32x16_bf16 v[64:79], v[184:187], v[144:147], v[64:79]
	ds_read_b64_tr_b16 v[52:53], v182 offset:31744
	ds_read_b64_tr_b16 v[54:55], v182 offset:32256
	v_add_f32_e32 v56, v62, v121
	v_add_f32_e32 v56, v63, v56
	v_add_f32_e32 v56, 0, v56
	v_cvt_pk_bf16_f32 v130, v60, v61
	v_cvt_pk_bf16_f32 v131, v62, v63
	v_mfma_f32_32x32x16_bf16 v[80:95], v[188:191], v[144:147], v[80:95]
	s_nop 3
	v_exp_f32_e32 v64, v64
	v_exp_f32_e32 v65, v65
	v_exp_f32_e32 v66, v66
	v_exp_f32_e32 v67, v67
	s_nop 0
	v_exp_f32_e32 v68, v68
	v_exp_f32_e32 v69, v69
	v_exp_f32_e32 v70, v70
	v_exp_f32_e32 v71, v71
	s_nop 0
	v_exp_f32_e32 v72, v72
	v_exp_f32_e32 v73, v73
	v_exp_f32_e32 v74, v74
	v_exp_f32_e32 v75, v75
	s_nop 0
	v_exp_f32_e32 v76, v76
	v_exp_f32_e32 v77, v77
	v_exp_f32_e32 v78, v78
	v_exp_f32_e32 v79, v79
	v_exp_f32_e32 v80, v80
	v_exp_f32_e32 v81, v81
	v_exp_f32_e32 v82, v82
	v_exp_f32_e32 v83, v83
	s_nop 0
	v_exp_f32_e32 v84, v84
	v_exp_f32_e32 v85, v85
	v_exp_f32_e32 v86, v86
	v_exp_f32_e32 v87, v87
	s_nop 0
	v_exp_f32_e32 v88, v88
	v_exp_f32_e32 v89, v89
	v_exp_f32_e32 v90, v90
	v_exp_f32_e32 v91, v91
	s_nop 0
	v_exp_f32_e32 v92, v92
	v_exp_f32_e32 v93, v93
	v_exp_f32_e32 v94, v94
	v_exp_f32_e32 v95, v95
	s_waitcnt lgkmcnt(14)
; #define SBAR() __builtin_amdgcn_sched_barrier(0)
;   #define PKW(P,B) cvtpk_s(P[B],P[B+1])
; template<int THRL,int VM,bool NOMAX> __device__ __forceinline__ void attn_unit(const bf16*Qb,const bf16*__restrict__ Kh,const bf16*__restrict__ Vh,bf16*Ob,const int NT,const int sp,float*wscr,char*shm){
;     ...
;   { float sacc=pB0[0]+pB0[1]; _Pragma("unroll") for(int r=2;r<16;++r)sacc+=pB0[r]; _Pragma("unroll") for(int r=0;r<16;++r)sacc+=pB1[r]; l_reg+=sacc;
;     pw0=(u32x4){PKW(pB0,0),PKW(pB0,2),PKW(pB0,4),PKW(pB0,6)};pw1=(u32x4){PKW(pB0,8),PKW(pB0,10),PKW(pB0,12),PKW(pB0,14)};pw2=(u32x4){PKW(pB1,0),PKW(pB1,2),PKW(pB1,4),PKW(pB1,6)};pw3=(u32x4){PKW(pB1,8),PKW(pB1,10),PKW(pB1,12),PKW(pB1,14)};
;     SBAR(); pv(o,vb0+VM*sl_cur,PAF(0),PAF(1),PAF(2),PAF(3)); if constexpr(VM==2) pv(o+2,vb0+VM*sl_cur+8192,PAF(0),PAF(1),PAF(2),PAF(3)); }
;     ...
;   {auto rr=__builtin_amdgcn_permlane32_swap(__float_as_uint(l_reg),__float_as_uint(l_reg),false,false);l_reg=__uint_as_float(rr[0])+__uint_as_float(rr[1]);}
;   if(hi==0)wsf[32+r32]=l_reg;asm volatile("s_waitcnt lgkmcnt(0)":::"memory");
	v_mfma_f32_32x32x16_bf16 v[16:31], v[140:143], v[112:115], v[16:31]
	v_add_f32_e32 v57, v64, v65
	v_add_f32_e32 v57, v66, v57
	v_add_f32_e32 v57, v67, v57
	v_add_f32_e32 v57, v68, v57
	v_add_f32_e32 v57, v69, v57
	v_add_f32_e32 v57, v70, v57
	v_add_f32_e32 v57, v71, v57
	s_waitcnt lgkmcnt(12)
	v_mfma_f32_32x32x16_bf16 v[32:47], v[140:143], v[96:99], v[32:47]
	v_add_f32_e32 v57, v72, v57
	v_add_f32_e32 v57, v73, v57
	v_add_f32_e32 v57, v74, v57
	v_add_f32_e32 v57, v75, v57
	v_add_f32_e32 v57, v76, v57
	v_add_f32_e32 v57, v77, v57
	v_add_f32_e32 v57, v78, v57
	s_waitcnt lgkmcnt(10)
	v_mfma_f32_32x32x16_bf16 v[16:31], v[136:139], v[116:119], v[16:31]
	v_add_f32_e32 v57, v79, v57
	v_add_f32_e32 v57, v80, v57
	v_add_f32_e32 v57, v81, v57
	v_add_f32_e32 v57, v82, v57
	v_add_f32_e32 v57, v83, v57
	v_add_f32_e32 v57, v84, v57
	v_add_f32_e32 v57, v85, v57
	s_waitcnt lgkmcnt(8)
	v_mfma_f32_32x32x16_bf16 v[32:47], v[136:139], v[100:103], v[32:47]
	v_add_f32_e32 v57, v86, v57
	v_add_f32_e32 v57, v87, v57
	v_add_f32_e32 v57, v88, v57
	v_add_f32_e32 v57, v89, v57
	v_add_f32_e32 v57, v90, v57
	v_add_f32_e32 v57, v91, v57
	v_add_f32_e32 v57, v92, v57
	s_waitcnt lgkmcnt(6)
	v_mfma_f32_32x32x16_bf16 v[16:31], v[132:135], v[104:107], v[16:31]
	v_add_f32_e32 v57, v93, v57
	v_add_f32_e32 v57, v94, v57
	v_add_f32_e32 v57, v95, v57
	v_add_f32_e32 v56, v120, v56
	v_add_f32_e32 v56, v56, v57
	v_cvt_pk_bf16_f32 v58, v64, v65
	v_cvt_pk_bf16_f32 v59, v66, v67
	s_waitcnt lgkmcnt(4)
	v_mfma_f32_32x32x16_bf16 v[32:47], v[132:135], v[48:51], v[32:47]
	v_cvt_pk_bf16_f32 v48, v80, v81
	v_cvt_pk_bf16_f32 v60, v68, v69
	v_cvt_pk_bf16_f32 v61, v70, v71
	v_cvt_pk_bf16_f32 v62, v72, v73
	v_cvt_pk_bf16_f32 v63, v74, v75
	v_cvt_pk_bf16_f32 v64, v76, v77
	v_cvt_pk_bf16_f32 v65, v78, v79
	s_waitcnt lgkmcnt(2)
	v_mfma_f32_32x32x16_bf16 v[16:31], v[128:131], v[108:111], v[16:31]
	v_cvt_pk_bf16_f32 v49, v82, v83
	v_cvt_pk_bf16_f32 v50, v84, v85
	v_cvt_pk_bf16_f32 v51, v86, v87
	v_cvt_pk_bf16_f32 v66, v88, v89
	v_cvt_pk_bf16_f32 v67, v90, v91
	v_cvt_pk_bf16_f32 v68, v92, v93
	v_cvt_pk_bf16_f32 v69, v94, v95
	s_waitcnt lgkmcnt(0)
	v_mfma_f32_32x32x16_bf16 v[32:47], v[128:131], v[52:55], v[32:47]
	v_add3_u32 v57, v174, v168, s18
	ds_read_b64_tr_b16 v[52:53],v57 offset:0
	ds_read_b64_tr_b16 v[54:55],v57 offset:512
	ds_read_b64_tr_b16 v[70:71],v57 offset:1024
	ds_read_b64_tr_b16 v[72:73],v57 offset:1536
	ds_read_b64_tr_b16 v[74:75],v57 offset:2048
	ds_read_b64_tr_b16 v[76:77],v57 offset:2560
	ds_read_b64_tr_b16 v[78:79],v57 offset:3072
	ds_read_b64_tr_b16 v[80:81],v57 offset:3584
	s_waitcnt lgkmcnt(0)
	s_nop 0
	v_mfma_f32_32x32x16_bf16 v[16:31], v[58:61], v[52:55], v[16:31]
	ds_read_b64_tr_b16 v[52:53],v57 offset:4096
	ds_read_b64_tr_b16 v[54:55],v57 offset:4608
	v_mfma_f32_32x32x16_bf16 v[16:31], v[62:65], v[70:73], v[16:31]
	ds_read_b64_tr_b16 v[70:71],v57 offset:5120
	ds_read_b64_tr_b16 v[72:73],v57 offset:5632
	v_mfma_f32_32x32x16_bf16 v[16:31], v[48:51], v[74:77], v[16:31]
	ds_read_b64_tr_b16 v[74:75],v57 offset:6144
	ds_read_b64_tr_b16 v[76:77],v57 offset:6656
	ds_read_b64_tr_b16 v[82:83],v57 offset:7168
	ds_read_b64_tr_b16 v[84:85],v57 offset:7680
	s_waitcnt lgkmcnt(0)
	v_mfma_f32_32x32x16_bf16 v[16:31], v[66:69], v[78:81], v[16:31]
	v_mfma_f32_32x32x16_bf16 v[32:47], v[58:61], v[52:55], v[32:47]
	v_cmp_gt_u32_e32 vcc, 32, v178
	v_mfma_f32_32x32x16_bf16 v[32:47], v[62:65], v[70:73], v[32:47]
	v_mfma_f32_32x32x16_bf16 v[32:47], v[48:51], v[74:77], v[32:47]
	v_mov_b32_e32 v48, v56
	s_nop 1
	v_permlane32_swap_b32_e32 v56, v48
	v_mfma_f32_32x32x16_bf16 v[32:47], v[66:69], v[82:85], v[32:47]
	s_and_saveexec_b64 s[16:17], vcc
	s_cbranch_execz .LBB0_878
	v_add_f32_e32 v48, v56, v48
	v_lshl_add_u32 v49, v180, 2, s29
	ds_write_b32 v49, v48 offset:49280
	s_branch .LBB0_878

.LBB0_891:
	v_mfma_f32_32x32x16_bf16 v[96:111], v[84:87], v[156:159], 0
	v_add_u32_e32 v187, s52, v168
	ds_read_b64_tr_b16 v[188:189], v187 offset:24576
	ds_read_b64_tr_b16 v[190:191], v187 offset:25088
	v_add_f32_e32 v88, v64, v65
	v_add_f32_e32 v88, v66, v88
	v_add_f32_e32 v88, v67, v88
	v_add_f32_e32 v88, v68, v88
	v_add_f32_e32 v88, v69, v88
	v_cvt_pk_bf16_f32 v140, v64, v65
	v_cvt_pk_bf16_f32 v141, v66, v67
	ds_read_b64_tr_b16 v[64:65], v187 offset:28672
	ds_read_b64_tr_b16 v[66:67], v187 offset:29184
	v_add_f32_e32 v84, v70, v88
	v_add_f32_e32 v84, v71, v84
	v_add_f32_e32 v84, v72, v84
	v_add_f32_e32 v128, v73, v84
	s_waitcnt lgkmcnt(10)
	v_mfma_f32_32x32x16_bf16 v[80:95], v[80:83], v[156:159], 0
	v_cvt_pk_bf16_f32 v142, v68, v69
	v_cvt_pk_bf16_f32 v143, v70, v71
	ds_read_b64_tr_b16 v[68:69], v187 offset:25600
	ds_read_b64_tr_b16 v[70:71], v187 offset:26112
	v_add_f32_e32 v128, v74, v128
	v_add_f32_e32 v128, v75, v128
	v_add_f32_e32 v128, v76, v128
	v_add_f32_e32 v128, v77, v128
	v_cvt_pk_bf16_f32 v136, v72, v73
	v_cvt_pk_bf16_f32 v137, v74, v75
	s_waitcnt lgkmcnt(11)
	v_mfma_f32_32x32x16_bf16 v[96:111], v[164:167], v[152:155], v[96:111]
	ds_read_b64_tr_b16 v[72:73], v187 offset:29696
	ds_read_b64_tr_b16 v[74:75], v187 offset:30208
	s_waitcnt lgkmcnt(12)
	v_mfma_f32_32x32x16_bf16 v[80:95], v[160:163], v[152:155], v[80:95]
	v_add_f32_e32 v128, v78, v128
	v_add_f32_e32 v128, v79, v128
	v_add_f32_e32 v128, v48, v128
	v_add_f32_e32 v128, v49, v128
	v_cvt_pk_bf16_f32 v138, v76, v77
	v_cvt_pk_bf16_f32 v139, v78, v79
	ds_read_b64_tr_b16 v[76:77], v187 offset:26624
	ds_read_b64_tr_b16 v[78:79], v187 offset:27136
	v_add_f32_e32 v128, v50, v128
	v_add_f32_e32 v128, v51, v128
	v_add_f32_e32 v128, v52, v128
	v_add_f32_e32 v128, v53, v128
	v_cvt_pk_bf16_f32 v132, v48, v49
	v_cvt_pk_bf16_f32 v133, v50, v51
	s_waitcnt lgkmcnt(13)
	v_mfma_f32_32x32x16_bf16 v[96:111], v[124:127], v[148:151], v[96:111]
	ds_read_b64_tr_b16 v[48:49], v187 offset:30720
	ds_read_b64_tr_b16 v[50:51], v187 offset:31232
	s_waitcnt lgkmcnt(14)
	v_mfma_f32_32x32x16_bf16 v[80:95], v[120:123], v[148:151], v[80:95]
	v_add_f32_e32 v124, v54, v128
	v_add_f32_e32 v124, v55, v124
	v_add_f32_e32 v124, v56, v124
	v_add_f32_e32 v124, v57, v124
	v_cvt_pk_bf16_f32 v134, v52, v53
	v_cvt_pk_bf16_f32 v135, v54, v55
	ds_read_b64_tr_b16 v[52:53], v187 offset:27648
	ds_read_b64_tr_b16 v[54:55], v187 offset:28160
	v_add_f32_e32 v120, v58, v124
	v_add_f32_e32 v120, v59, v120
	v_add_f32_e32 v120, v60, v120
	v_add_f32_e32 v120, v61, v120
	v_cvt_pk_bf16_f32 v128, v56, v57
	v_cvt_pk_bf16_f32 v129, v58, v59
	s_waitcnt lgkmcnt(14)
	v_mfma_f32_32x32x16_bf16 v[96:111], v[116:119], v[144:147], v[96:111]
	ds_read_b64_tr_b16 v[56:57], v187 offset:31744
	ds_read_b64_tr_b16 v[58:59], v187 offset:32256
	v_mfma_f32_32x32x16_bf16 v[80:95], v[112:115], v[144:147], v[80:95]
	v_add_f32_e32 v116, v62, v120
	v_add_f32_e32 v116, v63, v116
	v_add_f32_e32 v116, 0, v116
	v_cvt_pk_bf16_f32 v130, v60, v61
	v_cvt_pk_bf16_f32 v131, v62, v63
	v_lshl_add_u64 v[60:61], v[176:177], 0, s[38:39]
	s_add_i32 s35, s34, s17
	s_mov_b32 s52, m0
	s_mov_b32 m0, s35
	s_nop 0
	global_load_lds_dwordx4 v[60:61], off
	s_mov_b32 m0, s52
	v_lshl_add_u64 v[60:61], v[174:175], 0, s[38:39]
	s_add_i32 s35, s33, s16
	s_mov_b32 s52, m0
	s_mov_b32 m0, s35
	s_nop 0
	global_load_lds_dwordx4 v[60:61], off
	s_mov_b32 m0, s52
	v_add_f32_e32 v202, v186, v116
	s_waitcnt lgkmcnt(14)
	v_mfma_f32_32x32x16_bf16 v[16:31], v[140:143], v[188:191], v[16:31]
	v_exp_f32_e32 v96, v96
	v_exp_f32_e32 v97, v97
	v_exp_f32_e32 v98, v98
	v_exp_f32_e32 v99, v99
	s_waitcnt lgkmcnt(12)
	v_mfma_f32_32x32x16_bf16 v[32:47], v[140:143], v[64:67], v[32:47]
	v_exp_f32_e32 v100, v100
	v_exp_f32_e32 v101, v101
	v_exp_f32_e32 v102, v102
	v_exp_f32_e32 v103, v103
	v_add_u32_e32 v242, s33, v234
	v_add_u32_e32 v243, s33, v235
	v_add_u32_e32 v244, s33, v236
	v_add_u32_e32 v245, s33, v237
	ds_read_b128 v[60:63], v242
	ds_read_b128 v[112:115], v242 offset:4096
	s_waitcnt lgkmcnt(12)
	v_mfma_f32_32x32x16_bf16 v[16:31], v[136:139], v[68:71], v[16:31]
	v_exp_f32_e32 v104, v104
	v_exp_f32_e32 v105, v105
	v_exp_f32_e32 v106, v106
	v_exp_f32_e32 v107, v107
	ds_read_b128 v[116:119], v243
	ds_read_b128 v[120:123], v243 offset:4096
	s_waitcnt lgkmcnt(12)
	v_mfma_f32_32x32x16_bf16 v[32:47], v[136:139], v[72:75], v[32:47]
	v_exp_f32_e32 v108, v108
	v_exp_f32_e32 v109, v109
	v_exp_f32_e32 v110, v110
	v_exp_f32_e32 v111, v111
	ds_read_b128 v[124:127], v244
	ds_read_b128 v[160:163], v244 offset:4096
	s_waitcnt lgkmcnt(12)
	v_mfma_f32_32x32x16_bf16 v[16:31], v[132:135], v[76:79], v[16:31]
	v_exp_f32_e32 v80, v80
	v_exp_f32_e32 v81, v81
	v_exp_f32_e32 v82, v82
	v_exp_f32_e32 v83, v83
	ds_read_b128 v[164:167], v245
	ds_read_b128 v[186:189], v245 offset:4096
	s_waitcnt lgkmcnt(12)
	v_mfma_f32_32x32x16_bf16 v[32:47], v[132:135], v[48:51], v[32:47]
	v_exp_f32_e32 v84, v84
	v_exp_f32_e32 v85, v85
	v_exp_f32_e32 v86, v86
	v_exp_f32_e32 v87, v87
	s_waitcnt lgkmcnt(10)
	v_mfma_f32_32x32x16_bf16 v[16:31], v[128:131], v[52:55], v[16:31]
	v_exp_f32_e32 v88, v88
	v_exp_f32_e32 v89, v89
	v_exp_f32_e32 v90, v90
	v_exp_f32_e32 v91, v91
	s_waitcnt lgkmcnt(8)
	v_mfma_f32_32x32x16_bf16 v[32:47], v[128:131], v[56:59], v[32:47]
	v_exp_f32_e32 v92, v92
	v_exp_f32_e32 v93, v93
	v_exp_f32_e32 v94, v94
	v_exp_f32_e32 v95, v95
	s_waitcnt vmcnt(2) lgkmcnt(0)
	s_barrier
; #define WAIT_BAR(N) asm volatile("s_waitcnt vmcnt(" #N ") lgkmcnt(0)\n\ts_barrier":::"memory")
;   #define RESC() do{ if(!NOMAX&&resc){ asm volatile("s_waitcnt lgkmcnt(0)":::"memory"); \
;       _Pragma("unroll") for(int d_=0;d_<2*VM;++d_) _Pragma("unroll") for(int r=0;r<16;++r)o[d_][r]*=wsf[crow(r,hi)]; } }while(0)
;   #define ROT() do{sl_prev=sl_cur;sl_cur=sl_next;sl_next=(sl_next==(NSLOT-1)*SLOTB)?0:sl_next+SLOTB;}while(0)
; template<int THRL,int VM,bool NOMAX> __device__ __forceinline__ void attn_unit(const bf16*Qb,const bf16*__restrict__ Kh,const bf16*__restrict__ Vh,bf16*Ob,const int NT,const int sp,float*wscr,char*shm){
;     ...
;   int t=1;
;   for(;t+5<NT;t+=2){
;     STEP(pB0,pB1,pA0,pA1,t,true,true,true);     if constexpr(VM==2){WAIT_BAR(3);}else{WAIT_BAR(2);} RESC(); ROT();
;     STEP(pA0,pA1,pB0,pB1,t+1,true,true,true);   if constexpr(VM==2){WAIT_BAR(3);}else{WAIT_BAR(2);} RESC(); ROT();
	v_mfma_f32_32x32x16_bf16 v[64:79], v[60:63], v[156:159], 0
	s_add_i32 s35, s33, 0x2000
	s_cmpk_lg_i32 s33, 0x4000
	s_cselect_b32 s35, s35, 0
	v_add_u32_e32 v203, s34, v168
	ds_read_b64_tr_b16 v[190:191], v203 offset:24576
	ds_read_b64_tr_b16 v[192:193], v203 offset:25088
	v_add_f32_e32 v48, v96, v97
	v_add_f32_e32 v48, v98, v48
	v_add_f32_e32 v48, v99, v48
	v_add_f32_e32 v48, v100, v48
	v_add_f32_e32 v48, v101, v48
	v_cvt_pk_bf16_f32 v140, v96, v97
	v_cvt_pk_bf16_f32 v141, v98, v99
	ds_read_b64_tr_b16 v[96:97], v203 offset:28672
	ds_read_b64_tr_b16 v[98:99], v203 offset:29184
	v_add_f32_e32 v48, v102, v48
	v_add_f32_e32 v48, v103, v48
	v_add_f32_e32 v48, v104, v48
	v_add_f32_e32 v128, v105, v48
	s_waitcnt lgkmcnt(10)
	v_mfma_f32_32x32x16_bf16 v[48:63], v[112:115], v[156:159], 0
	v_cvt_pk_bf16_f32 v142, v100, v101
	v_cvt_pk_bf16_f32 v143, v102, v103
	ds_read_b64_tr_b16 v[100:101], v203 offset:25600
	ds_read_b64_tr_b16 v[102:103], v203 offset:26112
	s_waitcnt lgkmcnt(11)
	v_mfma_f32_32x32x16_bf16 v[64:79], v[116:119], v[152:155], v[64:79]
	v_add_f32_e32 v112, v106, v128
	v_add_f32_e32 v112, v107, v112
	v_add_f32_e32 v112, v108, v112
	v_add_f32_e32 v112, v109, v112
	v_cvt_pk_bf16_f32 v136, v104, v105
	v_cvt_pk_bf16_f32 v137, v106, v107
	ds_read_b64_tr_b16 v[104:105], v203 offset:29696
	ds_read_b64_tr_b16 v[106:107], v203 offset:30208
	s_waitcnt lgkmcnt(12)
	v_mfma_f32_32x32x16_bf16 v[48:63], v[120:123], v[152:155], v[48:63]
	v_add_f32_e32 v112, v110, v112
	v_add_f32_e32 v112, v111, v112
	v_add_f32_e32 v112, v80, v112
	v_add_f32_e32 v112, v81, v112
	v_cvt_pk_bf16_f32 v138, v108, v109
	v_cvt_pk_bf16_f32 v139, v110, v111
	ds_read_b64_tr_b16 v[108:109], v203 offset:26624
	ds_read_b64_tr_b16 v[110:111], v203 offset:27136
	s_waitcnt lgkmcnt(13)
	v_mfma_f32_32x32x16_bf16 v[64:79], v[124:127], v[148:151], v[64:79]
	v_add_f32_e32 v112, v82, v112
	v_add_f32_e32 v112, v83, v112
	v_add_f32_e32 v112, v84, v112
	v_add_f32_e32 v112, v85, v112
	v_cvt_pk_bf16_f32 v132, v80, v81
	v_cvt_pk_bf16_f32 v133, v82, v83
	ds_read_b64_tr_b16 v[194:195], v203 offset:30720
	ds_read_b64_tr_b16 v[196:197], v203 offset:31232
	s_waitcnt lgkmcnt(14)
	v_mfma_f32_32x32x16_bf16 v[48:63], v[160:163], v[148:151], v[48:63]
	v_add_f32_e32 v80, v86, v112
	v_add_f32_e32 v80, v87, v80
	v_add_f32_e32 v80, v88, v80
	v_add_f32_e32 v80, v89, v80
	v_cvt_pk_bf16_f32 v134, v84, v85
	v_cvt_pk_bf16_f32 v135, v86, v87
	ds_read_b64_tr_b16 v[198:199], v203 offset:27648
	ds_read_b64_tr_b16 v[200:201], v203 offset:28160
	s_waitcnt lgkmcnt(14)
	v_mfma_f32_32x32x16_bf16 v[64:79], v[164:167], v[144:147], v[64:79]
	v_add_f32_e32 v80, v90, v80
	v_add_f32_e32 v80, v91, v80
	v_add_f32_e32 v80, v92, v80
	v_add_f32_e32 v80, v93, v80
	v_cvt_pk_bf16_f32 v128, v88, v89
	v_cvt_pk_bf16_f32 v129, v90, v91
	ds_read_b64_tr_b16 v[88:89], v203 offset:31744
	ds_read_b64_tr_b16 v[90:91], v203 offset:32256
	v_mfma_f32_32x32x16_bf16 v[48:63], v[186:189], v[144:147], v[48:63]
	v_add_f32_e32 v80, v94, v80
	v_add_f32_e32 v80, v95, v80
	v_add_f32_e32 v80, 0, v80
	v_cvt_pk_bf16_f32 v130, v92, v93
	v_cvt_pk_bf16_f32 v131, v94, v95
	s_add_i32 s34, s33, s17
	s_mov_b32 s52, m0
	s_mov_b32 m0, s34
	s_nop 0
	global_load_lds_dwordx4 v[176:177], off
	s_mov_b32 m0, s52
	s_add_i32 s34, s35, s16
	s_mov_b32 s52, m0
	s_mov_b32 m0, s34
	s_nop 0
	global_load_lds_dwordx4 v[174:175], off
	s_mov_b32 m0, s52
	v_add_f32_e32 v186, v202, v80
	s_waitcnt lgkmcnt(14)
	v_mfma_f32_32x32x16_bf16 v[16:31], v[140:143], v[190:193], v[16:31]
	v_exp_f32_e32 v64, v64
	v_exp_f32_e32 v65, v65
	v_exp_f32_e32 v66, v66
	v_exp_f32_e32 v67, v67
	s_waitcnt lgkmcnt(12)
	v_mfma_f32_32x32x16_bf16 v[32:47], v[140:143], v[96:99], v[32:47]
	v_exp_f32_e32 v68, v68
	v_exp_f32_e32 v69, v69
	v_exp_f32_e32 v70, v70
	v_exp_f32_e32 v71, v71
	v_add_u32_e32 v242, s35, v234
	v_add_u32_e32 v243, s35, v235
	v_add_u32_e32 v244, s35, v236
	v_add_u32_e32 v245, s35, v237
	ds_read_b128 v[84:87], v242
	ds_read_b128 v[80:83], v242 offset:4096
	s_waitcnt lgkmcnt(12)
	v_mfma_f32_32x32x16_bf16 v[16:31], v[136:139], v[100:103], v[16:31]
	v_exp_f32_e32 v72, v72
	v_exp_f32_e32 v73, v73
	v_exp_f32_e32 v74, v74
	v_exp_f32_e32 v75, v75
	ds_read_b128 v[164:167], v243
	ds_read_b128 v[160:163], v243 offset:4096
	s_waitcnt lgkmcnt(12)
	v_mfma_f32_32x32x16_bf16 v[32:47], v[136:139], v[104:107], v[32:47]
	v_exp_f32_e32 v76, v76
	v_exp_f32_e32 v77, v77
	v_exp_f32_e32 v78, v78
	v_exp_f32_e32 v79, v79
	ds_read_b128 v[124:127], v244
	ds_read_b128 v[120:123], v244 offset:4096
	s_waitcnt lgkmcnt(12)
	v_mfma_f32_32x32x16_bf16 v[16:31], v[132:135], v[108:111], v[16:31]
	v_exp_f32_e32 v48, v48
	v_exp_f32_e32 v49, v49
	v_exp_f32_e32 v50, v50
	v_exp_f32_e32 v51, v51
	ds_read_b128 v[116:119], v245
	ds_read_b128 v[112:115], v245 offset:4096
	s_waitcnt lgkmcnt(12)
	v_mfma_f32_32x32x16_bf16 v[32:47], v[132:135], v[194:197], v[32:47]
	v_exp_f32_e32 v52, v52
	v_exp_f32_e32 v53, v53
	v_exp_f32_e32 v54, v54
	v_exp_f32_e32 v55, v55
	s_waitcnt lgkmcnt(10)
	v_mfma_f32_32x32x16_bf16 v[16:31], v[128:131], v[198:201], v[16:31]
	v_exp_f32_e32 v56, v56
	v_exp_f32_e32 v57, v57
	v_exp_f32_e32 v58, v58
	v_exp_f32_e32 v59, v59
	s_waitcnt lgkmcnt(8)
	v_mfma_f32_32x32x16_bf16 v[32:47], v[128:131], v[88:91], v[32:47]
	v_exp_f32_e32 v60, v60
	v_exp_f32_e32 v61, v61
	v_exp_f32_e32 v62, v62
	v_exp_f32_e32 v63, v63
	s_add_i32 s53, s35, 0x2000
	s_cmpk_lg_i32 s35, 0x4000
	s_mov_b32 s52, s33
	s_cselect_b32 s33, s53, 0
	s_add_i32 s29, s29, 2
	v_lshl_add_u64 v[174:175], v[174:175], 0, s[8:9]
	v_lshl_add_u64 v[176:177], v[176:177], 0, s[8:9]
	s_mov_b32 s34, s35
	s_cmp_lt_u32 s29, 57
	s_waitcnt vmcnt(2) lgkmcnt(0)
	s_barrier
	s_cbranch_scc1 .LBB0_891
	s_and_b32 s19, s19, 0x3fffffc0
	s_lshl_b32 s19, s19, 2
	s_add_i32 s19, s19, 0
	s_cmp_lg_u32 0, -1
	s_cselect_b32 s29, 0, 0
	s_add_i32 s33, s29, 0x6000
	v_add_u32_e32 v88, s33, v184
	v_add3_u32 v174, v88, v183, v185
	ds_read_b64_tr_b16 v[188:189], v168 offset:32768
	ds_read_b64_tr_b16 v[190:191], v168 offset:33280
	v_add_f32_e32 v88, v64, v65
	v_add_f32_e32 v88, v66, v88
	v_add_f32_e32 v88, v67, v88
	v_add_f32_e32 v88, v68, v88
	v_add_f32_e32 v88, v69, v88
	v_cvt_pk_bf16_f32 v140, v64, v65
	v_cvt_pk_bf16_f32 v141, v66, v67
	s_waitcnt lgkmcnt(9)
	v_mfma_f32_32x32x16_bf16 v[96:111], v[84:87], v[156:159], 0
	ds_read_b64_tr_b16 v[64:65], v168 offset:36864
	ds_read_b64_tr_b16 v[66:67], v168 offset:37376
	v_add_f32_e32 v84, v70, v88
	v_add_f32_e32 v84, v71, v84
	v_add_f32_e32 v84, v72, v84
	v_add_f32_e32 v128, v73, v84
	v_cvt_pk_bf16_f32 v142, v68, v69
	v_cvt_pk_bf16_f32 v143, v70, v71
	s_waitcnt lgkmcnt(10)
	v_mfma_f32_32x32x16_bf16 v[80:95], v[80:83], v[156:159], 0
	ds_read_b64_tr_b16 v[68:69], v168 offset:33792
	ds_read_b64_tr_b16 v[70:71], v168 offset:34304
	v_add_f32_e32 v128, v74, v128
	v_add_f32_e32 v128, v75, v128
	v_add_f32_e32 v128, v76, v128
	v_add_f32_e32 v128, v77, v128
	v_cvt_pk_bf16_f32 v136, v72, v73
	v_cvt_pk_bf16_f32 v137, v74, v75
	s_waitcnt lgkmcnt(11)
	v_mfma_f32_32x32x16_bf16 v[96:111], v[164:167], v[152:155], v[96:111]
	ds_read_b64_tr_b16 v[72:73], v168 offset:37888
	ds_read_b64_tr_b16 v[74:75], v168 offset:38400
	v_add_f32_e32 v128, v78, v128
	v_add_f32_e32 v128, v79, v128
	v_add_f32_e32 v128, v48, v128
	v_add_f32_e32 v128, v49, v128
	v_cvt_pk_bf16_f32 v138, v76, v77
	v_cvt_pk_bf16_f32 v139, v78, v79
	s_waitcnt lgkmcnt(12)
	v_mfma_f32_32x32x16_bf16 v[80:95], v[160:163], v[152:155], v[80:95]
	ds_read_b64_tr_b16 v[76:77], v168 offset:34816
	ds_read_b64_tr_b16 v[78:79], v168 offset:35328
	v_add_f32_e32 v128, v50, v128
	v_add_f32_e32 v128, v51, v128
	v_add_f32_e32 v128, v52, v128
	v_add_f32_e32 v128, v53, v128
	v_cvt_pk_bf16_f32 v132, v48, v49
	v_cvt_pk_bf16_f32 v133, v50, v51
	s_waitcnt lgkmcnt(13)
	v_mfma_f32_32x32x16_bf16 v[96:111], v[124:127], v[148:151], v[96:111]
	ds_read_b64_tr_b16 v[48:49], v168 offset:38912
	ds_read_b64_tr_b16 v[50:51], v168 offset:39424
	v_add_f32_e32 v124, v54, v128
	v_add_f32_e32 v124, v55, v124
	v_add_f32_e32 v124, v56, v124
	v_add_f32_e32 v124, v57, v124
	v_cvt_pk_bf16_f32 v134, v52, v53
	v_cvt_pk_bf16_f32 v135, v54, v55
	s_waitcnt lgkmcnt(14)
	v_mfma_f32_32x32x16_bf16 v[80:95], v[120:123], v[148:151], v[80:95]
	ds_read_b64_tr_b16 v[52:53], v168 offset:35840
	ds_read_b64_tr_b16 v[54:55], v168 offset:36352
	v_add_f32_e32 v120, v58, v124
	v_add_f32_e32 v120, v59, v120
	v_add_f32_e32 v120, v60, v120
	v_add_f32_e32 v120, v61, v120
	v_cvt_pk_bf16_f32 v128, v56, v57
	v_cvt_pk_bf16_f32 v129, v58, v59
	s_waitcnt lgkmcnt(14)
	v_mfma_f32_32x32x16_bf16 v[96:111], v[116:119], v[144:147], v[96:111]
	ds_read_b64_tr_b16 v[56:57], v168 offset:39936
	ds_read_b64_tr_b16 v[58:59], v168 offset:40448
	v_add_f32_e32 v116, v62, v120
	v_add_f32_e32 v116, v63, v116
	v_add_f32_e32 v116, 0, v116
	v_cvt_pk_bf16_f32 v130, v60, v61
	v_cvt_pk_bf16_f32 v131, v62, v63
	v_mfma_f32_32x32x16_bf16 v[80:95], v[112:115], v[144:147], v[80:95]
	s_add_i32 s28, s29, s28
	v_lshl_add_u64 v[60:61], v[172:173], 0, s[40:41]
	s_add_i32 s29, s28, 0x4000
	s_mov_b32 s33, m0
	s_mov_b32 m0, s29
	s_nop 0
	global_load_lds_dwordx4 v[60:61], off
	s_mov_b32 m0, s33
	v_lshl_add_u64 v[60:61], v[170:171], 0, s[42:43]
	s_mov_b32 s29, m0
	s_mov_b32 m0, s16
	s_nop 0
	global_load_lds_dwordx4 v[60:61], off
	s_mov_b32 m0, s29
	v_add_f32_e32 v175, v186, v116
	s_waitcnt lgkmcnt(14)
	v_mfma_f32_32x32x16_bf16 v[16:31], v[140:143], v[188:191], v[16:31]
	v_exp_f32_e32 v96, v96
	v_exp_f32_e32 v97, v97
	v_exp_f32_e32 v98, v98
	v_exp_f32_e32 v99, v99
	s_waitcnt lgkmcnt(12)
	v_mfma_f32_32x32x16_bf16 v[32:47], v[140:143], v[64:67], v[32:47]
	v_exp_f32_e32 v100, v100
	v_exp_f32_e32 v101, v101
	v_exp_f32_e32 v102, v102
	v_exp_f32_e32 v103, v103
	ds_read_b128 v[60:63], v234
	ds_read_b128 v[64:67], v234 offset:4096
	s_waitcnt lgkmcnt(12)
	v_mfma_f32_32x32x16_bf16 v[16:31], v[136:139], v[68:71], v[16:31]
	v_exp_f32_e32 v104, v104
	v_exp_f32_e32 v105, v105
	v_exp_f32_e32 v106, v106
	v_exp_f32_e32 v107, v107
	ds_read_b128 v[68:71], v235
	ds_read_b128 v[160:163], v235 offset:4096
	s_waitcnt lgkmcnt(12)
	v_mfma_f32_32x32x16_bf16 v[32:47], v[136:139], v[72:75], v[32:47]
	v_exp_f32_e32 v108, v108
	v_exp_f32_e32 v109, v109
	v_exp_f32_e32 v110, v110
	v_exp_f32_e32 v111, v111
	ds_read_b128 v[72:75], v236
	ds_read_b128 v[164:167], v236 offset:4096
	s_waitcnt lgkmcnt(12)
	v_mfma_f32_32x32x16_bf16 v[16:31], v[132:135], v[76:79], v[16:31]
	v_exp_f32_e32 v80, v80
	v_exp_f32_e32 v81, v81
	v_exp_f32_e32 v82, v82
	v_exp_f32_e32 v83, v83
	ds_read_b128 v[76:79], v237
	ds_read_b128 v[184:187], v237 offset:4096
	s_waitcnt lgkmcnt(12)
	v_mfma_f32_32x32x16_bf16 v[32:47], v[132:135], v[48:51], v[32:47]
	v_exp_f32_e32 v84, v84
	v_exp_f32_e32 v85, v85
	v_exp_f32_e32 v86, v86
	v_exp_f32_e32 v87, v87
	s_waitcnt lgkmcnt(10)
	v_mfma_f32_32x32x16_bf16 v[16:31], v[128:131], v[52:55], v[16:31]
	v_exp_f32_e32 v88, v88
	v_exp_f32_e32 v89, v89
	v_exp_f32_e32 v90, v90
	v_exp_f32_e32 v91, v91
	s_waitcnt lgkmcnt(8)
	v_mfma_f32_32x32x16_bf16 v[32:47], v[128:131], v[56:59], v[32:47]
	v_exp_f32_e32 v92, v92
	v_exp_f32_e32 v93, v93
	v_exp_f32_e32 v94, v94
	v_exp_f32_e32 v95, v95
	s_waitcnt vmcnt(2) lgkmcnt(0)
	s_barrier
	ds_read_b64_tr_b16 v[188:189], v168 offset:40960
	ds_read_b64_tr_b16 v[190:191], v168 offset:41472
	v_add_f32_e32 v48, v96, v97
	v_add_f32_e32 v48, v98, v48
	v_add_f32_e32 v48, v99, v48
	v_add_f32_e32 v48, v100, v48
	v_add_f32_e32 v48, v101, v48
	v_cvt_pk_bf16_f32 v140, v96, v97
	v_cvt_pk_bf16_f32 v141, v98, v99
	s_waitcnt lgkmcnt(9)
	v_mfma_f32_32x32x16_bf16 v[112:127], v[60:63], v[156:159], 0
	ds_read_b64_tr_b16 v[96:97], v168 offset:45056
	ds_read_b64_tr_b16 v[98:99], v168 offset:45568
	v_add_f32_e32 v48, v102, v48
	v_add_f32_e32 v48, v103, v48
	v_add_f32_e32 v48, v104, v48
	v_add_f32_e32 v128, v105, v48
	s_waitcnt lgkmcnt(10)
	v_mfma_f32_32x32x16_bf16 v[48:63], v[64:67], v[156:159], 0
	v_cvt_pk_bf16_f32 v142, v100, v101
	v_cvt_pk_bf16_f32 v143, v102, v103
	ds_read_b64_tr_b16 v[64:65], v168 offset:41984
	ds_read_b64_tr_b16 v[66:67], v168 offset:42496
	v_add_f32_e32 v100, v106, v128
	v_add_f32_e32 v100, v107, v100
	v_add_f32_e32 v100, v108, v100
	v_add_f32_e32 v100, v109, v100
	v_cvt_pk_bf16_f32 v136, v104, v105
	v_cvt_pk_bf16_f32 v137, v106, v107
	s_waitcnt lgkmcnt(11)
	v_mfma_f32_32x32x16_bf16 v[112:127], v[68:71], v[152:155], v[112:127]
	ds_read_b64_tr_b16 v[68:69], v168 offset:46080
	ds_read_b64_tr_b16 v[70:71], v168 offset:46592
	s_waitcnt lgkmcnt(12)
	v_mfma_f32_32x32x16_bf16 v[48:63], v[160:163], v[152:155], v[48:63]
	v_add_f32_e32 v100, v110, v100
	v_add_f32_e32 v100, v111, v100
	v_add_f32_e32 v100, v80, v100
	v_add_f32_e32 v104, v81, v100
	v_cvt_pk_bf16_f32 v138, v108, v109
	v_cvt_pk_bf16_f32 v139, v110, v111
	ds_read_b64_tr_b16 v[100:101], v168 offset:43008
	ds_read_b64_tr_b16 v[102:103], v168 offset:43520
	v_add_f32_e32 v104, v82, v104
	v_add_f32_e32 v104, v83, v104
	v_add_f32_e32 v104, v84, v104
	v_add_f32_e32 v104, v85, v104
	v_cvt_pk_bf16_f32 v132, v80, v81
	v_cvt_pk_bf16_f32 v133, v82, v83
	s_waitcnt lgkmcnt(13)
	v_mfma_f32_32x32x16_bf16 v[112:127], v[72:75], v[148:151], v[112:127]
	ds_read_b64_tr_b16 v[72:73], v168 offset:47104
	ds_read_b64_tr_b16 v[74:75], v168 offset:47616
	s_waitcnt lgkmcnt(14)
	v_mfma_f32_32x32x16_bf16 v[48:63], v[164:167], v[148:151], v[48:63]
	v_add_f32_e32 v80, v86, v104
	v_add_f32_e32 v80, v87, v80
	v_add_f32_e32 v80, v88, v80
	v_add_f32_e32 v104, v89, v80
	v_cvt_pk_bf16_f32 v134, v84, v85
	v_cvt_pk_bf16_f32 v135, v86, v87
	ds_read_b64_tr_b16 v[80:81], v168 offset:44032
	ds_read_b64_tr_b16 v[82:83], v168 offset:44544
	v_add_f32_e32 v84, v90, v104
	v_add_f32_e32 v84, v91, v84
	v_add_f32_e32 v84, v92, v84
	v_add_f32_e32 v84, v93, v84
	v_cvt_pk_bf16_f32 v128, v88, v89
	v_cvt_pk_bf16_f32 v129, v90, v91
	s_waitcnt lgkmcnt(14)
	v_mfma_f32_32x32x16_bf16 v[112:127], v[76:79], v[144:147], v[112:127]
	ds_read_b64_tr_b16 v[76:77], v168 offset:48128
	ds_read_b64_tr_b16 v[78:79], v168 offset:48640
	v_mfma_f32_32x32x16_bf16 v[48:63], v[184:187], v[144:147], v[48:63]
	v_add_f32_e32 v84, v94, v84
	v_add_f32_e32 v84, v95, v84
	v_add_f32_e32 v84, 0, v84
	v_cvt_pk_bf16_f32 v130, v92, v93
	v_cvt_pk_bf16_f32 v131, v94, v95
	s_nop 0
	v_add_f32_e32 v175, v175, v84
	v_lshl_add_u64 v[84:85], v[172:173], 0, s[44:45]
	s_mov_b32 s29, m0
	s_mov_b32 m0, s17
	s_nop 0
	global_load_lds_dwordx4 v[84:85], off
	s_mov_b32 m0, s29
	v_lshl_add_u64 v[84:85], v[170:171], 0, s[48:49]
	s_add_i32 s17, s28, 0x8000
	s_mov_b32 s29, m0
	s_mov_b32 m0, s17
	s_nop 0
	global_load_lds_dwordx4 v[84:85], off
	s_mov_b32 m0, s29
	s_waitcnt lgkmcnt(14)
	v_mfma_f32_32x32x16_bf16 v[16:31], v[140:143], v[188:191], v[16:31]
	v_exp_f32_e32 v112, v112
	v_exp_f32_e32 v113, v113
	v_exp_f32_e32 v114, v114
	v_exp_f32_e32 v115, v115
	s_waitcnt lgkmcnt(12)
	v_mfma_f32_32x32x16_bf16 v[32:47], v[140:143], v[96:99], v[32:47]
	v_exp_f32_e32 v116, v116
	v_exp_f32_e32 v117, v117
	v_exp_f32_e32 v118, v118
	v_exp_f32_e32 v119, v119
	ds_read_b128 v[84:87], v234 offset:8192
	ds_read_b128 v[96:99], v234 offset:12288
	s_waitcnt lgkmcnt(12)
	v_mfma_f32_32x32x16_bf16 v[16:31], v[136:139], v[64:67], v[16:31]
	v_exp_f32_e32 v120, v120
	v_exp_f32_e32 v121, v121
	v_exp_f32_e32 v122, v122
	v_exp_f32_e32 v123, v123
	ds_read_b128 v[104:107], v235 offset:8192
	ds_read_b128 v[108:111], v235 offset:12288
	s_waitcnt lgkmcnt(12)
	v_mfma_f32_32x32x16_bf16 v[32:47], v[136:139], v[68:71], v[32:47]
	v_exp_f32_e32 v124, v124
	v_exp_f32_e32 v125, v125
	v_exp_f32_e32 v126, v126
	v_exp_f32_e32 v127, v127
	ds_read_b128 v[160:163], v236 offset:8192
	ds_read_b128 v[164:167], v236 offset:12288
	s_waitcnt lgkmcnt(12)
	v_mfma_f32_32x32x16_bf16 v[16:31], v[132:135], v[100:103], v[16:31]
	v_exp_f32_e32 v48, v48
	v_exp_f32_e32 v49, v49
	v_exp_f32_e32 v50, v50
	v_exp_f32_e32 v51, v51
	ds_read_b128 v[100:103], v237 offset:8192
	ds_read_b128 v[184:187], v237 offset:12288
	s_waitcnt lgkmcnt(12)
	v_mfma_f32_32x32x16_bf16 v[32:47], v[132:135], v[72:75], v[32:47]
	v_exp_f32_e32 v52, v52
	v_exp_f32_e32 v53, v53
	v_exp_f32_e32 v54, v54
	v_exp_f32_e32 v55, v55
	s_waitcnt lgkmcnt(10)
	v_mfma_f32_32x32x16_bf16 v[16:31], v[128:131], v[80:83], v[16:31]
	v_exp_f32_e32 v56, v56
	v_exp_f32_e32 v57, v57
	v_exp_f32_e32 v58, v58
	v_exp_f32_e32 v59, v59
	s_waitcnt lgkmcnt(8)
	v_mfma_f32_32x32x16_bf16 v[32:47], v[128:131], v[76:79], v[32:47]
	v_exp_f32_e32 v60, v60
	v_exp_f32_e32 v61, v61
	v_exp_f32_e32 v62, v62
	v_exp_f32_e32 v63, v63
	s_waitcnt vmcnt(2) lgkmcnt(0)
	s_barrier
	ds_read_b64_tr_b16 v[188:189], v168 offset:24576
	ds_read_b64_tr_b16 v[190:191], v168 offset:25088
	v_add_f32_e32 v64, v112, v113
	v_add_f32_e32 v64, v114, v64
	v_add_f32_e32 v64, v115, v64
	v_add_f32_e32 v64, v116, v64
	v_add_f32_e32 v64, v117, v64
	v_cvt_pk_bf16_f32 v140, v112, v113
	v_cvt_pk_bf16_f32 v141, v114, v115
	s_waitcnt lgkmcnt(9)
	v_mfma_f32_32x32x16_bf16 v[80:95], v[84:87], v[156:159], 0
	ds_read_b64_tr_b16 v[112:113], v168 offset:28672
	ds_read_b64_tr_b16 v[114:115], v168 offset:29184
	v_add_f32_e32 v64, v118, v64
	v_add_f32_e32 v64, v119, v64
	v_add_f32_e32 v64, v120, v64
	v_add_f32_e32 v128, v121, v64
	v_cvt_pk_bf16_f32 v142, v116, v117
	v_cvt_pk_bf16_f32 v143, v118, v119
	s_waitcnt lgkmcnt(10)
	v_mfma_f32_32x32x16_bf16 v[64:79], v[96:99], v[156:159], 0
	ds_read_b64_tr_b16 v[96:97], v168 offset:25600
	ds_read_b64_tr_b16 v[98:99], v168 offset:26112
	v_add_f32_e32 v116, v122, v128
	v_add_f32_e32 v116, v123, v116
	v_add_f32_e32 v116, v124, v116
	v_add_f32_e32 v116, v125, v116
	v_cvt_pk_bf16_f32 v136, v120, v121
	v_cvt_pk_bf16_f32 v137, v122, v123
	s_waitcnt lgkmcnt(11)
	v_mfma_f32_32x32x16_bf16 v[80:95], v[104:107], v[152:155], v[80:95]
	ds_read_b64_tr_b16 v[104:105], v168 offset:29696
	ds_read_b64_tr_b16 v[106:107], v168 offset:30208
	v_add_f32_e32 v116, v126, v116
	v_add_f32_e32 v116, v127, v116
	v_add_f32_e32 v116, v48, v116
	v_add_f32_e32 v116, v49, v116
	v_cvt_pk_bf16_f32 v138, v124, v125
	v_cvt_pk_bf16_f32 v139, v126, v127
	s_waitcnt lgkmcnt(12)
	v_mfma_f32_32x32x16_bf16 v[64:79], v[108:111], v[152:155], v[64:79]
	ds_read_b64_tr_b16 v[108:109], v168 offset:26624
	ds_read_b64_tr_b16 v[110:111], v168 offset:27136
	v_add_f32_e32 v116, v50, v116
	v_add_f32_e32 v116, v51, v116
	v_add_f32_e32 v116, v52, v116
	v_add_f32_e32 v116, v53, v116
	v_cvt_pk_bf16_f32 v132, v48, v49
	v_cvt_pk_bf16_f32 v133, v50, v51
	s_waitcnt lgkmcnt(13)
	v_mfma_f32_32x32x16_bf16 v[80:95], v[160:163], v[148:151], v[80:95]
	ds_read_b64_tr_b16 v[48:49], v168 offset:30720
	ds_read_b64_tr_b16 v[50:51], v168 offset:31232
	v_add_f32_e32 v116, v54, v116
	v_add_f32_e32 v116, v55, v116
	v_add_f32_e32 v116, v56, v116
	v_add_f32_e32 v116, v57, v116
	v_cvt_pk_bf16_f32 v134, v52, v53
	v_cvt_pk_bf16_f32 v135, v54, v55
	s_waitcnt lgkmcnt(14)
	v_mfma_f32_32x32x16_bf16 v[64:79], v[164:167], v[148:151], v[64:79]
	ds_read_b64_tr_b16 v[52:53], v168 offset:27648
	ds_read_b64_tr_b16 v[54:55], v168 offset:28160
	v_add_f32_e32 v116, v58, v116
	v_add_f32_e32 v116, v59, v116
	v_add_f32_e32 v116, v60, v116
	v_add_f32_e32 v116, v61, v116
	v_cvt_pk_bf16_f32 v128, v56, v57
	v_cvt_pk_bf16_f32 v129, v58, v59
	s_waitcnt lgkmcnt(14)
	v_mfma_f32_32x32x16_bf16 v[80:95], v[100:103], v[144:147], v[80:95]
	ds_read_b64_tr_b16 v[56:57], v168 offset:31744
	ds_read_b64_tr_b16 v[58:59], v168 offset:32256
	v_add_f32_e32 v100, v62, v116
	v_add_f32_e32 v100, v63, v100
	v_add_f32_e32 v100, 0, v100
	v_cvt_pk_bf16_f32 v130, v60, v61
	v_cvt_pk_bf16_f32 v131, v62, v63
	v_mfma_f32_32x32x16_bf16 v[64:79], v[184:187], v[144:147], v[64:79]
	v_lshl_add_u64 v[60:61], v[170:171], 0, s[40:41]
	s_add_i32 s28, s28, 0xa000
	s_mov_b32 s17, m0
	s_mov_b32 m0, s28
	s_nop 0
	global_load_lds_dwordx4 v[60:61], off
	s_mov_b32 m0, s17
	v_add_f32_e32 v172, v175, v100
	s_waitcnt lgkmcnt(14)
	v_mfma_f32_32x32x16_bf16 v[16:31], v[140:143], v[188:191], v[16:31]
	v_exp_f32_e32 v80, v80
	v_exp_f32_e32 v81, v81
	v_exp_f32_e32 v82, v82
	v_exp_f32_e32 v83, v83
	s_waitcnt lgkmcnt(12)
	v_mfma_f32_32x32x16_bf16 v[32:47], v[140:143], v[112:115], v[32:47]
	v_exp_f32_e32 v84, v84
	v_exp_f32_e32 v85, v85
	v_exp_f32_e32 v86, v86
	v_exp_f32_e32 v87, v87
	ds_read_b128 v[60:63], v234 offset:16384
	ds_read_b128 v[112:115], v234 offset:20480
	s_waitcnt lgkmcnt(12)
	v_mfma_f32_32x32x16_bf16 v[16:31], v[136:139], v[96:99], v[16:31]
	v_exp_f32_e32 v88, v88
	v_exp_f32_e32 v89, v89
	v_exp_f32_e32 v90, v90
	v_exp_f32_e32 v91, v91
	ds_read_b128 v[116:119], v235 offset:16384
	ds_read_b128 v[120:123], v235 offset:20480
	s_waitcnt lgkmcnt(12)
	v_mfma_f32_32x32x16_bf16 v[32:47], v[136:139], v[104:107], v[32:47]
	v_exp_f32_e32 v92, v92
	v_exp_f32_e32 v93, v93
	v_exp_f32_e32 v94, v94
	v_exp_f32_e32 v95, v95
	ds_read_b128 v[124:127], v236 offset:16384
	ds_read_b128 v[160:163], v236 offset:20480
	s_waitcnt lgkmcnt(12)
	v_mfma_f32_32x32x16_bf16 v[16:31], v[132:135], v[108:111], v[16:31]
	v_exp_f32_e32 v64, v64
	v_exp_f32_e32 v65, v65
	v_exp_f32_e32 v66, v66
	v_exp_f32_e32 v67, v67
	ds_read_b128 v[164:167], v237 offset:16384
	ds_read_b128 v[184:187], v237 offset:20480
	s_waitcnt lgkmcnt(12)
	v_mfma_f32_32x32x16_bf16 v[32:47], v[132:135], v[48:51], v[32:47]
	v_exp_f32_e32 v68, v68
	v_exp_f32_e32 v69, v69
	v_exp_f32_e32 v70, v70
	v_exp_f32_e32 v71, v71
	s_waitcnt lgkmcnt(10)
	v_mfma_f32_32x32x16_bf16 v[16:31], v[128:131], v[52:55], v[16:31]
	v_exp_f32_e32 v72, v72
	v_exp_f32_e32 v73, v73
	v_exp_f32_e32 v74, v74
	v_exp_f32_e32 v75, v75
	s_waitcnt lgkmcnt(8)
	v_mfma_f32_32x32x16_bf16 v[32:47], v[128:131], v[56:59], v[32:47]
	v_exp_f32_e32 v76, v76
	v_exp_f32_e32 v77, v77
	v_exp_f32_e32 v78, v78
	v_exp_f32_e32 v79, v79
	s_waitcnt vmcnt(1) lgkmcnt(0)
	s_barrier
	ds_read_b64_tr_b16 v[188:189], v168 offset:32768
	ds_read_b64_tr_b16 v[190:191], v168 offset:33280
	v_add_f32_e32 v48, v80, v81
	v_add_f32_e32 v48, v82, v48
	v_add_f32_e32 v48, v83, v48
	v_add_f32_e32 v48, v84, v48
	v_add_f32_e32 v48, v85, v48
	v_cvt_pk_bf16_f32 v140, v80, v81
	v_cvt_pk_bf16_f32 v141, v82, v83
	s_waitcnt lgkmcnt(9)
	v_mfma_f32_32x32x16_bf16 v[96:111], v[60:63], v[156:159], 0
	ds_read_b64_tr_b16 v[80:81], v168 offset:36864
	ds_read_b64_tr_b16 v[82:83], v168 offset:37376
	v_add_f32_e32 v48, v86, v48
	v_add_f32_e32 v48, v87, v48
	v_add_f32_e32 v48, v88, v48
	v_add_f32_e32 v128, v89, v48
	s_waitcnt lgkmcnt(10)
	v_mfma_f32_32x32x16_bf16 v[48:63], v[112:115], v[156:159], 0
	v_cvt_pk_bf16_f32 v142, v84, v85
	v_cvt_pk_bf16_f32 v143, v86, v87
	ds_read_b64_tr_b16 v[84:85], v168 offset:33792
	ds_read_b64_tr_b16 v[86:87], v168 offset:34304
	v_add_f32_e32 v112, v90, v128
	v_add_f32_e32 v112, v91, v112
	v_add_f32_e32 v112, v92, v112
	v_add_f32_e32 v112, v93, v112
	v_cvt_pk_bf16_f32 v136, v88, v89
	v_cvt_pk_bf16_f32 v137, v90, v91
	s_waitcnt lgkmcnt(11)
	v_mfma_f32_32x32x16_bf16 v[96:111], v[116:119], v[152:155], v[96:111]
	ds_read_b64_tr_b16 v[88:89], v168 offset:37888
	ds_read_b64_tr_b16 v[90:91], v168 offset:38400
	s_waitcnt lgkmcnt(12)
	v_mfma_f32_32x32x16_bf16 v[48:63], v[120:123], v[152:155], v[48:63]
	v_add_f32_e32 v112, v94, v112
	v_add_f32_e32 v112, v95, v112
	v_add_f32_e32 v112, v64, v112
	v_add_f32_e32 v112, v65, v112
	v_cvt_pk_bf16_f32 v138, v92, v93
	v_cvt_pk_bf16_f32 v139, v94, v95
	ds_read_b64_tr_b16 v[92:93], v168 offset:34816
	ds_read_b64_tr_b16 v[94:95], v168 offset:35328
	v_add_f32_e32 v112, v66, v112
	v_add_f32_e32 v112, v67, v112
	v_add_f32_e32 v112, v68, v112
	v_add_f32_e32 v112, v69, v112
	v_cvt_pk_bf16_f32 v132, v64, v65
	v_cvt_pk_bf16_f32 v133, v66, v67
	s_waitcnt lgkmcnt(13)
	v_mfma_f32_32x32x16_bf16 v[96:111], v[124:127], v[148:151], v[96:111]
	ds_read_b64_tr_b16 v[64:65], v168 offset:38912
	ds_read_b64_tr_b16 v[66:67], v168 offset:39424
	s_waitcnt lgkmcnt(14)
	v_mfma_f32_32x32x16_bf16 v[48:63], v[160:163], v[148:151], v[48:63]
	v_add_f32_e32 v112, v70, v112
	v_add_f32_e32 v112, v71, v112
	v_add_f32_e32 v112, v72, v112
	v_add_f32_e32 v112, v73, v112
	v_cvt_pk_bf16_f32 v134, v68, v69
	v_cvt_pk_bf16_f32 v135, v70, v71
	ds_read_b64_tr_b16 v[68:69], v168 offset:35840
	ds_read_b64_tr_b16 v[70:71], v168 offset:36352
	v_add_f32_e32 v112, v74, v112
	v_add_f32_e32 v112, v75, v112
	v_add_f32_e32 v112, v76, v112
	v_add_f32_e32 v112, v77, v112
	v_cvt_pk_bf16_f32 v128, v72, v73
	v_cvt_pk_bf16_f32 v129, v74, v75
	s_waitcnt lgkmcnt(14)
	v_mfma_f32_32x32x16_bf16 v[96:111], v[164:167], v[144:147], v[96:111]
	ds_read_b64_tr_b16 v[72:73], v168 offset:39936
	ds_read_b64_tr_b16 v[74:75], v168 offset:40448
	v_mfma_f32_32x32x16_bf16 v[48:63], v[184:187], v[144:147], v[48:63]
	v_add_f32_e32 v112, v78, v112
	v_add_f32_e32 v112, v79, v112
	v_add_f32_e32 v112, 0, v112
	v_cvt_pk_bf16_f32 v130, v76, v77
	v_cvt_pk_bf16_f32 v131, v78, v79
	v_lshl_add_u64 v[76:77], v[170:171], 0, s[44:45]
	s_mov_b32 s17, m0
	s_mov_b32 m0, s16
	s_nop 0
	global_load_lds_dwordx4 v[76:77], off
	s_mov_b32 m0, s17
	v_add_f32_e32 v120, v172, v112
	s_waitcnt lgkmcnt(14)
	v_mfma_f32_32x32x16_bf16 v[16:31], v[140:143], v[188:191], v[16:31]
	v_exp_f32_e32 v96, v96
	v_exp_f32_e32 v97, v97
	v_exp_f32_e32 v98, v98
	v_exp_f32_e32 v99, v99
	s_waitcnt lgkmcnt(12)
	v_mfma_f32_32x32x16_bf16 v[32:47], v[140:143], v[80:83], v[32:47]
	v_exp_f32_e32 v100, v100
	v_exp_f32_e32 v101, v101
	v_exp_f32_e32 v102, v102
	v_exp_f32_e32 v103, v103
	ds_read_b128 v[76:79], v234
	ds_read_b128 v[80:83], v234 offset:4096
	s_waitcnt lgkmcnt(12)
	v_mfma_f32_32x32x16_bf16 v[16:31], v[136:139], v[84:87], v[16:31]
	v_exp_f32_e32 v104, v104
	v_exp_f32_e32 v105, v105
	v_exp_f32_e32 v106, v106
	v_exp_f32_e32 v107, v107
	ds_read_b128 v[122:125], v235
	ds_read_b128 v[160:163], v235 offset:4096
	s_waitcnt lgkmcnt(12)
	v_mfma_f32_32x32x16_bf16 v[32:47], v[136:139], v[88:91], v[32:47]
	v_exp_f32_e32 v108, v108
	v_exp_f32_e32 v109, v109
	v_exp_f32_e32 v110, v110
	v_exp_f32_e32 v111, v111
	ds_read_b128 v[164:167], v236
	ds_read_b128 v[170:173], v236 offset:4096
	s_waitcnt lgkmcnt(12)
	v_mfma_f32_32x32x16_bf16 v[16:31], v[132:135], v[92:95], v[16:31]
	v_exp_f32_e32 v48, v48
	v_exp_f32_e32 v49, v49
	v_exp_f32_e32 v50, v50
	v_exp_f32_e32 v51, v51
	ds_read_b128 v[184:187], v237
	ds_read_b128 v[188:191], v237 offset:4096
	s_waitcnt lgkmcnt(12)
	v_mfma_f32_32x32x16_bf16 v[32:47], v[132:135], v[64:67], v[32:47]
	v_exp_f32_e32 v52, v52
	v_exp_f32_e32 v53, v53
	v_exp_f32_e32 v54, v54
	v_exp_f32_e32 v55, v55
	s_waitcnt lgkmcnt(10)
	v_mfma_f32_32x32x16_bf16 v[16:31], v[128:131], v[68:71], v[16:31]
	v_exp_f32_e32 v56, v56
	v_exp_f32_e32 v57, v57
	v_exp_f32_e32 v58, v58
	v_exp_f32_e32 v59, v59
	s_waitcnt lgkmcnt(8)
	v_mfma_f32_32x32x16_bf16 v[32:47], v[128:131], v[72:75], v[32:47]
	v_exp_f32_e32 v60, v60
	v_exp_f32_e32 v61, v61
	v_exp_f32_e32 v62, v62
	v_exp_f32_e32 v63, v63
	s_waitcnt vmcnt(0) lgkmcnt(0)
	s_barrier
	ds_read_b64_tr_b16 v[112:113], v168 offset:40960
	ds_read_b64_tr_b16 v[114:115], v168 offset:41472
	v_add_f32_e32 v64, v96, v97
	v_add_f32_e32 v64, v98, v64
	v_add_f32_e32 v64, v99, v64
	v_add_f32_e32 v64, v100, v64
	v_add_f32_e32 v84, v101, v64
	v_cvt_pk_bf16_f32 v140, v96, v97
	v_cvt_pk_bf16_f32 v141, v98, v99
	s_waitcnt lgkmcnt(9)
	v_mfma_f32_32x32x16_bf16 v[64:79], v[76:79], v[156:159], 0
	ds_read_b64_tr_b16 v[96:97], v168 offset:45056
	ds_read_b64_tr_b16 v[98:99], v168 offset:45568
	v_add_f32_e32 v84, v102, v84
	v_add_f32_e32 v84, v103, v84
	v_add_f32_e32 v84, v104, v84
	v_add_f32_e32 v121, v105, v84
	v_cvt_pk_bf16_f32 v142, v100, v101
	v_cvt_pk_bf16_f32 v143, v102, v103
	s_waitcnt lgkmcnt(10)
	v_mfma_f32_32x32x16_bf16 v[80:95], v[80:83], v[156:159], 0
	ds_read_b64_tr_b16 v[116:117], v168 offset:41984
	ds_read_b64_tr_b16 v[118:119], v168 offset:42496
	v_add_f32_e32 v100, v106, v121
	v_add_f32_e32 v100, v107, v100
	v_add_f32_e32 v100, v108, v100
	v_add_f32_e32 v121, v109, v100
	v_cvt_pk_bf16_f32 v136, v104, v105
	v_cvt_pk_bf16_f32 v137, v106, v107
	s_waitcnt lgkmcnt(11)
	v_mfma_f32_32x32x16_bf16 v[64:79], v[122:125], v[152:155], v[64:79]
	ds_read_b64_tr_b16 v[100:101], v168 offset:46080
	ds_read_b64_tr_b16 v[102:103], v168 offset:46592
	v_add_f32_e32 v104, v110, v121
	v_add_f32_e32 v104, v111, v104
	v_add_f32_e32 v104, v48, v104
	v_add_f32_e32 v121, v49, v104
	v_cvt_pk_bf16_f32 v138, v108, v109
	v_cvt_pk_bf16_f32 v139, v110, v111
	s_waitcnt lgkmcnt(12)
	v_mfma_f32_32x32x16_bf16 v[80:95], v[160:163], v[152:155], v[80:95]
	ds_read_b64_tr_b16 v[104:105], v168 offset:43008
	ds_read_b64_tr_b16 v[106:107], v168 offset:43520
	v_add_f32_e32 v108, v50, v121
	v_add_f32_e32 v108, v51, v108
	v_add_f32_e32 v108, v52, v108
	v_add_f32_e32 v108, v53, v108
	v_cvt_pk_bf16_f32 v132, v48, v49
	v_cvt_pk_bf16_f32 v133, v50, v51
	s_waitcnt lgkmcnt(13)
	v_mfma_f32_32x32x16_bf16 v[64:79], v[164:167], v[148:151], v[64:79]
	ds_read_b64_tr_b16 v[48:49], v168 offset:47104
	ds_read_b64_tr_b16 v[50:51], v168 offset:47616
	v_add_f32_e32 v108, v54, v108
	v_add_f32_e32 v108, v55, v108
	v_add_f32_e32 v108, v56, v108
	v_add_f32_e32 v121, v57, v108
	v_cvt_pk_bf16_f32 v134, v52, v53
	v_cvt_pk_bf16_f32 v135, v54, v55
	s_waitcnt lgkmcnt(14)
	v_mfma_f32_32x32x16_bf16 v[80:95], v[170:173], v[148:151], v[80:95]
	ds_read_b64_tr_b16 v[108:109], v168 offset:44032
	ds_read_b64_tr_b16 v[110:111], v168 offset:44544
	v_add_f32_e32 v52, v58, v121
	v_add_f32_e32 v52, v59, v52
	v_add_f32_e32 v52, v60, v52
	v_add_f32_e32 v121, v61, v52
	v_cvt_pk_bf16_f32 v128, v56, v57
	v_cvt_pk_bf16_f32 v129, v58, v59
	s_waitcnt lgkmcnt(14)
	v_mfma_f32_32x32x16_bf16 v[64:79], v[184:187], v[144:147], v[64:79]
	ds_read_b64_tr_b16 v[52:53], v168 offset:48128
	ds_read_b64_tr_b16 v[54:55], v168 offset:48640
	v_add_f32_e32 v56, v62, v121
	v_add_f32_e32 v56, v63, v56
	v_add_f32_e32 v56, 0, v56
	v_cvt_pk_bf16_f32 v130, v60, v61
	v_cvt_pk_bf16_f32 v131, v62, v63
	v_mfma_f32_32x32x16_bf16 v[80:95], v[188:191], v[144:147], v[80:95]
	s_nop 3
	v_exp_f32_e32 v64, v64
	v_exp_f32_e32 v65, v65
	v_exp_f32_e32 v66, v66
	v_exp_f32_e32 v67, v67
	s_nop 0
	v_exp_f32_e32 v68, v68
	v_exp_f32_e32 v69, v69
	v_exp_f32_e32 v70, v70
	v_exp_f32_e32 v71, v71
	s_nop 0
	v_exp_f32_e32 v72, v72
	v_exp_f32_e32 v73, v73
	v_exp_f32_e32 v74, v74
	v_exp_f32_e32 v75, v75
	s_nop 0
	v_exp_f32_e32 v76, v76
	v_exp_f32_e32 v77, v77
	v_exp_f32_e32 v78, v78
	v_exp_f32_e32 v79, v79
	v_exp_f32_e32 v80, v80
	v_exp_f32_e32 v81, v81
	v_exp_f32_e32 v82, v82
	v_exp_f32_e32 v83, v83
	s_nop 0
	v_exp_f32_e32 v84, v84
	v_exp_f32_e32 v85, v85
	v_exp_f32_e32 v86, v86
	v_exp_f32_e32 v87, v87
	s_nop 0
	v_exp_f32_e32 v88, v88
	v_exp_f32_e32 v89, v89
	v_exp_f32_e32 v90, v90
	v_exp_f32_e32 v91, v91
	s_nop 0
	v_exp_f32_e32 v92, v92
	v_exp_f32_e32 v93, v93
	v_exp_f32_e32 v94, v94
	v_exp_f32_e32 v95, v95
	s_waitcnt lgkmcnt(14)
; #define SBAR() __builtin_amdgcn_sched_barrier(0)
;   #define PKW(P,B) cvtpk_s(P[B],P[B+1])
; template<int THRL,int VM,bool NOMAX> __device__ __forceinline__ void attn_unit(const bf16*Qb,const bf16*__restrict__ Kh,const bf16*__restrict__ Vh,bf16*Ob,const int NT,const int sp,float*wscr,char*shm){
;     ...
;   { float sacc=pB0[0]+pB0[1]; _Pragma("unroll") for(int r=2;r<16;++r)sacc+=pB0[r]; _Pragma("unroll") for(int r=0;r<16;++r)sacc+=pB1[r]; l_reg+=sacc;
;     pw0=(u32x4){PKW(pB0,0),PKW(pB0,2),PKW(pB0,4),PKW(pB0,6)};pw1=(u32x4){PKW(pB0,8),PKW(pB0,10),PKW(pB0,12),PKW(pB0,14)};pw2=(u32x4){PKW(pB1,0),PKW(pB1,2),PKW(pB1,4),PKW(pB1,6)};pw3=(u32x4){PKW(pB1,8),PKW(pB1,10),PKW(pB1,12),PKW(pB1,14)};
;     SBAR(); pv(o,vb0+VM*sl_cur,PAF(0),PAF(1),PAF(2),PAF(3)); if constexpr(VM==2) pv(o+2,vb0+VM*sl_cur+8192,PAF(0),PAF(1),PAF(2),PAF(3)); }
;     ...
;   {auto rr=__builtin_amdgcn_permlane32_swap(__float_as_uint(l_reg),__float_as_uint(l_reg),false,false);l_reg=__uint_as_float(rr[0])+__uint_as_float(rr[1]);}
;   if(hi==0)wsf[32+r32]=l_reg;asm volatile("s_waitcnt lgkmcnt(0)":::"memory");
	v_mfma_f32_32x32x16_bf16 v[16:31], v[140:143], v[112:115], v[16:31]
	v_add_f32_e32 v57, v64, v65
	v_add_f32_e32 v57, v66, v57
	v_add_f32_e32 v57, v67, v57
	v_add_f32_e32 v57, v68, v57
	v_add_f32_e32 v57, v69, v57
	v_add_f32_e32 v57, v70, v57
	v_add_f32_e32 v57, v71, v57
	s_waitcnt lgkmcnt(12)
	v_mfma_f32_32x32x16_bf16 v[32:47], v[140:143], v[96:99], v[32:47]
	v_add_f32_e32 v57, v72, v57
	v_add_f32_e32 v57, v73, v57
	v_add_f32_e32 v57, v74, v57
	v_add_f32_e32 v57, v75, v57
	v_add_f32_e32 v57, v76, v57
	v_add_f32_e32 v57, v77, v57
	v_add_f32_e32 v57, v78, v57
	s_waitcnt lgkmcnt(10)
	v_mfma_f32_32x32x16_bf16 v[16:31], v[136:139], v[116:119], v[16:31]
	v_add_f32_e32 v57, v79, v57
	v_add_f32_e32 v57, v80, v57
	v_add_f32_e32 v57, v81, v57
	v_add_f32_e32 v57, v82, v57
	v_add_f32_e32 v57, v83, v57
	v_add_f32_e32 v57, v84, v57
	v_add_f32_e32 v57, v85, v57
	s_waitcnt lgkmcnt(8)
	v_mfma_f32_32x32x16_bf16 v[32:47], v[136:139], v[100:103], v[32:47]
	v_add_f32_e32 v57, v86, v57
	v_add_f32_e32 v57, v87, v57
	v_add_f32_e32 v57, v88, v57
	v_add_f32_e32 v57, v89, v57
	v_add_f32_e32 v57, v90, v57
	v_add_f32_e32 v57, v91, v57
	v_add_f32_e32 v57, v92, v57
	s_waitcnt lgkmcnt(6)
	v_mfma_f32_32x32x16_bf16 v[16:31], v[132:135], v[104:107], v[16:31]
	v_add_f32_e32 v57, v93, v57
	v_add_f32_e32 v57, v94, v57
	v_add_f32_e32 v57, v95, v57
	v_add_f32_e32 v56, v120, v56
	v_add_f32_e32 v56, v56, v57
	v_cvt_pk_bf16_f32 v58, v64, v65
	v_cvt_pk_bf16_f32 v59, v66, v67
	s_waitcnt lgkmcnt(4)
	v_mfma_f32_32x32x16_bf16 v[32:47], v[132:135], v[48:51], v[32:47]
	v_cvt_pk_bf16_f32 v48, v80, v81
	v_cvt_pk_bf16_f32 v60, v68, v69
	v_cvt_pk_bf16_f32 v61, v70, v71
	v_cvt_pk_bf16_f32 v62, v72, v73
	v_cvt_pk_bf16_f32 v63, v74, v75
	v_cvt_pk_bf16_f32 v64, v76, v77
	v_cvt_pk_bf16_f32 v65, v78, v79
	s_waitcnt lgkmcnt(2)
	v_mfma_f32_32x32x16_bf16 v[16:31], v[128:131], v[108:111], v[16:31]
	v_cvt_pk_bf16_f32 v49, v82, v83
	v_cvt_pk_bf16_f32 v50, v84, v85
	v_cvt_pk_bf16_f32 v51, v86, v87
	v_cvt_pk_bf16_f32 v66, v88, v89
	v_cvt_pk_bf16_f32 v67, v90, v91
	v_cvt_pk_bf16_f32 v68, v92, v93
	v_cvt_pk_bf16_f32 v69, v94, v95
	s_waitcnt lgkmcnt(0)
	v_mfma_f32_32x32x16_bf16 v[32:47], v[128:131], v[52:55], v[32:47]
	ds_read_b64_tr_b16 v[52:53],v174 offset:0
	ds_read_b64_tr_b16 v[54:55],v174 offset:512
	ds_read_b64_tr_b16 v[70:71],v174 offset:1024
	ds_read_b64_tr_b16 v[72:73],v174 offset:1536
	ds_read_b64_tr_b16 v[74:75],v174 offset:2048
	ds_read_b64_tr_b16 v[76:77],v174 offset:2560
	ds_read_b64_tr_b16 v[78:79],v174 offset:3072
	ds_read_b64_tr_b16 v[80:81],v174 offset:3584
	s_waitcnt lgkmcnt(0)
	s_nop 0
	v_mfma_f32_32x32x16_bf16 v[16:31], v[58:61], v[52:55], v[16:31]
	ds_read_b64_tr_b16 v[52:53],v174 offset:4096
	ds_read_b64_tr_b16 v[54:55],v174 offset:4608
	v_mfma_f32_32x32x16_bf16 v[16:31], v[62:65], v[70:73], v[16:31]
	ds_read_b64_tr_b16 v[70:71],v174 offset:5120
	ds_read_b64_tr_b16 v[72:73],v174 offset:5632
	v_mfma_f32_32x32x16_bf16 v[16:31], v[48:51], v[74:77], v[16:31]
	ds_read_b64_tr_b16 v[74:75],v174 offset:6144
	ds_read_b64_tr_b16 v[76:77],v174 offset:6656
	ds_read_b64_tr_b16 v[82:83],v174 offset:7168
	ds_read_b64_tr_b16 v[84:85],v174 offset:7680
	s_waitcnt lgkmcnt(0)
	v_mfma_f32_32x32x16_bf16 v[16:31], v[66:69], v[78:81], v[16:31]
	v_mfma_f32_32x32x16_bf16 v[32:47], v[58:61], v[52:55], v[32:47]
	v_cmp_gt_u32_e32 vcc, 32, v178
	v_mfma_f32_32x32x16_bf16 v[32:47], v[62:65], v[70:73], v[32:47]
	v_mfma_f32_32x32x16_bf16 v[32:47], v[48:51], v[74:77], v[32:47]
	v_mov_b32_e32 v48, v56
	s_nop 1
	v_permlane32_swap_b32_e32 v56, v48
	v_mfma_f32_32x32x16_bf16 v[32:47], v[66:69], v[82:85], v[32:47]
	s_and_saveexec_b64 s[16:17], vcc
	s_cbranch_execz .LBB0_887
	v_add_f32_e32 v48, v56, v48
	v_lshl_add_u32 v49, v180, 2, s19
	ds_write_b32 v49, v48 offset:49280
	s_branch .LBB0_887
